# v32 with the per-step priority raise moved up to the start of the step (covers LDS read issue + softmax VALU)
# baseline (speedup 1.0000x reference)
; #define SBAR() __builtin_amdgcn_sched_barrier(0)
; #define ATT_DMA_K(t) do { const bf16_t* kg_ = Kh + (size_t)(t) * 64 * LDK; LAS unsigned char* sb_ = lds + ((t) & 3) * KBUF; \
;     _Pragma("unroll") for (int i_ = 0; i_ < NKP; ++i_) __builtin_amdgcn_global_load_lds((const unsigned*)(kg_ + kgo[i_]), (LAS unsigned*)(sb_ + (wid + 8 * i_) * 1024), 16, 0, 0); } while (0)
; #define ATT_DMA_V(t, vs) do { const bf16_t* vg_ = Vh + (size_t)(t) * 64 * LDV; LAS unsigned char* sb_ = lds + V_OFF + (vs) * SHM_V; \
;     _Pragma("unroll") for (int i_ = 0; i_ < 2; ++i_) __builtin_amdgcn_global_load_lds((const unsigned*)(vg_ + vgo[i_]), (LAS unsigned*)(sb_ + (2 * wid + i_) * 1024), 16, 0, 0); } while (0)
; #define ATT_SEG(t) do { if constexpr (MODE != 0) { if (((t) == tL && tL > 0) || (t) == tR) { const float f_ = (t) == tR ? fR : fL; l_reg *= f_; \
;     _Pragma("unroll") for (int d = 0; d < 4; ++d) _Pragma("unroll") for (int r = 0; r < 16; ++r) o[d][r] *= f_; } } } while (0)
; #define ATT_TOP(N) do { asm volatile("s_waitcnt vmcnt(%0)" :: "n"(N) : "memory"); __builtin_amdgcn_s_barrier(); asm volatile("" ::: "memory"); } while (0)
; template <int DQK, int MODE, int LDQ, int LDK, int LDV> ...
;     ...
;         if (j + 2 < NT) ATT_TOP(NKP + 2); else ATT_TOP(0);
;         if (j + 3 < NT) ATT_DMA_K(j + 3);
;         if (j + 2 < NT) ATT_DMA_V(j + 2, v2);
;         ATT_SEG(j); SBAR();
;         ATT_STEP(pA, pB, 0, v0, true, 1, j);
.Lstg_d0_top_10:
	s_setprio 1
	s_add_i32 s1, s95, s1
	global_load_lds_dwordx4 v[100:101], off
	s_add_i32 s2, s1, 0x400
	s_mov_b32 m0, s1
	s_add_i32 s1, s62, s0
	global_load_lds_dwordx4 v[102:103], off
	s_mov_b32 m0, s2
	s_add_i32 s74, s6, s0
	global_load_lds_dwordx4 v[104:105], off
	s_cmp_eq_u32 s1, 1
	s_cselect_b64 s[2:3], -1, 0
	s_and_b64 vcc, s[4:5], s[2:3]
	s_cmp_eq_u32 s74, 1
	s_cselect_b64 s[2:3], -1, 0
	s_or_b64 vcc, s[2:3], vcc
	s_andn2_b64 vcc, exec, vcc
	s_mov_b32 s1, s23
	s_cbranch_vccnz .LBB0_1922
	v_cndmask_b32_e64 v122, v112, v113, s[2:3]
	v_pk_mul_f32 v[14:15], v[14:15], v[122:123] op_sel_hi:[1,0]
	v_pk_mul_f32 v[12:13], v[12:13], v[122:123] op_sel_hi:[1,0]
	v_pk_mul_f32 v[10:11], v[10:11], v[122:123] op_sel_hi:[1,0]
	v_pk_mul_f32 v[8:9], v[8:9], v[122:123] op_sel_hi:[1,0]
	v_pk_mul_f32 v[6:7], v[6:7], v[122:123] op_sel_hi:[1,0]
	v_pk_mul_f32 v[4:5], v[4:5], v[122:123] op_sel_hi:[1,0]
	v_pk_mul_f32 v[2:3], v[2:3], v[122:123] op_sel_hi:[1,0]
	v_pk_mul_f32 v[0:1], v[0:1], v[122:123] op_sel_hi:[1,0]
	v_pk_mul_f32 v[62:63], v[62:63], v[122:123] op_sel_hi:[1,0]
	v_pk_mul_f32 v[60:61], v[60:61], v[122:123] op_sel_hi:[1,0]
	v_pk_mul_f32 v[58:59], v[58:59], v[122:123] op_sel_hi:[1,0]
	v_pk_mul_f32 v[56:57], v[56:57], v[122:123] op_sel_hi:[1,0]
	v_pk_mul_f32 v[54:55], v[54:55], v[122:123] op_sel_hi:[1,0]
	v_pk_mul_f32 v[52:53], v[52:53], v[122:123] op_sel_hi:[1,0]
	v_pk_mul_f32 v[50:51], v[50:51], v[122:123] op_sel_hi:[1,0]
	v_pk_mul_f32 v[48:49], v[48:49], v[122:123] op_sel_hi:[1,0]
	v_pk_mul_f32 v[46:47], v[46:47], v[122:123] op_sel_hi:[1,0]
	v_pk_mul_f32 v[44:45], v[44:45], v[122:123] op_sel_hi:[1,0]
	v_pk_mul_f32 v[42:43], v[42:43], v[122:123] op_sel_hi:[1,0]
	v_pk_mul_f32 v[40:41], v[40:41], v[122:123] op_sel_hi:[1,0]
	v_pk_mul_f32 v[38:39], v[38:39], v[122:123] op_sel_hi:[1,0]
	v_pk_mul_f32 v[36:37], v[36:37], v[122:123] op_sel_hi:[1,0]
	v_pk_mul_f32 v[34:35], v[34:35], v[122:123] op_sel_hi:[1,0]
	v_pk_mul_f32 v[32:33], v[32:33], v[122:123] op_sel_hi:[1,0]
	v_pk_mul_f32 v[30:31], v[30:31], v[122:123] op_sel_hi:[1,0]
	v_pk_mul_f32 v[28:29], v[28:29], v[122:123] op_sel_hi:[1,0]
	v_pk_mul_f32 v[26:27], v[26:27], v[122:123] op_sel_hi:[1,0]
	v_pk_mul_f32 v[24:25], v[24:25], v[122:123] op_sel_hi:[1,0]
	v_pk_mul_f32 v[22:23], v[22:23], v[122:123] op_sel_hi:[1,0]
	v_pk_mul_f32 v[20:21], v[20:21], v[122:123] op_sel_hi:[1,0]
	v_pk_mul_f32 v[18:19], v[18:19], v[122:123] op_sel_hi:[1,0]
	v_pk_mul_f32 v[16:17], v[16:17], v[122:123] op_sel_hi:[1,0]
	v_mul_f32_e32 v120, v120, v122
.LBB0_1922:
	s_add_i32 s3, s0, -1
	s_add_i32 s2, s22, 0xffffa000
	s_and_b32 s2, s2, 0x6000
	v_add_u32_e32 v121, s2, v114
	v_add_u32_e32 v122, v121, v115
	v_add_u32_e32 v126, v121, v116
	ds_read_b128 v[122:125], v122 offset:4096
	ds_read_b128 v[132:135], v126 offset:4096
	v_add_u32_e32 v126, v121, v117
	v_add_u32_e32 v121, v121, v118
	s_lshl_b32 s2, s1, 14
	ds_read_b128 v[136:139], v126 offset:4096
	ds_read_b128 v[140:143], v121 offset:4096
	v_add_u32_e32 v121, s2, v106
	ds_read_b64_tr_b16 v[144:145], v121 offset:0
	ds_read_b64_tr_b16 v[146:147], v121 offset:0x800
	ds_read_b64_tr_b16 v[148:149], v121 offset:0x1000
	ds_read_b64_tr_b16 v[150:151], v121 offset:0x1800
	ds_read_b64_tr_b16 v[152:153], v121 offset:0x200
	ds_read_b64_tr_b16 v[154:155], v121 offset:0xa00
	ds_read_b64_tr_b16 v[156:157], v121 offset:0x1200
	ds_read_b64_tr_b16 v[158:159], v121 offset:0x1a00
	ds_read_b64_tr_b16 v[162:163], v121 offset:0x400
	ds_read_b64_tr_b16 v[164:165], v121 offset:0xc00
	ds_read_b64_tr_b16 v[166:167], v121 offset:0x1400
	ds_read_b64_tr_b16 v[168:169], v121 offset:0x1c00
	ds_read_b64_tr_b16 v[170:171], v121 offset:0x600
	ds_read_b64_tr_b16 v[172:173], v121 offset:0xe00
	ds_read_b64_tr_b16 v[174:175], v121 offset:0x1600
	ds_read_b64_tr_b16 v[176:177], v121 offset:0x1e00
	v_exp_f32_e32 v64, v64
	v_exp_f32_e32 v65, v65
	v_exp_f32_e32 v66, v66
	v_exp_f32_e32 v67, v67
	v_exp_f32_e32 v68, v68
	v_add_f32_e32 v126, 0, v64
	v_exp_f32_e32 v69, v69
	v_add_f32_e32 v126, v65, v126
	v_exp_f32_e32 v70, v70
	v_add_f32_e32 v126, v66, v126
	v_exp_f32_e32 v71, v71
	v_add_f32_e32 v126, v67, v126
	v_exp_f32_e32 v72, v72
	v_add_f32_e32 v126, v68, v126
	v_exp_f32_e32 v73, v73
	v_add_f32_e32 v126, v69, v126
	v_exp_f32_e32 v74, v74
	v_add_f32_e32 v126, v70, v126
	v_exp_f32_e32 v75, v75
	v_add_f32_e32 v126, v71, v126
	v_exp_f32_e32 v76, v76
	v_add_f32_e32 v126, v72, v126
	v_exp_f32_e32 v77, v77
	v_add_f32_e32 v126, v73, v126
	v_exp_f32_e32 v78, v78
	v_add_f32_e32 v126, v74, v126
	v_exp_f32_e32 v79, v79
	v_add_f32_e32 v126, v75, v126
	v_add_f32_e32 v126, v76, v126
	v_add_f32_e32 v126, v77, v126
	v_add_f32_e32 v126, v78, v126
	v_add_f32_e32 v126, v79, v126
	v_add_f32_e32 v120, v126, v120
	v_cvt_pk_bf16_f32 v64, v64, v65
	v_cvt_pk_bf16_f32 v65, v66, v67
	v_cvt_pk_bf16_f32 v66, v68, v69
	v_cvt_pk_bf16_f32 v67, v70, v71
	v_cvt_pk_bf16_f32 v68, v72, v73
	v_cvt_pk_bf16_f32 v69, v74, v75
	v_cvt_pk_bf16_f32 v70, v76, v77
	v_cvt_pk_bf16_f32 v71, v78, v79
	s_nop 0
	v_permlane32_swap_b32_e32 v64, v66
	v_permlane32_swap_b32_e32 v65, v67
	v_permlane32_swap_b32_e32 v68, v70
	v_permlane32_swap_b32_e32 v69, v71
	s_waitcnt lgkmcnt(0)
	s_setprio 0
	v_mfma_f32_32x32x16_bf16 v[0:15], v[64:67], v[144:147], v[0:15]
	s_cmp_lt_i32 s3, s55
	s_cselect_b64 vcc, -1, 0
	s_cmp_ge_i32 s3, s97
	s_cselect_b64 s[74:75], -1, 0
	s_or_b64 s[74:75], vcc, s[74:75]
	s_and_b64 vcc, exec, s[74:75]
	v_mfma_f32_32x32x16_bf16 v[48:63], v[64:67], v[152:155], v[48:63]
	v_mfma_f32_32x32x16_bf16 v[32:47], v[64:67], v[162:165], v[32:47]
	v_mfma_f32_32x32x16_bf16 v[16:31], v[64:67], v[170:173], v[16:31]
	v_mfma_f32_32x32x16_bf16 v[0:15], v[68:71], v[148:151], v[0:15]
	v_mfma_f32_32x32x16_bf16 v[48:63], v[68:71], v[156:159], v[48:63]
	v_mfma_f32_32x32x16_bf16 v[32:47], v[68:71], v[166:169], v[32:47]
	v_mfma_f32_32x32x16_bf16 v[16:31], v[68:71], v[174:177], v[16:31]
	v_mfma_f32_32x32x16_bf16 v[64:79], v[122:125], v[92:95], 0
	v_mfma_f32_32x32x16_bf16 v[64:79], v[132:135], v[88:91], v[64:79]
	v_mfma_f32_32x32x16_bf16 v[64:79], v[136:139], v[84:87], v[64:79]
	v_mfma_f32_32x32x16_bf16 v[64:79], v[140:143], v[80:83], v[64:79]
	s_setprio 1
	v_add_u32_e32 v122, s7, v119
	s_cbranch_vccnz .LBB0_1924
	v_add_u32_e32 v138, 0x28908, v122
	v_add_u32_e32 v140, 0x28920, v122
	v_add_u32_e32 v142, 0x28928, v122
	v_add_u32_e32 v124, 0x28940, v122
	v_add_u32_e32 v126, 0x28948, v122
	v_add_u32_e32 v132, 0x28960, v122
	v_add_u32_e32 v134, 0x28968, v122
	v_add_u32_e32 v123, 0x28900, v122
	ds_read2_b32 v[124:125], v124 offset1:1
	ds_read2_b32 v[126:127], v126 offset1:1
	ds_read2_b32 v[132:133], v132 offset1:1
	ds_read2_b32 v[134:135], v134 offset1:1
	ds_read2_b32 v[136:137], v123 offset1:1
	ds_read2_b32 v[138:139], v138 offset1:1
	ds_read2_b32 v[140:141], v140 offset1:1
	ds_read2_b32 v[142:143], v142 offset1:1
	s_waitcnt lgkmcnt(0)
	v_pk_add_f32 v[78:79], v[78:79], v[134:135]
	v_pk_add_f32 v[76:77], v[76:77], v[132:133]
	v_pk_add_f32 v[74:75], v[74:75], v[126:127]
	v_pk_add_f32 v[72:73], v[72:73], v[124:125]
	v_pk_add_f32 v[70:71], v[70:71], v[142:143]
	v_pk_add_f32 v[68:69], v[68:69], v[140:141]
	v_pk_add_f32 v[66:67], v[66:67], v[138:139]
	v_pk_add_f32 v[64:65], v[64:65], v[136:137]
.LBB0_1924:
	s_add_i32 s3, s22, 0xffffc000
	s_and_b32 s3, s3, 0x6000
	v_add_u32_e32 v123, s3, v114
	v_add_u32_e32 v140, v123, v118
	v_add_u32_e32 v136, v123, v117
	v_add_u32_e32 v132, v123, v116
	v_add_u32_e32 v123, v123, v115
	ds_read_b128 v[124:127], v123
	ds_read_b128 v[132:135], v132
	ds_read_b128 v[136:139], v136
	ds_read_b128 v[140:143], v140
	ds_read_b64_tr_b16 v[144:145], v121 offset:0x2000
	ds_read_b64_tr_b16 v[146:147], v121 offset:0x2800
	ds_read_b64_tr_b16 v[148:149], v121 offset:0x3000
	ds_read_b64_tr_b16 v[150:151], v121 offset:0x3800
	ds_read_b64_tr_b16 v[152:153], v121 offset:0x2200
	ds_read_b64_tr_b16 v[154:155], v121 offset:0x2a00
	ds_read_b64_tr_b16 v[156:157], v121 offset:0x3200
	ds_read_b64_tr_b16 v[158:159], v121 offset:0x3a00
	ds_read_b64_tr_b16 v[162:163], v121 offset:0x2400
	ds_read_b64_tr_b16 v[164:165], v121 offset:0x2c00
	ds_read_b64_tr_b16 v[166:167], v121 offset:0x3400
	ds_read_b64_tr_b16 v[168:169], v121 offset:0x3c00
	ds_read_b64_tr_b16 v[170:171], v121 offset:0x2600
	ds_read_b64_tr_b16 v[172:173], v121 offset:0x2e00
	ds_read_b64_tr_b16 v[174:175], v121 offset:0x3600
	ds_read_b64_tr_b16 v[176:177], v121 offset:0x3e00
	v_exp_f32_e32 v64, v64
	v_exp_f32_e32 v65, v65
	v_exp_f32_e32 v66, v66
	v_exp_f32_e32 v67, v67
	v_exp_f32_e32 v68, v68
	v_add_f32_e32 v121, 0, v64
	v_exp_f32_e32 v69, v69
	v_add_f32_e32 v121, v65, v121
	v_exp_f32_e32 v70, v70
	v_add_f32_e32 v121, v66, v121
	v_exp_f32_e32 v71, v71
	v_add_f32_e32 v121, v67, v121
	v_exp_f32_e32 v72, v72
	v_add_f32_e32 v121, v68, v121
	v_exp_f32_e32 v73, v73
	v_add_f32_e32 v121, v69, v121
	v_exp_f32_e32 v74, v74
	v_add_f32_e32 v121, v70, v121
	v_exp_f32_e32 v75, v75
	v_add_f32_e32 v121, v71, v121
	v_exp_f32_e32 v76, v76
	v_add_f32_e32 v121, v72, v121
	v_exp_f32_e32 v77, v77
	v_add_f32_e32 v121, v73, v121
	v_exp_f32_e32 v78, v78
	v_add_f32_e32 v121, v74, v121
	v_exp_f32_e32 v79, v79
	v_add_f32_e32 v121, v75, v121
	v_add_f32_e32 v121, v76, v121
	v_add_f32_e32 v121, v77, v121
	v_add_f32_e32 v121, v78, v121
	v_add_f32_e32 v121, v79, v121
	v_add_f32_e32 v120, v120, v121
	v_cvt_pk_bf16_f32 v64, v64, v65
	v_cvt_pk_bf16_f32 v65, v66, v67
	v_cvt_pk_bf16_f32 v66, v68, v69
	v_cvt_pk_bf16_f32 v67, v70, v71
	v_cvt_pk_bf16_f32 v68, v72, v73
	v_cvt_pk_bf16_f32 v69, v74, v75
	v_cvt_pk_bf16_f32 v70, v76, v77
	v_cvt_pk_bf16_f32 v71, v78, v79
	s_nop 0
	v_permlane32_swap_b32_e32 v64, v66
	v_permlane32_swap_b32_e32 v65, v67
	v_permlane32_swap_b32_e32 v68, v70
	v_permlane32_swap_b32_e32 v69, v71
	s_waitcnt lgkmcnt(0)
	s_setprio 0
	s_cmp_lt_u32 s33, 0x100
	s_cbranch_scc1 .Lstg_d0_mid_11
	s_waitcnt vmcnt(3)
	s_barrier

; DI int v_rd_base(int lane) { return ((lane & 3) << 3) | (((lane >> 2) & 3) << 6) | (((lane >> 4) & 1) << 5) | (((lane >> 5) & 1) << 8); }
; #define ATT_DMA_K(t) do { const bf16_t* kg_ = Kh + (size_t)(t) * 64 * LDK; LAS unsigned char* sb_ = lds + ((t) & 3) * KBUF; \
;     _Pragma("unroll") for (int i_ = 0; i_ < NKP; ++i_) __builtin_amdgcn_global_load_lds((const unsigned*)(kg_ + kgo[i_]), (LAS unsigned*)(sb_ + (wid + 8 * i_) * 1024), 16, 0, 0); } while (0)
; #define ATT_DMA_V(t, vs) do { const bf16_t* vg_ = Vh + (size_t)(t) * 64 * LDV; LAS unsigned char* sb_ = lds + V_OFF + (vs) * SHM_V; \
;     _Pragma("unroll") for (int i_ = 0; i_ < 2; ++i_) __builtin_amdgcn_global_load_lds((const unsigned*)(vg_ + vgo[i_]), (LAS unsigned*)(sb_ + (2 * wid + i_) * 1024), 16, 0, 0); } while (0)
; #define ATT_BIAS(P, t, half) do { if constexpr (MODE != 0) { if ((t) >= tL && (t) < tR) { const LAS float* bp_ = bt + ((t) * 64 + (half) * 32 - qpos + 224 + 4 * hi);     \
;     _Pragma("unroll") for (int r = 0; r < 16; ++r) P[r] += bp_[(r & 3) + 8 * (r >> 2)]; } } } while (0)
; #define ATT_TOP(N) do { asm volatile("s_waitcnt vmcnt(%0)" :: "n"(N) : "memory"); __builtin_amdgcn_s_barrier(); asm volatile("" ::: "memory"); } while (0)
; DI void expsum(f32x16& p, float& l_reg, bf16x8& pa0, bf16x8& pa1) {
; #pragma unroll
;     for (int r = 0; r < 16; ++r) p[r] = __builtin_amdgcn_exp2f(p[r]);
;     float ps = 0.f;
; #pragma unroll
;     for (int r = 0; r < 16; ++r) ps += p[r];
;     l_reg += ps; asm volatile("" : "+v"(l_reg));
;     ...
;     ATT_PK4(p, 0, pa0); ATT_PK4(p, 8, pa1);
;     ...
; }
; template <int DQK, int MODE, int LDQ, int LDK, int LDV> ...
;     ...
;     const int vbase = (int)(unsigned)(size_t)lds + V_OFF + v_rd_base(lane);
;     ...
;     constexpr int NDA = ND0 > 6 ? 6 : ND0;
;     ...
;     f32x16 pA, pB; bf16x8 pa0, pa1;
;     int v0 = 0, v1 = 1, v2 = 2;
;     ATT_TOP(NKP + 2);
;     { bf16x8 kf[NDA]; k_reads<DQK, 0, NDA>(kf, lds, 0, r32, hi); ATT_LGKM0(); qk_mma<0, NDA>(pA, kf, qr);
;       if constexpr (ND0 > NDA) { bf16x8 kg[ND0 - NDA]; k_reads<DQK, NDA, ND0>(kg, lds, 0, r32, hi); ATT_LGKM0(); qk_mma<NDA, ND0>(pA, kg, qr); }
;       ATT_BIAS(pA, 0, 0); }
;     if (wid >= 4) __builtin_amdgcn_s_setprio(1);
;     for (int j = 0; j < NT; ++j) {
;         if (j + 2 < NT) ATT_TOP(NKP + 2); else ATT_TOP(0);
;         if (j + 3 < NT) ATT_DMA_K(j + 3);
;         if (j + 2 < NT) ATT_DMA_V(j + 2, v2);
.Lstg_d0_t61_12:
	s_setprio 1
	v_lshl_add_u64 v[96:97], v[96:97], 1, s[56:57]
	s_mov_b32 m0, s0
	v_lshl_add_u64 v[98:99], v[98:99], 1, s[56:57]
	global_load_lds_dwordx4 v[96:97], off
	s_mov_b32 m0, s1
	s_cmp_lg_u32 s55, 61
	global_load_lds_dwordx4 v[98:99], off
	s_cselect_b64 s[0:1], -1, 0
	s_cmp_eq_u32 s58, 61
	s_cselect_b64 s[2:3], -1, 0
	s_cmp_lg_u32 s58, 61
	s_cselect_b64 s[4:5], -1, 0
	s_and_b64 s[0:1], s[4:5], s[0:1]
	s_and_b64 vcc, exec, s[0:1]
	s_cbranch_vccnz .LBB0_1930
	v_cndmask_b32_e64 v96, v112, v113, s[2:3]
	v_pk_mul_f32 v[14:15], v[14:15], v[96:97] op_sel_hi:[1,0]
	v_pk_mul_f32 v[12:13], v[12:13], v[96:97] op_sel_hi:[1,0]
	v_pk_mul_f32 v[10:11], v[10:11], v[96:97] op_sel_hi:[1,0]
	v_pk_mul_f32 v[8:9], v[8:9], v[96:97] op_sel_hi:[1,0]
	v_pk_mul_f32 v[6:7], v[6:7], v[96:97] op_sel_hi:[1,0]
	v_pk_mul_f32 v[4:5], v[4:5], v[96:97] op_sel_hi:[1,0]
	v_pk_mul_f32 v[2:3], v[2:3], v[96:97] op_sel_hi:[1,0]
	v_pk_mul_f32 v[0:1], v[0:1], v[96:97] op_sel_hi:[1,0]
	v_pk_mul_f32 v[62:63], v[62:63], v[96:97] op_sel_hi:[1,0]
	v_pk_mul_f32 v[60:61], v[60:61], v[96:97] op_sel_hi:[1,0]
	v_pk_mul_f32 v[58:59], v[58:59], v[96:97] op_sel_hi:[1,0]
	v_pk_mul_f32 v[56:57], v[56:57], v[96:97] op_sel_hi:[1,0]
	v_pk_mul_f32 v[54:55], v[54:55], v[96:97] op_sel_hi:[1,0]
	v_pk_mul_f32 v[52:53], v[52:53], v[96:97] op_sel_hi:[1,0]
	v_pk_mul_f32 v[50:51], v[50:51], v[96:97] op_sel_hi:[1,0]
	v_pk_mul_f32 v[48:49], v[48:49], v[96:97] op_sel_hi:[1,0]
	v_pk_mul_f32 v[46:47], v[46:47], v[96:97] op_sel_hi:[1,0]
	v_pk_mul_f32 v[44:45], v[44:45], v[96:97] op_sel_hi:[1,0]
	v_pk_mul_f32 v[42:43], v[42:43], v[96:97] op_sel_hi:[1,0]
	v_pk_mul_f32 v[40:41], v[40:41], v[96:97] op_sel_hi:[1,0]
	v_pk_mul_f32 v[38:39], v[38:39], v[96:97] op_sel_hi:[1,0]
	v_pk_mul_f32 v[36:37], v[36:37], v[96:97] op_sel_hi:[1,0]
	v_pk_mul_f32 v[34:35], v[34:35], v[96:97] op_sel_hi:[1,0]
	v_pk_mul_f32 v[32:33], v[32:33], v[96:97] op_sel_hi:[1,0]
	v_pk_mul_f32 v[30:31], v[30:31], v[96:97] op_sel_hi:[1,0]
	v_pk_mul_f32 v[28:29], v[28:29], v[96:97] op_sel_hi:[1,0]
	v_pk_mul_f32 v[26:27], v[26:27], v[96:97] op_sel_hi:[1,0]
	v_pk_mul_f32 v[24:25], v[24:25], v[96:97] op_sel_hi:[1,0]
	v_pk_mul_f32 v[22:23], v[22:23], v[96:97] op_sel_hi:[1,0]
	v_pk_mul_f32 v[20:21], v[20:21], v[96:97] op_sel_hi:[1,0]
	v_pk_mul_f32 v[18:19], v[18:19], v[96:97] op_sel_hi:[1,0]
	v_pk_mul_f32 v[16:17], v[16:17], v[96:97] op_sel_hi:[1,0]
	v_mul_f32_e32 v120, v120, v96
.LBB0_1930:
	s_mov_b64 s[96:97], 0xc00
	ds_read_b128 v[98:101], v107 offset:12288
	ds_read_b128 v[102:105], v108 offset:12288
	ds_read_b128 v[114:117], v109 offset:12288
	ds_read_b128 v[122:125], v110 offset:12288
	v_lshl_add_u32 v96, s64, 14, v106
	ds_read_b64_tr_b16 v[132:133], v96 offset:0
	ds_read_b64_tr_b16 v[134:135], v96 offset:0x800
	ds_read_b64_tr_b16 v[136:137], v96 offset:0x1000
	ds_read_b64_tr_b16 v[138:139], v96 offset:0x1800
	ds_read_b64_tr_b16 v[140:141], v96 offset:0x200
	ds_read_b64_tr_b16 v[142:143], v96 offset:0xa00
	ds_read_b64_tr_b16 v[144:145], v96 offset:0x1200
	ds_read_b64_tr_b16 v[146:147], v96 offset:0x1a00
	ds_read_b64_tr_b16 v[148:149], v96 offset:0x400
	ds_read_b64_tr_b16 v[150:151], v96 offset:0xc00
	ds_read_b64_tr_b16 v[152:153], v96 offset:0x1400
	ds_read_b64_tr_b16 v[154:155], v96 offset:0x1c00
	ds_read_b64_tr_b16 v[156:157], v96 offset:0x600
	ds_read_b64_tr_b16 v[158:159], v96 offset:0xe00
	ds_read_b64_tr_b16 v[162:163], v96 offset:0x1600
	ds_read_b64_tr_b16 v[164:165], v96 offset:0x1e00
	v_exp_f32_e32 v64, v64
	v_exp_f32_e32 v65, v65
	v_exp_f32_e32 v66, v66
	v_exp_f32_e32 v67, v67
	v_exp_f32_e32 v68, v68
	v_add_f32_e32 v97, 0, v64
	v_exp_f32_e32 v69, v69
	v_add_f32_e32 v97, v65, v97
	v_exp_f32_e32 v70, v70
	v_add_f32_e32 v97, v66, v97
	v_exp_f32_e32 v71, v71
	v_add_f32_e32 v97, v67, v97
	v_exp_f32_e32 v72, v72
	v_add_f32_e32 v97, v68, v97
	v_exp_f32_e32 v73, v73
	v_add_f32_e32 v97, v69, v97
	v_exp_f32_e32 v74, v74
	v_add_f32_e32 v97, v70, v97
	v_exp_f32_e32 v75, v75
	v_add_f32_e32 v97, v71, v97
	v_exp_f32_e32 v76, v76
	v_add_f32_e32 v97, v72, v97
	v_exp_f32_e32 v77, v77
	v_add_f32_e32 v97, v73, v97
	v_exp_f32_e32 v78, v78
	v_add_f32_e32 v97, v74, v97
	v_exp_f32_e32 v79, v79
	v_add_f32_e32 v97, v75, v97
	v_add_f32_e32 v97, v76, v97
	v_add_f32_e32 v97, v77, v97
	v_add_f32_e32 v97, v78, v97
	v_add_f32_e32 v97, v79, v97
	v_add_f32_e32 v97, v97, v120
	v_cvt_pk_bf16_f32 v64, v64, v65
	v_cvt_pk_bf16_f32 v65, v66, v67
	v_cvt_pk_bf16_f32 v66, v68, v69
	v_cvt_pk_bf16_f32 v67, v70, v71
	v_cvt_pk_bf16_f32 v68, v72, v73
	v_cvt_pk_bf16_f32 v69, v74, v75
	v_cvt_pk_bf16_f32 v70, v76, v77
	v_cvt_pk_bf16_f32 v71, v78, v79
	s_nop 0
	v_permlane32_swap_b32_e32 v64, v66
	v_permlane32_swap_b32_e32 v65, v67
	v_permlane32_swap_b32_e32 v68, v70
	v_permlane32_swap_b32_e32 v69, v71
	s_waitcnt lgkmcnt(0)
	s_setprio 0
	v_mfma_f32_32x32x16_bf16 v[0:15], v[64:67], v[132:135], v[0:15]
	s_cmp_gt_i32 s55, 61
	s_cselect_b64 s[0:1], -1, 0
	s_cmp_lt_i32 s58, 62
	s_cselect_b64 s[2:3], -1, 0
	s_or_b64 s[0:1], s[0:1], s[2:3]
	s_and_b64 vcc, exec, s[0:1]
	v_mfma_f32_32x32x16_bf16 v[48:63], v[64:67], v[140:143], v[48:63]
	v_mfma_f32_32x32x16_bf16 v[32:47], v[64:67], v[148:151], v[32:47]
	v_mfma_f32_32x32x16_bf16 v[16:31], v[64:67], v[156:159], v[16:31]
	v_mfma_f32_32x32x16_bf16 v[0:15], v[68:71], v[136:139], v[0:15]
	v_mfma_f32_32x32x16_bf16 v[48:63], v[68:71], v[144:147], v[48:63]
	v_mfma_f32_32x32x16_bf16 v[32:47], v[68:71], v[152:155], v[32:47]
	v_mfma_f32_32x32x16_bf16 v[16:31], v[68:71], v[162:165], v[16:31]
	s_waitcnt lgkmcnt(0)
	v_mfma_f32_32x32x16_bf16 v[64:79], v[98:101], v[92:95], 0
	v_mfma_f32_32x32x16_bf16 v[64:79], v[102:105], v[88:91], v[64:79]
	v_mfma_f32_32x32x16_bf16 v[64:79], v[114:117], v[84:87], v[64:79]
	v_mfma_f32_32x32x16_bf16 v[64:79], v[122:125], v[80:83], v[64:79]
	s_setprio 1
	s_cbranch_vccnz .LBB0_1932
	v_sub_u32_e32 v98, 0xf40, v111
	v_lshlrev_b32_e32 v98, 2, v98
	v_add3_u32 v98, s88, v98, v130
	v_add_u32_e32 v114, 0x400, v98
	v_add_u32_e32 v116, 0x408, v98
	v_add_u32_e32 v118, 0x420, v98
	v_add_u32_e32 v120, 0x428, v98
	v_add_u32_e32 v99, 0x440, v98
	v_add_u32_e32 v100, 0x448, v98
	v_add_u32_e32 v102, 0x460, v98
	v_add_u32_e32 v104, 0x468, v98
	ds_read2_b32 v[98:99], v99 offset1:1
	ds_read2_b32 v[100:101], v100 offset1:1
	ds_read2_b32 v[102:103], v102 offset1:1
	ds_read2_b32 v[104:105], v104 offset1:1
	ds_read2_b32 v[114:115], v114 offset1:1
	ds_read2_b32 v[116:117], v116 offset1:1
	ds_read2_b32 v[118:119], v118 offset1:1
	ds_read2_b32 v[120:121], v120 offset1:1
	s_waitcnt lgkmcnt(0)
	v_pk_add_f32 v[78:79], v[78:79], v[104:105]
	v_pk_add_f32 v[76:77], v[76:77], v[102:103]
	v_pk_add_f32 v[74:75], v[74:75], v[100:101]
	v_pk_add_f32 v[72:73], v[72:73], v[98:99]
	v_pk_add_f32 v[70:71], v[70:71], v[120:121]
	v_pk_add_f32 v[68:69], v[68:69], v[118:119]
	v_pk_add_f32 v[66:67], v[66:67], v[116:117]
	v_pk_add_f32 v[64:65], v[64:65], v[114:115]
; #define SBAR() __builtin_amdgcn_sched_barrier(0)
; #define ATT_DMA_K(t) do { const bf16_t* kg_ = Kh + (size_t)(t) * 64 * LDK; LAS unsigned char* sb_ = lds + ((t) & 3) * KBUF; \
;     _Pragma("unroll") for (int i_ = 0; i_ < NKP; ++i_) __builtin_amdgcn_global_load_lds((const unsigned*)(kg_ + kgo[i_]), (LAS unsigned*)(sb_ + (wid + 8 * i_) * 1024), 16, 0, 0); } while (0)
; #define ATT_DMA_V(t, vs) do { const bf16_t* vg_ = Vh + (size_t)(t) * 64 * LDV; LAS unsigned char* sb_ = lds + V_OFF + (vs) * SHM_V; \
;     _Pragma("unroll") for (int i_ = 0; i_ < 2; ++i_) __builtin_amdgcn_global_load_lds((const unsigned*)(vg_ + vgo[i_]), (LAS unsigned*)(sb_ + (2 * wid + i_) * 1024), 16, 0, 0); } while (0)
; #define ATT_SEG(t) do { if constexpr (MODE != 0) { if (((t) == tL && tL > 0) || (t) == tR) { const float f_ = (t) == tR ? fR : fL; l_reg *= f_; \
;     _Pragma("unroll") for (int d = 0; d < 4; ++d) _Pragma("unroll") for (int r = 0; r < 16; ++r) o[d][r] *= f_; } } } while (0)
; #define ATT_TOP(N) do { asm volatile("s_waitcnt vmcnt(%0)" :: "n"(N) : "memory"); __builtin_amdgcn_s_barrier(); asm volatile("" ::: "memory"); } while (0)
; DI void expsum(f32x16& p, float& l_reg, bf16x8& pa0, bf16x8& pa1) {
; #pragma unroll
;     for (int r = 0; r < 16; ++r) p[r] = __builtin_amdgcn_exp2f(p[r]);
;     float ps = 0.f;
; #pragma unroll
;     for (int r = 0; r < 16; ++r) ps += p[r];
;     l_reg += ps; asm volatile("" : "+v"(l_reg));
;     ...
;     ATT_PK4(p, 0, pa0); ATT_PK4(p, 8, pa1);
;     ...
; }
; template <int DQK, int MODE, int LDQ, int LDK, int LDV> ...
;     ...
;     f32x16 pA, pB; bf16x8 pa0, pa1;
;     int v0 = 0, v1 = 1, v2 = 2;
;     ATT_TOP(NKP + 2);
;     { bf16x8 kf[NDA]; k_reads<DQK, 0, NDA>(kf, lds, 0, r32, hi); ATT_LGKM0(); qk_mma<0, NDA>(pA, kf, qr);
;       if constexpr (ND0 > NDA) { bf16x8 kg[ND0 - NDA]; k_reads<DQK, NDA, ND0>(kg, lds, 0, r32, hi); ATT_LGKM0(); qk_mma<NDA, ND0>(pA, kg, qr); }
;       ATT_BIAS(pA, 0, 0); }
;     if (wid >= 4) __builtin_amdgcn_s_setprio(1);
;     for (int j = 0; j < NT; ++j) {
;         if (j + 2 < NT) ATT_TOP(NKP + 2); else ATT_TOP(0);
;         if (j + 3 < NT) ATT_DMA_K(j + 3);
;         if (j + 2 < NT) ATT_DMA_V(j + 2, v2);
;         ATT_SEG(j); SBAR();
;         ATT_STEP(pA, pB, 0, v0, true, 1, j);
;         ATT_STEP(pB, pA, 1, v0, (j + 1 < NT), 0, j + 1);
.LBB0_1932:
	s_movk_i32 s64, 0x70
	ds_read_b128 v[98:101], v107 offset:16384
	ds_read_b128 v[102:105], v108 offset:16384
	ds_read_b128 v[114:117], v109 offset:16384
	ds_read_b128 v[118:121], v110 offset:16384
	ds_read_b64_tr_b16 v[122:123], v96 offset:0x2000
	ds_read_b64_tr_b16 v[124:125], v96 offset:0x2800
	ds_read_b64_tr_b16 v[132:133], v96 offset:0x3000
	ds_read_b64_tr_b16 v[134:135], v96 offset:0x3800
	ds_read_b64_tr_b16 v[136:137], v96 offset:0x2200
	ds_read_b64_tr_b16 v[138:139], v96 offset:0x2a00
	ds_read_b64_tr_b16 v[140:141], v96 offset:0x3200
	ds_read_b64_tr_b16 v[142:143], v96 offset:0x3a00
	ds_read_b64_tr_b16 v[144:145], v96 offset:0x2400
	ds_read_b64_tr_b16 v[146:147], v96 offset:0x2c00
	ds_read_b64_tr_b16 v[148:149], v96 offset:0x3400
	ds_read_b64_tr_b16 v[150:151], v96 offset:0x3c00
	ds_read_b64_tr_b16 v[152:153], v96 offset:0x2600
	ds_read_b64_tr_b16 v[154:155], v96 offset:0x2e00
	ds_read_b64_tr_b16 v[156:157], v96 offset:0x3600
	ds_read_b64_tr_b16 v[158:159], v96 offset:0x3e00
	s_nop 5
	v_exp_f32_e32 v64, v64
	v_exp_f32_e32 v65, v65
	v_exp_f32_e32 v66, v66
	v_exp_f32_e32 v67, v67
	v_exp_f32_e32 v68, v68
	v_add_f32_e32 v96, 0, v64
	v_exp_f32_e32 v69, v69
	v_add_f32_e32 v96, v65, v96
	v_exp_f32_e32 v70, v70
	v_add_f32_e32 v96, v66, v96
	v_exp_f32_e32 v71, v71
	v_add_f32_e32 v96, v67, v96
	v_exp_f32_e32 v72, v72
	v_add_f32_e32 v96, v68, v96
	v_exp_f32_e32 v73, v73
	v_add_f32_e32 v96, v69, v96
	v_exp_f32_e32 v74, v74
	v_add_f32_e32 v96, v70, v96
	v_exp_f32_e32 v75, v75
	v_add_f32_e32 v96, v71, v96
	v_exp_f32_e32 v76, v76
	v_add_f32_e32 v96, v72, v96
	v_exp_f32_e32 v77, v77
	v_add_f32_e32 v96, v73, v96
	v_exp_f32_e32 v78, v78
	v_add_f32_e32 v96, v74, v96
	v_exp_f32_e32 v79, v79
	v_add_f32_e32 v96, v75, v96
	v_add_f32_e32 v96, v76, v96
	v_add_f32_e32 v96, v77, v96
	v_add_f32_e32 v96, v78, v96
	v_add_f32_e32 v96, v79, v96
	v_add_f32_e32 v96, v97, v96
	v_cvt_pk_bf16_f32 v64, v64, v65
	v_cvt_pk_bf16_f32 v65, v66, v67
	v_cvt_pk_bf16_f32 v66, v68, v69
	v_cvt_pk_bf16_f32 v67, v70, v71
	v_cvt_pk_bf16_f32 v68, v72, v73
	v_cvt_pk_bf16_f32 v69, v74, v75
	v_cvt_pk_bf16_f32 v70, v76, v77
	v_cvt_pk_bf16_f32 v71, v78, v79
	s_nop 0
	v_permlane32_swap_b32_e32 v64, v66
	v_permlane32_swap_b32_e32 v65, v67
	v_permlane32_swap_b32_e32 v68, v70
	v_permlane32_swap_b32_e32 v69, v71
	s_waitcnt lgkmcnt(0)
	s_setprio 0
	s_cmp_lt_u32 s33, 0x100
	s_cbranch_scc1 .Lstg_d0_m61_13
	s_waitcnt vmcnt(0)
	s_barrier

; DI int v_rd_base(int lane) { return ((lane & 3) << 3) | (((lane >> 2) & 3) << 6) | (((lane >> 4) & 1) << 5) | (((lane >> 5) & 1) << 8); }
; DI void expsum(f32x16& p, float& l_reg, bf16x8& pa0, bf16x8& pa1) {
; #pragma unroll
;     for (int r = 0; r < 16; ++r) p[r] = __builtin_amdgcn_exp2f(p[r]);
;     float ps = 0.f;
; #pragma unroll
;     for (int r = 0; r < 16; ++r) ps += p[r];
;     l_reg += ps; asm volatile("" : "+v"(l_reg));
;     ...
;     ATT_PK4(p, 0, pa0); ATT_PK4(p, 8, pa1);
;     ...
; }
; template <int DQK, int MODE, int LDQ, int LDK, int LDV> ...
;     ...
;     const int vbase = (int)(unsigned)(size_t)lds + V_OFF + v_rd_base(lane);
;     ...
;     constexpr int NDA = ND0 > 6 ? 6 : ND0;
.Lstg_d0_t62_14:
	s_setprio 1
	s_cmp_lg_u32 s58, 62
	s_cselect_b64 s[6:7], -1, 0
	s_and_b64 s[0:1], s[6:7], s[0:1]
	s_and_b64 vcc, exec, s[0:1]
	s_cbranch_vccnz .LBB0_1936
	v_cndmask_b32_e64 v98, v112, v113, s[4:5]
	v_pk_mul_f32 v[14:15], v[98:99], v[14:15] op_sel_hi:[0,1]
	v_pk_mul_f32 v[12:13], v[98:99], v[12:13] op_sel_hi:[0,1]
	v_pk_mul_f32 v[10:11], v[98:99], v[10:11] op_sel_hi:[0,1]
	v_pk_mul_f32 v[8:9], v[98:99], v[8:9] op_sel_hi:[0,1]
	v_pk_mul_f32 v[6:7], v[98:99], v[6:7] op_sel_hi:[0,1]
	v_pk_mul_f32 v[4:5], v[98:99], v[4:5] op_sel_hi:[0,1]
	v_pk_mul_f32 v[2:3], v[98:99], v[2:3] op_sel_hi:[0,1]
	v_pk_mul_f32 v[0:1], v[98:99], v[0:1] op_sel_hi:[0,1]
	v_pk_mul_f32 v[62:63], v[98:99], v[62:63] op_sel_hi:[0,1]
	v_pk_mul_f32 v[60:61], v[98:99], v[60:61] op_sel_hi:[0,1]
	v_pk_mul_f32 v[58:59], v[98:99], v[58:59] op_sel_hi:[0,1]
	v_pk_mul_f32 v[56:57], v[98:99], v[56:57] op_sel_hi:[0,1]
	v_pk_mul_f32 v[54:55], v[98:99], v[54:55] op_sel_hi:[0,1]
	v_pk_mul_f32 v[52:53], v[98:99], v[52:53] op_sel_hi:[0,1]
	v_pk_mul_f32 v[50:51], v[98:99], v[50:51] op_sel_hi:[0,1]
	v_pk_mul_f32 v[48:49], v[98:99], v[48:49] op_sel_hi:[0,1]
	v_pk_mul_f32 v[46:47], v[98:99], v[46:47] op_sel_hi:[0,1]
	v_pk_mul_f32 v[44:45], v[98:99], v[44:45] op_sel_hi:[0,1]
	v_pk_mul_f32 v[42:43], v[98:99], v[42:43] op_sel_hi:[0,1]
	v_pk_mul_f32 v[40:41], v[98:99], v[40:41] op_sel_hi:[0,1]
	v_pk_mul_f32 v[38:39], v[98:99], v[38:39] op_sel_hi:[0,1]
	v_pk_mul_f32 v[36:37], v[98:99], v[36:37] op_sel_hi:[0,1]
	v_pk_mul_f32 v[34:35], v[98:99], v[34:35] op_sel_hi:[0,1]
	v_pk_mul_f32 v[32:33], v[98:99], v[32:33] op_sel_hi:[0,1]
	v_pk_mul_f32 v[30:31], v[98:99], v[30:31] op_sel_hi:[0,1]
	v_pk_mul_f32 v[28:29], v[98:99], v[28:29] op_sel_hi:[0,1]
	v_pk_mul_f32 v[26:27], v[98:99], v[26:27] op_sel_hi:[0,1]
	v_pk_mul_f32 v[24:25], v[98:99], v[24:25] op_sel_hi:[0,1]
	v_pk_mul_f32 v[22:23], v[98:99], v[22:23] op_sel_hi:[0,1]
	v_pk_mul_f32 v[20:21], v[98:99], v[20:21] op_sel_hi:[0,1]
	v_pk_mul_f32 v[18:19], v[98:99], v[18:19] op_sel_hi:[0,1]
	v_pk_mul_f32 v[16:17], v[98:99], v[16:17] op_sel_hi:[0,1]
	v_mul_f32_e32 v96, v98, v96
.LBB0_1936:
	ds_read_b128 v[100:103], v107 offset:20480
	ds_read_b128 v[114:117], v108 offset:20480
	ds_read_b128 v[118:121], v109 offset:20480
	ds_read_b128 v[122:125], v110 offset:20480
	v_add_u32_e32 v98, 0x8000, v106
	ds_read_b64_tr_b16 v[132:133], v98 offset:0
	ds_read_b64_tr_b16 v[134:135], v98 offset:0x800
	ds_read_b64_tr_b16 v[136:137], v98 offset:0x1000
	ds_read_b64_tr_b16 v[138:139], v98 offset:0x1800
	ds_read_b64_tr_b16 v[140:141], v98 offset:0x200
	ds_read_b64_tr_b16 v[142:143], v98 offset:0xa00
	ds_read_b64_tr_b16 v[144:145], v98 offset:0x1200
	ds_read_b64_tr_b16 v[146:147], v98 offset:0x1a00
	ds_read_b64_tr_b16 v[148:149], v98 offset:0x400
	ds_read_b64_tr_b16 v[150:151], v98 offset:0xc00
	ds_read_b64_tr_b16 v[152:153], v98 offset:0x1400
	ds_read_b64_tr_b16 v[154:155], v98 offset:0x1c00
	ds_read_b64_tr_b16 v[156:157], v98 offset:0x600
	ds_read_b64_tr_b16 v[158:159], v98 offset:0xe00
	ds_read_b64_tr_b16 v[162:163], v98 offset:0x1600
	ds_read_b64_tr_b16 v[164:165], v98 offset:0x1e00
	v_exp_f32_e32 v64, v64
	v_exp_f32_e32 v65, v65
	v_exp_f32_e32 v66, v66
	v_exp_f32_e32 v67, v67
	v_exp_f32_e32 v68, v68
	v_add_f32_e32 v99, 0, v64
	v_exp_f32_e32 v69, v69
	v_add_f32_e32 v99, v65, v99
	v_exp_f32_e32 v70, v70
	v_add_f32_e32 v99, v66, v99
	v_exp_f32_e32 v71, v71
	v_add_f32_e32 v99, v67, v99
	v_exp_f32_e32 v72, v72
	v_add_f32_e32 v99, v68, v99
	v_exp_f32_e32 v73, v73
	v_add_f32_e32 v99, v69, v99
	v_exp_f32_e32 v74, v74
	v_add_f32_e32 v99, v70, v99
	v_exp_f32_e32 v75, v75
	v_add_f32_e32 v99, v71, v99
	v_exp_f32_e32 v76, v76
	v_add_f32_e32 v99, v72, v99
	v_exp_f32_e32 v77, v77
	v_add_f32_e32 v99, v73, v99
	v_exp_f32_e32 v78, v78
	v_add_f32_e32 v99, v74, v99
	v_exp_f32_e32 v79, v79
	v_add_f32_e32 v99, v75, v99
	v_add_f32_e32 v99, v76, v99
	v_add_f32_e32 v99, v77, v99
	v_add_f32_e32 v99, v78, v99
	v_add_f32_e32 v99, v79, v99
	v_add_f32_e32 v96, v99, v96
	v_cvt_pk_bf16_f32 v64, v64, v65
	v_cvt_pk_bf16_f32 v65, v66, v67
	v_cvt_pk_bf16_f32 v66, v68, v69
	v_cvt_pk_bf16_f32 v67, v70, v71
	v_cvt_pk_bf16_f32 v68, v72, v73
	v_cvt_pk_bf16_f32 v69, v74, v75
	v_cvt_pk_bf16_f32 v70, v76, v77
	v_cvt_pk_bf16_f32 v71, v78, v79
	s_nop 0
	v_permlane32_swap_b32_e32 v64, v66
	v_permlane32_swap_b32_e32 v65, v67
	v_permlane32_swap_b32_e32 v68, v70
	v_permlane32_swap_b32_e32 v69, v71
	s_waitcnt lgkmcnt(0)
	s_setprio 0
	v_mfma_f32_32x32x16_bf16 v[0:15], v[64:67], v[132:135], v[0:15]
	s_and_b64 vcc, exec, s[2:3]
	v_mfma_f32_32x32x16_bf16 v[48:63], v[64:67], v[140:143], v[48:63]
	v_mfma_f32_32x32x16_bf16 v[32:47], v[64:67], v[148:151], v[32:47]
	v_mfma_f32_32x32x16_bf16 v[16:31], v[64:67], v[156:159], v[16:31]
	v_mfma_f32_32x32x16_bf16 v[0:15], v[68:71], v[136:139], v[0:15]
	v_mfma_f32_32x32x16_bf16 v[48:63], v[68:71], v[144:147], v[48:63]
	v_mfma_f32_32x32x16_bf16 v[32:47], v[68:71], v[152:155], v[32:47]
	v_mfma_f32_32x32x16_bf16 v[16:31], v[68:71], v[162:165], v[16:31]
	s_waitcnt lgkmcnt(0)
	v_mfma_f32_32x32x16_bf16 v[64:79], v[100:103], v[92:95], 0
	v_mfma_f32_32x32x16_bf16 v[64:79], v[114:117], v[88:91], v[64:79]
	v_mfma_f32_32x32x16_bf16 v[64:79], v[118:121], v[84:87], v[64:79]
	v_mfma_f32_32x32x16_bf16 v[64:79], v[122:125], v[80:83], v[64:79]
	s_setprio 1
	s_cbranch_vccnz .LBB0_1938
	v_add3_u32 v97, s88, v97, v130
	v_add_u32_e32 v118, 0x408, v97
	v_add_u32_e32 v120, 0x420, v97
	v_add_u32_e32 v122, 0x428, v97
	v_add_u32_e32 v100, 0x440, v97
	v_add_u32_e32 v102, 0x448, v97
	v_add_u32_e32 v104, 0x460, v97
	v_add_u32_e32 v99, 0x400, v97
	v_add_u32_e32 v97, 0x468, v97
	ds_read2_b32 v[100:101], v100 offset1:1
	ds_read2_b32 v[102:103], v102 offset1:1
	ds_read2_b32 v[104:105], v104 offset1:1
	ds_read2_b32 v[114:115], v97 offset1:1
	ds_read2_b32 v[116:117], v99 offset1:1
	ds_read2_b32 v[118:119], v118 offset1:1
	ds_read2_b32 v[120:121], v120 offset1:1
	ds_read2_b32 v[122:123], v122 offset1:1
	s_waitcnt lgkmcnt(0)
	v_pk_add_f32 v[78:79], v[78:79], v[114:115]
	v_pk_add_f32 v[76:77], v[76:77], v[104:105]
	v_pk_add_f32 v[74:75], v[74:75], v[102:103]
	v_pk_add_f32 v[72:73], v[72:73], v[100:101]
	v_pk_add_f32 v[70:71], v[70:71], v[122:123]
	v_pk_add_f32 v[68:69], v[68:69], v[120:121]
	v_pk_add_f32 v[66:67], v[66:67], v[118:119]
	v_pk_add_f32 v[64:65], v[64:65], v[116:117]
; DI void expsum(f32x16& p, float& l_reg, bf16x8& pa0, bf16x8& pa1) {
; #pragma unroll
;     for (int r = 0; r < 16; ++r) p[r] = __builtin_amdgcn_exp2f(p[r]);
;     float ps = 0.f;
; #pragma unroll
;     for (int r = 0; r < 16; ++r) ps += p[r];
;     l_reg += ps; asm volatile("" : "+v"(l_reg));
;     ...
;     ATT_PK4(p, 0, pa0); ATT_PK4(p, 8, pa1);
;     ...
; }
.LBB0_1938:
	ds_read_b128 v[100:103], v107 offset:24576
	ds_read_b128 v[114:117], v108 offset:24576
	ds_read_b128 v[118:121], v109 offset:24576
	ds_read_b128 v[122:125], v110 offset:24576
	ds_read_b64_tr_b16 v[132:133], v98 offset:0x2000
	ds_read_b64_tr_b16 v[134:135], v98 offset:0x2800
	ds_read_b64_tr_b16 v[136:137], v98 offset:0x3000
	ds_read_b64_tr_b16 v[138:139], v98 offset:0x3800
	ds_read_b64_tr_b16 v[140:141], v98 offset:0x2200
	ds_read_b64_tr_b16 v[142:143], v98 offset:0x2a00
	ds_read_b64_tr_b16 v[144:145], v98 offset:0x3200
	ds_read_b64_tr_b16 v[146:147], v98 offset:0x3a00
	ds_read_b64_tr_b16 v[148:149], v98 offset:0x2400
	ds_read_b64_tr_b16 v[150:151], v98 offset:0x2c00
	ds_read_b64_tr_b16 v[152:153], v98 offset:0x3400
	ds_read_b64_tr_b16 v[154:155], v98 offset:0x3c00
	ds_read_b64_tr_b16 v[156:157], v98 offset:0x2600
	ds_read_b64_tr_b16 v[158:159], v98 offset:0x2e00
	ds_read_b64_tr_b16 v[162:163], v98 offset:0x3600
	ds_read_b64_tr_b16 v[164:165], v98 offset:0x3e00
	s_nop 6
	v_exp_f32_e32 v64, v64
	v_exp_f32_e32 v65, v65
	v_exp_f32_e32 v66, v66
	v_exp_f32_e32 v67, v67
	v_exp_f32_e32 v68, v68
	v_add_f32_e32 v97, 0, v64
	v_exp_f32_e32 v69, v69
	v_add_f32_e32 v97, v65, v97
	v_exp_f32_e32 v70, v70
	v_add_f32_e32 v97, v66, v97
	v_exp_f32_e32 v71, v71
	v_add_f32_e32 v97, v67, v97
	v_exp_f32_e32 v72, v72
	v_add_f32_e32 v97, v68, v97
	v_exp_f32_e32 v73, v73
	v_add_f32_e32 v97, v69, v97
	v_exp_f32_e32 v74, v74
	v_add_f32_e32 v97, v70, v97
	v_exp_f32_e32 v75, v75
	v_add_f32_e32 v97, v71, v97
	v_exp_f32_e32 v76, v76
	v_add_f32_e32 v97, v72, v97
	v_exp_f32_e32 v77, v77
	v_add_f32_e32 v97, v73, v97
	v_exp_f32_e32 v78, v78
	v_add_f32_e32 v97, v74, v97
	v_exp_f32_e32 v79, v79
	v_add_f32_e32 v97, v75, v97
	v_add_f32_e32 v97, v76, v97
	v_add_f32_e32 v97, v77, v97
	v_add_f32_e32 v97, v78, v97
	v_add_f32_e32 v97, v79, v97
	v_add_f32_e32 v96, v96, v97
	v_cvt_pk_bf16_f32 v64, v64, v65
	v_cvt_pk_bf16_f32 v65, v66, v67
	v_cvt_pk_bf16_f32 v66, v68, v69
	v_cvt_pk_bf16_f32 v67, v70, v71
	v_cvt_pk_bf16_f32 v68, v72, v73
	v_cvt_pk_bf16_f32 v69, v74, v75
	v_cvt_pk_bf16_f32 v70, v76, v77
	v_cvt_pk_bf16_f32 v71, v78, v79
	s_nop 0
	v_permlane32_swap_b32_e32 v64, v66
	v_permlane32_swap_b32_e32 v65, v67
	v_permlane32_swap_b32_e32 v68, v70
	v_permlane32_swap_b32_e32 v69, v71
	s_waitcnt lgkmcnt(0)
	s_setprio 0
	s_cmp_lt_u32 s33, 0x100
	s_cbranch_scc1 .Lstg_d0_m62_15
	s_waitcnt vmcnt(0)
	s_barrier

; DI int v_rd_base(int lane) { return ((lane & 3) << 3) | (((lane >> 2) & 3) << 6) | (((lane >> 4) & 1) << 5) | (((lane >> 5) & 1) << 8); }
; DI void expsum(f32x16& p, float& l_reg, bf16x8& pa0, bf16x8& pa1) {
; #pragma unroll
;     for (int r = 0; r < 16; ++r) p[r] = __builtin_amdgcn_exp2f(p[r]);
;     float ps = 0.f;
; #pragma unroll
;     for (int r = 0; r < 16; ++r) ps += p[r];
;     l_reg += ps; asm volatile("" : "+v"(l_reg));
;     ...
;     ATT_PK4(p, 0, pa0); ATT_PK4(p, 8, pa1);
;     ...
; }
; template <int DQK, int MODE, int LDQ, int LDK, int LDV> ...
;     ...
;     const int vbase = (int)(unsigned)(size_t)lds + V_OFF + v_rd_base(lane);
;     ...
;     constexpr int NDA = ND0 > 6 ? 6 : ND0;
.Lstg_d0_t63_16:
	s_setprio 1
	s_cmp_lg_u32 s58, 63
	s_cselect_b64 s[6:7], -1, 0
	s_and_b64 s[0:1], s[6:7], s[0:1]
	s_and_b64 vcc, exec, s[0:1]
	s_cbranch_vccnz .LBB0_1942
	v_cndmask_b32_e64 v98, v112, v113, s[4:5]
	v_pk_mul_f32 v[14:15], v[98:99], v[14:15] op_sel_hi:[0,1]
	v_pk_mul_f32 v[12:13], v[98:99], v[12:13] op_sel_hi:[0,1]
	v_pk_mul_f32 v[10:11], v[98:99], v[10:11] op_sel_hi:[0,1]
	v_pk_mul_f32 v[8:9], v[98:99], v[8:9] op_sel_hi:[0,1]
	v_pk_mul_f32 v[6:7], v[98:99], v[6:7] op_sel_hi:[0,1]
	v_pk_mul_f32 v[4:5], v[98:99], v[4:5] op_sel_hi:[0,1]
	v_pk_mul_f32 v[2:3], v[98:99], v[2:3] op_sel_hi:[0,1]
	v_pk_mul_f32 v[0:1], v[98:99], v[0:1] op_sel_hi:[0,1]
	v_pk_mul_f32 v[62:63], v[98:99], v[62:63] op_sel_hi:[0,1]
	v_pk_mul_f32 v[60:61], v[98:99], v[60:61] op_sel_hi:[0,1]
	v_pk_mul_f32 v[58:59], v[98:99], v[58:59] op_sel_hi:[0,1]
	v_pk_mul_f32 v[56:57], v[98:99], v[56:57] op_sel_hi:[0,1]
	v_pk_mul_f32 v[54:55], v[98:99], v[54:55] op_sel_hi:[0,1]
	v_pk_mul_f32 v[52:53], v[98:99], v[52:53] op_sel_hi:[0,1]
	v_pk_mul_f32 v[50:51], v[98:99], v[50:51] op_sel_hi:[0,1]
	v_pk_mul_f32 v[48:49], v[98:99], v[48:49] op_sel_hi:[0,1]
	v_pk_mul_f32 v[46:47], v[98:99], v[46:47] op_sel_hi:[0,1]
	v_pk_mul_f32 v[44:45], v[98:99], v[44:45] op_sel_hi:[0,1]
	v_pk_mul_f32 v[42:43], v[98:99], v[42:43] op_sel_hi:[0,1]
	v_pk_mul_f32 v[40:41], v[98:99], v[40:41] op_sel_hi:[0,1]
	v_pk_mul_f32 v[38:39], v[98:99], v[38:39] op_sel_hi:[0,1]
	v_pk_mul_f32 v[36:37], v[98:99], v[36:37] op_sel_hi:[0,1]
	v_pk_mul_f32 v[34:35], v[98:99], v[34:35] op_sel_hi:[0,1]
	v_pk_mul_f32 v[32:33], v[98:99], v[32:33] op_sel_hi:[0,1]
	v_pk_mul_f32 v[30:31], v[98:99], v[30:31] op_sel_hi:[0,1]
	v_pk_mul_f32 v[28:29], v[98:99], v[28:29] op_sel_hi:[0,1]
	v_pk_mul_f32 v[26:27], v[98:99], v[26:27] op_sel_hi:[0,1]
	v_pk_mul_f32 v[24:25], v[98:99], v[24:25] op_sel_hi:[0,1]
	v_pk_mul_f32 v[22:23], v[98:99], v[22:23] op_sel_hi:[0,1]
	v_pk_mul_f32 v[20:21], v[98:99], v[20:21] op_sel_hi:[0,1]
	v_pk_mul_f32 v[18:19], v[98:99], v[18:19] op_sel_hi:[0,1]
	v_pk_mul_f32 v[16:17], v[98:99], v[16:17] op_sel_hi:[0,1]
	v_mul_f32_e32 v96, v98, v96
.LBB0_1942:
	ds_read_b128 v[98:101], v107 offset:28672
	ds_read_b128 v[102:105], v108 offset:28672
	ds_read_b128 v[112:115], v109 offset:28672
	ds_read_b128 v[108:111], v110 offset:28672
	ds_read_b64_tr_b16 v[116:117], v106 offset:0
	ds_read_b64_tr_b16 v[118:119], v106 offset:0x800
	ds_read_b64_tr_b16 v[120:121], v106 offset:0x1000
	ds_read_b64_tr_b16 v[122:123], v106 offset:0x1800
	ds_read_b64_tr_b16 v[124:125], v106 offset:0x200
	ds_read_b64_tr_b16 v[126:127], v106 offset:0xa00
	ds_read_b64_tr_b16 v[132:133], v106 offset:0x1200
	ds_read_b64_tr_b16 v[134:135], v106 offset:0x1a00
	ds_read_b64_tr_b16 v[136:137], v106 offset:0x400
	ds_read_b64_tr_b16 v[138:139], v106 offset:0xc00
	ds_read_b64_tr_b16 v[140:141], v106 offset:0x1400
	ds_read_b64_tr_b16 v[142:143], v106 offset:0x1c00
	ds_read_b64_tr_b16 v[144:145], v106 offset:0x600
	ds_read_b64_tr_b16 v[146:147], v106 offset:0xe00
	ds_read_b64_tr_b16 v[148:149], v106 offset:0x1600
	ds_read_b64_tr_b16 v[150:151], v106 offset:0x1e00
	v_exp_f32_e32 v64, v64
	v_exp_f32_e32 v65, v65
	v_exp_f32_e32 v66, v66
	v_exp_f32_e32 v67, v67
	v_exp_f32_e32 v68, v68
	v_add_f32_e32 v107, 0, v64
	v_exp_f32_e32 v69, v69
	v_add_f32_e32 v107, v65, v107
	v_exp_f32_e32 v70, v70
	v_add_f32_e32 v107, v66, v107
	v_exp_f32_e32 v71, v71
	v_add_f32_e32 v107, v67, v107
	v_exp_f32_e32 v72, v72
	v_add_f32_e32 v107, v68, v107
	v_exp_f32_e32 v73, v73
	v_add_f32_e32 v107, v69, v107
	v_exp_f32_e32 v74, v74
	v_add_f32_e32 v107, v70, v107
	v_exp_f32_e32 v75, v75
	v_add_f32_e32 v107, v71, v107
	v_exp_f32_e32 v76, v76
	v_add_f32_e32 v107, v72, v107
	v_exp_f32_e32 v77, v77
	v_add_f32_e32 v107, v73, v107
	v_exp_f32_e32 v78, v78
	v_add_f32_e32 v107, v74, v107
	v_exp_f32_e32 v79, v79
	v_add_f32_e32 v107, v75, v107
	v_add_f32_e32 v107, v76, v107
	v_add_f32_e32 v107, v77, v107
	v_add_f32_e32 v107, v78, v107
	v_add_f32_e32 v107, v79, v107
	v_add_f32_e32 v96, v107, v96
	v_cvt_pk_bf16_f32 v64, v64, v65
	v_cvt_pk_bf16_f32 v65, v66, v67
	v_cvt_pk_bf16_f32 v66, v68, v69
	v_cvt_pk_bf16_f32 v67, v70, v71
	v_cvt_pk_bf16_f32 v68, v72, v73
	v_cvt_pk_bf16_f32 v69, v74, v75
	v_cvt_pk_bf16_f32 v70, v76, v77
	v_cvt_pk_bf16_f32 v71, v78, v79
	s_nop 0
	v_permlane32_swap_b32_e32 v64, v66
	v_permlane32_swap_b32_e32 v65, v67
	v_permlane32_swap_b32_e32 v68, v70
	v_permlane32_swap_b32_e32 v69, v71
	s_waitcnt lgkmcnt(0)
	s_setprio 0
	v_mfma_f32_32x32x16_bf16 v[0:15], v[64:67], v[116:119], v[0:15]
	s_and_b64 vcc, exec, s[2:3]
	v_mfma_f32_32x32x16_bf16 v[48:63], v[64:67], v[124:127], v[48:63]
	v_mfma_f32_32x32x16_bf16 v[32:47], v[64:67], v[136:139], v[32:47]
	v_mfma_f32_32x32x16_bf16 v[16:31], v[64:67], v[144:147], v[16:31]
	v_mfma_f32_32x32x16_bf16 v[0:15], v[68:71], v[120:123], v[0:15]
	v_mfma_f32_32x32x16_bf16 v[48:63], v[68:71], v[132:135], v[48:63]
	v_mfma_f32_32x32x16_bf16 v[32:47], v[68:71], v[140:143], v[32:47]
	v_mfma_f32_32x32x16_bf16 v[16:31], v[68:71], v[148:151], v[16:31]
	s_waitcnt lgkmcnt(0)
	v_mfma_f32_32x32x16_bf16 v[64:79], v[98:101], v[92:95], 0
	v_mfma_f32_32x32x16_bf16 v[64:79], v[102:105], v[88:91], v[64:79]
	v_mfma_f32_32x32x16_bf16 v[64:79], v[112:115], v[84:87], v[64:79]
	v_mfma_f32_32x32x16_bf16 v[64:79], v[108:111], v[80:83], v[64:79]
	s_setprio 1
	s_cbranch_vccnz .LBB0_1944
	v_add3_u32 v80, s88, v97, v130
	v_add_u32_e32 v88, 0x400, v80
	v_add_u32_e32 v90, 0x408, v80
	v_add_u32_e32 v92, 0x420, v80
	v_add_u32_e32 v94, 0x428, v80
	v_add_u32_e32 v81, 0x440, v80
	v_add_u32_e32 v82, 0x448, v80
	v_add_u32_e32 v84, 0x460, v80
	v_add_u32_e32 v86, 0x468, v80
	ds_read2_b32 v[80:81], v81 offset1:1
	ds_read2_b32 v[82:83], v82 offset1:1
	ds_read2_b32 v[84:85], v84 offset1:1
	ds_read2_b32 v[86:87], v86 offset1:1
	ds_read2_b32 v[88:89], v88 offset1:1
	ds_read2_b32 v[90:91], v90 offset1:1
	ds_read2_b32 v[92:93], v92 offset1:1
	ds_read2_b32 v[94:95], v94 offset1:1
	s_waitcnt lgkmcnt(0)
	v_pk_add_f32 v[78:79], v[78:79], v[86:87]
	v_pk_add_f32 v[76:77], v[76:77], v[84:85]
	v_pk_add_f32 v[74:75], v[74:75], v[82:83]
	v_pk_add_f32 v[72:73], v[72:73], v[80:81]
	v_pk_add_f32 v[70:71], v[70:71], v[94:95]
	v_pk_add_f32 v[68:69], v[68:69], v[92:93]
	v_pk_add_f32 v[66:67], v[66:67], v[90:91]
	v_pk_add_f32 v[64:65], v[64:65], v[88:89]
; template <int TAG = 0> DI int fresh_tid(int wv) { int l; asm volatile("v_mbcnt_lo_u32_b32 %0, -1, 0\n\tv_mbcnt_hi_u32_b32 %0, -1, %0 ; site %1" : "=v"(l) : "n"(TAG)); return wv * 64 + l; }
; DI unsigned short f2bf(float x) { unsigned u = __float_as_uint(x); u += 0x7fffu + ((u >> 16) & 1u); return (unsigned short)(u >> 16); }
; DI int crow(int r, int hi) { return (r & 3) + 8 * (r >> 2) + 4 * hi; }
; DI float swap_sum(float v) { auto rr = __builtin_amdgcn_permlane32_swap(__float_as_uint(v), __float_as_uint(v), false, false); return __uint_as_float(rr[0]) + __uint_as_float(rr[1]); }
; template <int DQK, int MODE, int LDQ, int LDK, int LDV> ...
;     ...
;         ATT_STEP(pB, pA, 1, v0, (j + 1 < NT), 0, j + 1);
;         { const int t_ = v0; v0 = v1; v1 = v2; v2 = t_; }
;     }
;     __builtin_amdgcn_s_setprio(0);
;     ...
;     l_reg = swap_sum(l_reg);
;     { const int lane2 = fresh_tid<110 + MODE>(wv) & 63, r32 = lane2 & 31, hi = lane2 >> 5;
;     if (hi == 0) li_l[r32] = l_reg;
;     asm volatile("s_waitcnt lgkmcnt(0)" ::: "memory");
;     float s0v[MODE == 2 ? 16 : 1][4];
;     if constexpr (MODE == 2) {
; #pragma unroll
;         for (int r = 0; r < 16; ++r)
; #pragma unroll
;             for (int d0 = 0; d0 < 4; ++d0) s0v[r][d0] = S0[(size_t)(wid * 32 + crow(r, hi)) * 512 + d0 * 32 + r32];
;     }
; #pragma unroll
;     for (int r = 0; r < 16; ++r) { const int orow = wid * 32 + crow(r, hi); const float rl = __builtin_amdgcn_rcpf(li_l[crow(r, hi)]);
;         if constexpr (MODE == 0) {
; #pragma unroll
;             for (int d0 = 0; d0 < 4; ++d0) AOb[(size_t)orow * 1024 + d0 * 32 + r32] = f2bf(o[d0][r] * rl);
;         } else if constexpr (MODE == 1) {
; #pragma unroll
;             for (int d0 = 0; d0 < 4; ++d0) S0[(size_t)orow * 512 + d0 * 32 + r32] = o[d0][r] * rl;
.LBB0_1944:
	s_lshl_b32 s0, s54, 2
	s_add_i32 s0, s0, 0
	s_add_i32 s0, s0, 0x24000
	ds_read_b64_tr_b16 v[80:81], v106 offset:0x2000
	ds_read_b64_tr_b16 v[82:83], v106 offset:0x2800
	ds_read_b64_tr_b16 v[84:85], v106 offset:0x3000
	ds_read_b64_tr_b16 v[86:87], v106 offset:0x3800
	ds_read_b64_tr_b16 v[88:89], v106 offset:0x2200
	ds_read_b64_tr_b16 v[90:91], v106 offset:0x2a00
	ds_read_b64_tr_b16 v[92:93], v106 offset:0x3200
	ds_read_b64_tr_b16 v[94:95], v106 offset:0x3a00
	ds_read_b64_tr_b16 v[98:99], v106 offset:0x2400
	ds_read_b64_tr_b16 v[100:101], v106 offset:0x2c00
	ds_read_b64_tr_b16 v[102:103], v106 offset:0x3400
	ds_read_b64_tr_b16 v[104:105], v106 offset:0x3c00
	ds_read_b64_tr_b16 v[108:109], v106 offset:0x2600
	ds_read_b64_tr_b16 v[110:111], v106 offset:0x2e00
	ds_read_b64_tr_b16 v[112:113], v106 offset:0x3600
	ds_read_b64_tr_b16 v[114:115], v106 offset:0x3e00
	s_nop 7
	v_exp_f32_e32 v97, v64
	v_exp_f32_e32 v65, v65
	v_exp_f32_e32 v106, v66
	v_exp_f32_e32 v67, v67
	v_exp_f32_e32 v68, v68
	v_add_f32_e32 v64, 0, v97
	v_exp_f32_e32 v69, v69
	v_add_f32_e32 v64, v65, v64
	v_exp_f32_e32 v70, v70
	v_add_f32_e32 v64, v106, v64
	v_exp_f32_e32 v71, v71
	v_add_f32_e32 v64, v67, v64
	v_exp_f32_e32 v72, v72
	v_add_f32_e32 v64, v68, v64
	v_exp_f32_e32 v73, v73
	v_add_f32_e32 v64, v69, v64
	v_exp_f32_e32 v74, v74
	v_add_f32_e32 v64, v70, v64
	v_exp_f32_e32 v75, v75
	v_add_f32_e32 v64, v71, v64
	v_exp_f32_e32 v76, v76
	v_add_f32_e32 v64, v72, v64
	v_exp_f32_e32 v77, v77
	v_add_f32_e32 v64, v73, v64
	v_exp_f32_e32 v78, v78
	v_add_f32_e32 v64, v74, v64
	v_exp_f32_e32 v79, v79
	v_add_f32_e32 v64, v75, v64
	v_add_f32_e32 v64, v76, v64
	v_add_f32_e32 v64, v77, v64
	v_add_f32_e32 v64, v78, v64
	v_add_f32_e32 v64, v79, v64
	v_add_f32_e32 v64, v96, v64
	v_cvt_pk_bf16_f32 v66, v97, v65
	v_cvt_pk_bf16_f32 v67, v106, v67
	v_cvt_pk_bf16_f32 v68, v68, v69
	v_cvt_pk_bf16_f32 v69, v70, v71
	v_cvt_pk_bf16_f32 v70, v72, v73
	v_cvt_pk_bf16_f32 v71, v74, v75
	v_cvt_pk_bf16_f32 v72, v76, v77
	v_cvt_pk_bf16_f32 v73, v78, v79
	s_nop 0
	v_permlane32_swap_b32_e32 v66, v68
	v_permlane32_swap_b32_e32 v67, v69
	v_permlane32_swap_b32_e32 v70, v72
	v_permlane32_swap_b32_e32 v71, v73
	s_waitcnt lgkmcnt(0)
	s_setprio 0
	v_mfma_f32_32x32x16_bf16 v[0:15], v[66:69], v[80:83], v[0:15]
	v_mfma_f32_32x32x16_bf16 v[48:63], v[66:69], v[88:91], v[48:63]
	v_mfma_f32_32x32x16_bf16 v[32:47], v[66:69], v[98:101], v[32:47]
	v_mfma_f32_32x32x16_bf16 v[16:31], v[66:69], v[108:111], v[16:31]
	v_mfma_f32_32x32x16_bf16 v[0:15], v[70:73], v[84:87], v[0:15]
	v_mfma_f32_32x32x16_bf16 v[48:63], v[70:73], v[92:95], v[48:63]
	v_mfma_f32_32x32x16_bf16 v[32:47], v[70:73], v[102:105], v[32:47]
	v_mfma_f32_32x32x16_bf16 v[16:31], v[70:73], v[112:115], v[16:31]
	s_setprio 0
	v_mbcnt_lo_u32_b32 v66, -1, 0
	v_mbcnt_hi_u32_b32 v66, -1, v66
	v_mov_b32_e32 v67, v64
	v_and_b32_e32 v65, 31, v66
	v_bfe_u32 v66, v66, 5, 1
	v_permlane32_swap_b32_e32 v64, v67
	v_cmp_eq_u32_e32 vcc, 0, v66
	s_and_saveexec_b64 s[2:3], vcc
	v_lshl_add_u32 v68, v65, 2, s0
	v_add_f32_e32 v64, v64, v67
	ds_write_b32 v68, v64
	s_or_b64 exec, exec, s[2:3]
	s_waitcnt lgkmcnt(0)
	v_lshl_add_u32 v68, v66, 4, s0
	ds_read_b128 v[70:73], v68
	ds_read_b128 v[74:77], v68 offset:32
	s_lshl_b64 s[58:59], s[40:41], 11
	v_readlane_b32 s1, v255, 2
	s_add_u32 s1, s1, s58
	v_readlane_b32 s2, v255, 0
	s_addc_u32 s2, s2, s59
	s_lshl_b32 s3, s87, 2
	s_waitcnt lgkmcnt(0)
	v_rcp_f32_e32 v69, v70
	s_add_u32 s54, s1, s3
	v_lshl_or_b32 v66, v66, 2, s94
	s_addc_u32 s55, s2, 0
	v_lshlrev_b32_e32 v130, 2, v65
	v_ashrrev_i32_e32 v67, 31, v66
	v_lshl_add_u64 v[64:65], s[54:55], 0, v[130:131]
	v_lshlrev_b64 v[78:79], 11, v[66:67]
	v_lshl_add_u64 v[78:79], v[64:65], 0, v[78:79]
	v_mul_f32_e32 v0, v0, v69
	global_store_dword v[78:79], v0, off
	v_mul_f32_e32 v0, v48, v69
	global_store_dword v[78:79], v0, off offset:128
	v_mul_f32_e32 v0, v32, v69
	global_store_dword v[78:79], v0, off offset:256
	v_mul_f32_e32 v0, v16, v69
	global_store_dword v[78:79], v0, off offset:384
	v_rcp_f32_e32 v0, v71
	v_or_b32_e32 v70, 1, v66
	v_ashrrev_i32_e32 v71, 31, v70
	v_lshlrev_b64 v[70:71], 11, v[70:71]
	v_lshl_add_u64 v[70:71], v[64:65], 0, v[70:71]
	v_mul_f32_e32 v1, v1, v0
	global_store_dword v[70:71], v1, off
	v_mul_f32_e32 v1, v49, v0
	global_store_dword v[70:71], v1, off offset:128
	v_mul_f32_e32 v1, v33, v0
	v_mul_f32_e32 v0, v17, v0
	v_rcp_f32_e32 v16, v72
	global_store_dword v[70:71], v0, off offset:384
	v_or_b32_e32 v0, 2, v66
	global_store_dword v[70:71], v1, off offset:256
	v_ashrrev_i32_e32 v1, 31, v0
	v_lshlrev_b64 v[0:1], 11, v[0:1]
	v_lshl_add_u64 v[0:1], v[64:65], 0, v[0:1]
	v_mul_f32_e32 v2, v2, v16
	global_store_dword v[0:1], v2, off
	v_mul_f32_e32 v2, v50, v16
	global_store_dword v[0:1], v2, off offset:128
	v_mul_f32_e32 v2, v34, v16
	global_store_dword v[0:1], v2, off offset:256
	v_mul_f32_e32 v2, v18, v16
	global_store_dword v[0:1], v2, off offset:384
	v_rcp_f32_e32 v2, v73
	v_or_b32_e32 v0, 3, v66
	v_ashrrev_i32_e32 v1, 31, v0
	v_lshlrev_b64 v[0:1], 11, v[0:1]
	v_lshl_add_u64 v[0:1], v[64:65], 0, v[0:1]
	v_mul_f32_e32 v3, v3, v2
	global_store_dword v[0:1], v3, off
	v_mul_f32_e32 v3, v51, v2
	global_store_dword v[0:1], v3, off offset:128
	v_mul_f32_e32 v3, v35, v2
	v_mul_f32_e32 v2, v19, v2
	global_store_dword v[0:1], v2, off offset:384
	v_rcp_f32_e32 v2, v74
	global_store_dword v[0:1], v3, off offset:256
	v_or_b32_e32 v0, 8, v66
	v_ashrrev_i32_e32 v1, 31, v0
	v_lshlrev_b64 v[0:1], 11, v[0:1]
	v_lshl_add_u64 v[0:1], v[64:65], 0, v[0:1]
	v_mul_f32_e32 v3, v4, v2
	global_store_dword v[0:1], v3, off
	v_mul_f32_e32 v3, v52, v2
	global_store_dword v[0:1], v3, off offset:128
; DI unsigned short f2bf(float x) { unsigned u = __float_as_uint(x); u += 0x7fffu + ((u >> 16) & 1u); return (unsigned short)(u >> 16); }
; DI int crow(int r, int hi) { return (r & 3) + 8 * (r >> 2) + 4 * hi; }
; template <int DQK, int MODE, int LDQ, int LDK, int LDV> ...
;     ...
;     for (int r = 0; r < 16; ++r) { const int orow = wid * 32 + crow(r, hi); const float rl = __builtin_amdgcn_rcpf(li_l[crow(r, hi)]);
;         if constexpr (MODE == 0) {
; #pragma unroll
;             for (int d0 = 0; d0 < 4; ++d0) AOb[(size_t)orow * 1024 + d0 * 32 + r32] = f2bf(o[d0][r] * rl);
;         } else if constexpr (MODE == 1) {
; #pragma unroll
;             for (int d0 = 0; d0 < 4; ++d0) S0[(size_t)orow * 512 + d0 * 32 + r32] = o[d0][r] * rl;
	v_mul_f32_e32 v3, v36, v2
	v_mul_f32_e32 v2, v20, v2
	global_store_dword v[0:1], v2, off offset:384
	v_rcp_f32_e32 v2, v75
	global_store_dword v[0:1], v3, off offset:256
	v_or_b32_e32 v0, 9, v66
	v_ashrrev_i32_e32 v1, 31, v0
	v_lshlrev_b64 v[0:1], 11, v[0:1]
	v_lshl_add_u64 v[0:1], v[64:65], 0, v[0:1]
	v_mul_f32_e32 v3, v5, v2
	global_store_dword v[0:1], v3, off
	v_mul_f32_e32 v3, v53, v2
	global_store_dword v[0:1], v3, off offset:128
	v_mul_f32_e32 v3, v37, v2
	v_mul_f32_e32 v2, v21, v2
	global_store_dword v[0:1], v2, off offset:384
	v_rcp_f32_e32 v2, v76
	global_store_dword v[0:1], v3, off offset:256
	v_or_b32_e32 v0, 10, v66
	v_ashrrev_i32_e32 v1, 31, v0
	v_lshlrev_b64 v[0:1], 11, v[0:1]
	v_lshl_add_u64 v[0:1], v[64:65], 0, v[0:1]
	v_mul_f32_e32 v3, v6, v2
	global_store_dword v[0:1], v3, off
	v_mul_f32_e32 v3, v54, v2
	global_store_dword v[0:1], v3, off offset:128
	v_mul_f32_e32 v3, v38, v2
	v_mul_f32_e32 v2, v22, v2
	v_rcp_f32_e32 v6, v77
	global_store_dword v[0:1], v3, off offset:256
	global_store_dword v[0:1], v2, off offset:384
	v_or_b32_e32 v0, 11, v66
	v_ashrrev_i32_e32 v1, 31, v0
	v_lshlrev_b64 v[0:1], 11, v[0:1]
	v_lshl_add_u64 v[4:5], v[64:65], 0, v[0:1]
	v_mul_f32_e32 v0, v7, v6
	global_store_dword v[4:5], v0, off
	v_mul_f32_e32 v0, v55, v6
	global_store_dword v[4:5], v0, off offset:128
	v_mul_f32_e32 v0, v39, v6
	global_store_dword v[4:5], v0, off offset:256
	ds_read_b128 v[0:3], v68 offset:64
	v_mul_f32_e32 v6, v23, v6
	global_store_dword v[4:5], v6, off offset:384
	ds_read_b128 v[4:7], v68 offset:96
	v_or_b32_e32 v16, 16, v66
	s_waitcnt lgkmcnt(0)
	v_rcp_f32_e32 v0, v0
	v_ashrrev_i32_e32 v17, 31, v16
	v_lshlrev_b64 v[16:17], 11, v[16:17]
	v_lshl_add_u64 v[16:17], v[64:65], 0, v[16:17]
	v_mul_f32_e32 v8, v8, v0
	global_store_dword v[16:17], v8, off
	v_mul_f32_e32 v8, v56, v0
	global_store_dword v[16:17], v8, off offset:128
	v_mul_f32_e32 v8, v40, v0
	global_store_dword v[16:17], v8, off offset:256
	v_mul_f32_e32 v0, v24, v0
	v_rcp_f32_e32 v8, v1
	global_store_dword v[16:17], v0, off offset:384
	v_or_b32_e32 v0, 17, v66
	v_ashrrev_i32_e32 v1, 31, v0
	v_lshlrev_b64 v[0:1], 11, v[0:1]
	v_lshl_add_u64 v[0:1], v[64:65], 0, v[0:1]
	v_mul_f32_e32 v9, v9, v8
	global_store_dword v[0:1], v9, off
	v_mul_f32_e32 v9, v57, v8
	global_store_dword v[0:1], v9, off offset:128
	v_mul_f32_e32 v9, v41, v8
	v_mul_f32_e32 v8, v25, v8
	v_rcp_f32_e32 v2, v2
	global_store_dword v[0:1], v9, off offset:256
	global_store_dword v[0:1], v8, off offset:384
	v_or_b32_e32 v0, 18, v66
	v_ashrrev_i32_e32 v1, 31, v0
	v_lshlrev_b64 v[0:1], 11, v[0:1]
	v_lshl_add_u64 v[0:1], v[64:65], 0, v[0:1]
	v_mul_f32_e32 v8, v10, v2
	global_store_dword v[0:1], v8, off
	v_mul_f32_e32 v8, v58, v2
	global_store_dword v[0:1], v8, off offset:128
	v_mul_f32_e32 v8, v42, v2
	v_mul_f32_e32 v2, v26, v2
	global_store_dword v[0:1], v2, off offset:384
	v_rcp_f32_e32 v2, v3
	global_store_dword v[0:1], v8, off offset:256
	v_or_b32_e32 v0, 19, v66
	v_ashrrev_i32_e32 v1, 31, v0
	v_lshlrev_b64 v[0:1], 11, v[0:1]
	v_lshl_add_u64 v[0:1], v[64:65], 0, v[0:1]
	v_mul_f32_e32 v3, v11, v2
	global_store_dword v[0:1], v3, off
	v_mul_f32_e32 v3, v59, v2
	global_store_dword v[0:1], v3, off offset:128
	v_mul_f32_e32 v3, v43, v2
	v_mul_f32_e32 v2, v27, v2
	global_store_dword v[0:1], v2, off offset:384
	v_rcp_f32_e32 v2, v4
	global_store_dword v[0:1], v3, off offset:256
	v_or_b32_e32 v0, 24, v66
	v_ashrrev_i32_e32 v1, 31, v0
	v_lshlrev_b64 v[0:1], 11, v[0:1]
	v_lshl_add_u64 v[0:1], v[64:65], 0, v[0:1]
	v_mul_f32_e32 v3, v12, v2
	global_store_dword v[0:1], v3, off
	v_mul_f32_e32 v3, v60, v2
	global_store_dword v[0:1], v3, off offset:128
	v_mul_f32_e32 v3, v44, v2
	v_mul_f32_e32 v2, v28, v2
	global_store_dword v[0:1], v2, off offset:384
	v_rcp_f32_e32 v2, v5
	global_store_dword v[0:1], v3, off offset:256
	v_or_b32_e32 v0, 25, v66
	v_ashrrev_i32_e32 v1, 31, v0
	v_lshlrev_b64 v[0:1], 11, v[0:1]
	v_lshl_add_u64 v[0:1], v[64:65], 0, v[0:1]
	v_mul_f32_e32 v3, v13, v2
	global_store_dword v[0:1], v3, off
	v_mul_f32_e32 v3, v61, v2
	global_store_dword v[0:1], v3, off offset:128
	v_mul_f32_e32 v3, v45, v2
	v_mul_f32_e32 v2, v29, v2
	global_store_dword v[0:1], v2, off offset:384
	v_rcp_f32_e32 v2, v6
	global_store_dword v[0:1], v3, off offset:256
	v_or_b32_e32 v0, 26, v66
	v_ashrrev_i32_e32 v1, 31, v0
	v_lshlrev_b64 v[0:1], 11, v[0:1]
	v_lshl_add_u64 v[0:1], v[64:65], 0, v[0:1]
	v_mul_f32_e32 v3, v14, v2
	global_store_dword v[0:1], v3, off
	v_mul_f32_e32 v3, v62, v2
	global_store_dword v[0:1], v3, off offset:128
	v_mul_f32_e32 v3, v46, v2
	v_mul_f32_e32 v2, v30, v2
	global_store_dword v[0:1], v2, off offset:384
	v_rcp_f32_e32 v2, v7
	global_store_dword v[0:1], v3, off offset:256
	v_or_b32_e32 v0, 27, v66
	v_ashrrev_i32_e32 v1, 31, v0
	v_lshlrev_b64 v[0:1], 11, v[0:1]
	v_lshl_add_u64 v[0:1], v[64:65], 0, v[0:1]
	v_mul_f32_e32 v3, v15, v2
	global_store_dword v[0:1], v3, off
	v_mul_f32_e32 v3, v63, v2
	global_store_dword v[0:1], v3, off offset:128
	v_mul_f32_e32 v3, v47, v2
	v_mul_f32_e32 v2, v31, v2
	global_store_dword v[0:1], v3, off offset:256
	global_store_dword v[0:1], v2, off offset:384
	s_waitcnt vmcnt(0)
	s_barrier
; #define LAS __attribute__((address_space(3)))
; template <int DQK, int MODE, int LDQ, int LDK, int LDV> ...
;     ...
;     int tid_ = fresh_tid<100 + MODE>(wv); const int tid = tid_, wid = __builtin_amdgcn_readfirstlane(tid >> 6), lane = tid & 63, r32 = lane & 31, hi = lane >> 5;
;     LAS float* ws = (LAS float*)(lds + WS_OFF) + wid * 64; LAS float* li_l = ws;
;     const LAS float* bt = (const LAS float*)(lds + BT_OFF);
;     float l_reg = 0.f; f32x16 o[4];
; #pragma unroll
;     for (int d = 0; d < 4; ++d)
; #pragma unroll
;         for (int r = 0; r < 16; ++r) o[d][r] = 0.f;
;     int kgo[NKP], vgo[2];
; #pragma unroll
;     for (int i = 0; i < NKP; ++i) { const int L = (wid + 8 * i) * 64 + lane, row = L / CPR, slot = L % CPR, cc = (slot & ~7) | ((slot & 7) ^ ((row >> 1) & 7)); kgo[i] = row * LDK + cc * 8; }
; #pragma unroll
;     for (int i = 0; i < 2; ++i) { const int L = (2 * wid + i) * 64 + lane, st = L >> 5, w5 = L & 31, kk = (st >> 2) * 8 + (w5 >> 2), c = (st & 3) * 32 + (w5 & 3) * 8;
;         const int k = (kk & ~0xC) | ((kk & 4) << 1) | ((kk & 8) >> 1); vgo[i] = k * LDV + c; }
;     ...
;     ATT_DMA_K(0); ATT_DMA_K(1); ATT_DMA_V(0, 0); ATT_DMA_K(2); ATT_DMA_V(1, 1);
;     bf16x8 qr[ND0];
;     { const bf16_t* Qw = Qb + (size_t)(wid * 32 + r32) * LDQ + hi * 8;
; #pragma unroll
;       for (int d0 = 0; d0 < ND0; ++d0) qr[d0] = *(const bf16x8*)(Qw + d0 * 16);
;       if constexpr (MODE == 0) {
;           float ss = 0.f;
; #pragma unroll
;           for (int d0 = 0; d0 < ND0; ++d0)
; #pragma unroll
;               for (int j = 0; j < 8; ++j) { const float f = bf2f((unsigned short)qr[d0][j]); ss += f * f; }
;           ss = swap_sum(ss);
;           const float rstd = rsqrtf(ss * (1.f / DQK) + EPS) * C;
; #pragma unroll
;           for (int d0 = 0; d0 < ND0; ++d0) { const float* g = gq + d0 * 16 + hi * 8;
;               { float f[8]; _Pragma("unroll") for (int j = 0; j < 8; ++j) f[j] = bf2f((unsigned short)qr[d0][j]) * rstd * g[j];
;                 u32x4 w = {cvtpk(f[0], f[1]), cvtpk(f[2], f[3]), cvtpk(f[4], f[5]), cvtpk(f[6], f[7])}; qr[d0] = __builtin_bit_cast(bf16x8, w); asm volatile("" ::: "memory"); } }
;       } }
;     const int qlo = q0 + wid * 32, qpos = qlo + r32;
;     const int tL = MODE == 0 ? 0 : (qlo >= 191 ? (qlo - 127) >> 6 : 0), tR = MODE == 0 ? NT : min(NT, (qlo + 222) >> 6);
	v_mbcnt_lo_u32_b32 v7, -1, 0
	v_mbcnt_hi_u32_b32 v7, -1, v7
	s_mov_b64 s[4:5], 0x880
	v_add_u32_e32 v0, s33, v7
	v_bfe_u32 v4, v0, 2, 2
	v_readfirstlane_b32 s0, v0
	s_ashr_i32 s2, s0, 31
	s_ashr_i32 s1, s0, 6
	v_mov_b32_e32 v1, s0
	v_bfi_b32 v1, s63, v1, v7
	s_lshr_b32 s2, s2, 29
	v_add_u32_e32 v3, s2, v1
	s_lshl_b32 s2, s1, 7
	v_ashrrev_i32_e32 v9, 3, v3
	v_and_b32_e32 v3, 0x1ffffff8, v3
	s_ashr_i32 s3, s2, 4
	v_lshrrev_b32_e32 v0, 1, v0
	v_sub_u32_e32 v1, v1, v3
	v_lshrrev_b32_e32 v3, 1, v9
	v_lshlrev_b32_e32 v18, 3, v7
	s_and_b32 s2, s3, -16
	v_and_b32_e32 v6, 8, v0
	s_lshr_b32 s3, s3, 1
	v_bitop3_b32 v1, v3, v1, 7 bitop3:0x6c
	v_and_b32_e32 v3, 32, v7
	v_and_b32_e32 v5, 24, v18
	s_and_b32 s3, s3, 4
	v_or3_b32 v0, v6, v4, s2
	v_or_b32_e32 v10, v3, v5
	v_or_b32_e32 v0, s3, v0
	v_lshl_or_b32 v96, v0, 11, v10
	v_lshlrev_b32_e32 v0, 11, v9
	v_lshl_add_u32 v0, v1, 3, v0
	v_ashrrev_i32_e32 v1, 31, v0
	v_lshlrev_b64 v[10:11], 1, v[0:1]
	v_lshl_add_u64 v[12:13], s[46:47], 0, v[10:11]
	v_lshl_add_u64 v[12:13], v[12:13], 0, s[4:5]
	s_lshl_b32 s4, s1, 10
	s_add_i32 s94, s4, 0
	s_mov_b32 m0, s94
	v_lshl_add_u64 v[10:11], s[48:49], 0, v[10:11]
	s_mov_b64 s[4:5], 0x40080
	global_load_lds_dwordx4 v[12:13], off
	v_lshl_add_u64 v[12:13], v[10:11], 0, s[4:5]
	s_add_i32 m0, s94, 0x2000
	s_lshl_b32 s4, s1, 11
	v_ashrrev_i32_e32 v97, 31, v96
	global_load_lds_dwordx4 v[12:13], off
	s_add_i32 s6, s4, 0
	v_lshlrev_b64 v[12:13], 1, v[96:97]
	s_add_i32 s48, s6, 0x18000
	v_lshl_add_u64 v[14:15], s[46:47], 0, v[12:13]
	v_lshl_add_u64 v[16:17], v[14:15], 0, s[96:97]
	s_mov_b32 m0, s48
	s_mov_b64 s[4:5], 0xc80
	global_load_lds_dwordx4 v[16:17], off
	v_lshl_add_u64 v[14:15], v[14:15], 0, s[4:5]
	s_add_i32 m0, s6, 0x18400
	s_mov_b64 s[4:5], 0x80080
	v_or_b32_e32 v98, 64, v96
	global_load_lds_dwordx4 v[14:15], off
	v_lshl_add_u64 v[10:11], v[10:11], 0, s[4:5]
	s_add_i32 m0, s94, 0x4000
	v_ashrrev_i32_e32 v99, 31, v98
	global_load_lds_dwordx4 v[10:11], off
	s_add_i32 m0, s6, 0x1c000
	v_lshl_add_u64 v[10:11], s[52:53], 0, v[12:13]
	v_and_b32_e32 v2, 31, v7
	global_load_lds_dwordx4 v[10:11], off
	v_lshl_add_u64 v[10:11], v[98:99], 1, s[52:53]
	s_add_i32 m0, s6, 0x1c400
	s_lshl_b32 s46, s1, 5
	global_load_lds_dwordx4 v[10:11], off
	v_or_b32_e32 v10, s46, v2
	v_ashrrev_i32_e32 v11, 31, v10
	v_bfe_u32 v8, v7, 5, 1
	v_lshlrev_b64 v[10:11], 12, v[10:11]
	v_lshl_add_u64 v[10:11], s[44:45], 0, v[10:11]
	v_lshlrev_b32_e32 v130, 4, v8
	v_lshl_add_u64 v[10:11], v[10:11], 0, v[130:131]
	global_load_dwordx4 v[92:95], v[10:11], off offset:1152
	global_load_dwordx4 v[88:91], v[10:11], off offset:1184
	global_load_dwordx4 v[84:87], v[10:11], off offset:1216
	global_load_dwordx4 v[80:83], v[10:11], off offset:1248
	v_and_b32_e32 v11, 0x70, v18
	v_mov_b32_e32 v9, s88
	v_mov_b32_e32 v10, s81
	v_lshl_add_u32 v114, v2, 7, 0
	v_bitop3_b32 v115, v130, v18, s64 bitop3:0x78
	v_bitop3_b32 v117, v130, v11, 64 bitop3:0x36
	s_add_i32 s4, s46, s89
	ds_read_b32 v9, v9
	ds_read_b32 v10, v10
	s_waitcnt vmcnt(3)
	s_barrier
	v_add_u32_e32 v107, v114, v115
	v_bitop3_b32 v116, v130, v11, 32 bitop3:0x36
	v_add_u32_e32 v109, v114, v117
	v_bitop3_b32 v118, v130, v11, s65 bitop3:0x36
	s_add_i32 s5, s4, 0xffffff81
	v_add_u32_e32 v108, v114, v116
	ds_read_b128 v[12:15], v107
	ds_read_b128 v[16:19], v108
	v_add_u32_e32 v110, v114, v118
	ds_read_b128 v[20:23], v109
	ds_read_b128 v[24:27], v110
	s_ashr_i32 s5, s5, 6
	s_cmpk_gt_i32 s4, 0xbe
	v_or_b32_e32 v111, s4, v2
	s_cselect_b32 s47, s5, 0
	s_addk_i32 s4, 0xde
	s_ashr_i32 s45, s4, 6
	s_waitcnt lgkmcnt(0)
	s_waitcnt vmcnt(0) lgkmcnt(0)
	v_mfma_f32_32x32x16_bf16 v[64:79], v[12:15], v[92:95], 0
	s_cmp_gt_i32 s47, 0
	s_cselect_b64 s[4:5], -1, 0
	s_cmp_lt_i32 s45, 1
	s_cselect_b64 s[6:7], -1, 0
	s_or_b64 s[4:5], s[6:7], s[4:5]
	s_and_b64 vcc, exec, s[4:5]
	v_mfma_f32_32x32x16_bf16 v[64:79], v[16:19], v[88:91], v[64:79]
	v_mfma_f32_32x32x16_bf16 v[64:79], v[20:23], v[84:87], v[64:79]
	v_mfma_f32_32x32x16_bf16 v[64:79], v[24:27], v[80:83], v[64:79]
	s_cbranch_vccnz .LBB0_1948
	v_lshlrev_b32_e32 v8, 2, v8
	v_sub_u32_e32 v8, v8, v111
	v_lshl_add_u32 v8, v8, 2, s88
	ds_read2_b32 v[12:13], v8 offset0:240 offset1:241
	ds_read2_b32 v[14:15], v8 offset0:242 offset1:243
	ds_read2_b32 v[16:17], v8 offset0:248 offset1:249
	ds_read2_b32 v[18:19], v8 offset0:250 offset1:251
	ds_read2_b32 v[20:21], v8 offset0:224 offset1:225
	ds_read2_b32 v[22:23], v8 offset0:226 offset1:227
	ds_read2_b32 v[24:25], v8 offset0:232 offset1:233
	ds_read2_b32 v[26:27], v8 offset0:234 offset1:235
	s_waitcnt lgkmcnt(4)
	v_pk_add_f32 v[78:79], v[78:79], v[18:19]
	v_pk_add_f32 v[76:77], v[76:77], v[16:17]
	v_pk_add_f32 v[74:75], v[74:75], v[14:15]
	v_pk_add_f32 v[72:73], v[72:73], v[12:13]
	s_waitcnt lgkmcnt(0)
	v_pk_add_f32 v[70:71], v[70:71], v[26:27]
	v_pk_add_f32 v[68:69], v[68:69], v[24:25]
	v_pk_add_f32 v[66:67], v[66:67], v[22:23]
	v_pk_add_f32 v[64:65], v[64:65], v[20:21]

; #define SBAR() __builtin_amdgcn_sched_barrier(0)
; #define ATT_DMA_K(t) do { const bf16_t* kg_ = Kh + (size_t)(t) * 64 * LDK; LAS unsigned char* sb_ = lds + ((t) & 3) * KBUF; \
;     _Pragma("unroll") for (int i_ = 0; i_ < NKP; ++i_) __builtin_amdgcn_global_load_lds((const unsigned*)(kg_ + kgo[i_]), (LAS unsigned*)(sb_ + (wid + 8 * i_) * 1024), 16, 0, 0); } while (0)
; #define ATT_DMA_V(t, vs) do { const bf16_t* vg_ = Vh + (size_t)(t) * 64 * LDV; LAS unsigned char* sb_ = lds + V_OFF + (vs) * SHM_V; \
;     _Pragma("unroll") for (int i_ = 0; i_ < 2; ++i_) __builtin_amdgcn_global_load_lds((const unsigned*)(vg_ + vgo[i_]), (LAS unsigned*)(sb_ + (2 * wid + i_) * 1024), 16, 0, 0); } while (0)
; #define ATT_SEG(t) do { if constexpr (MODE != 0) { if (((t) == tL && tL > 0) || (t) == tR) { const float f_ = (t) == tR ? fR : fL; l_reg *= f_; \
;     _Pragma("unroll") for (int d = 0; d < 4; ++d) _Pragma("unroll") for (int r = 0; r < 16; ++r) o[d][r] *= f_; } } } while (0)
; #define ATT_TOP(N) do { asm volatile("s_waitcnt vmcnt(%0)" :: "n"(N) : "memory"); __builtin_amdgcn_s_barrier(); asm volatile("" ::: "memory"); } while (0)
; template <int DQK, int MODE, int LDQ, int LDK, int LDV> ...
;     ...
;     for (int j = 0; j < NT; ++j) {
;         if (j + 2 < NT) ATT_TOP(NKP + 2); else ATT_TOP(0);
;         if (j + 3 < NT) ATT_DMA_K(j + 3);
;         if (j + 2 < NT) ATT_DMA_V(j + 2, v2);
;         ATT_SEG(j); SBAR();
.Lstg_d1_top_18:
	s_setprio 1
	s_add_i32 s2, s48, s2
	global_load_lds_dwordx4 v[100:101], off
	s_add_i32 s3, s2, 0x400
	s_mov_b32 m0, s2
	s_add_i32 s2, s53, s0
	global_load_lds_dwordx4 v[102:103], off
	s_mov_b32 m0, s3
	s_add_i32 s23, s6, s0
	global_load_lds_dwordx4 v[104:105], off
	s_cmp_eq_u32 s2, 1
	s_cselect_b64 s[2:3], -1, 0
	s_and_b64 s[74:75], s[4:5], s[2:3]
	s_cmp_eq_u32 s23, 1
	s_cselect_b64 s[2:3], -1, 0
	s_or_b64 s[74:75], s[2:3], s[74:75]
	s_andn2_b64 vcc, exec, s[74:75]
	s_mov_b32 s23, s62
	s_cbranch_vccnz .LBB0_1953
	v_cndmask_b32_e64 v122, v112, v113, s[2:3]
	v_pk_mul_f32 v[14:15], v[14:15], v[122:123] op_sel_hi:[1,0]
	v_pk_mul_f32 v[12:13], v[12:13], v[122:123] op_sel_hi:[1,0]
	v_pk_mul_f32 v[10:11], v[10:11], v[122:123] op_sel_hi:[1,0]
	v_pk_mul_f32 v[8:9], v[8:9], v[122:123] op_sel_hi:[1,0]
	v_pk_mul_f32 v[6:7], v[6:7], v[122:123] op_sel_hi:[1,0]
	v_pk_mul_f32 v[4:5], v[4:5], v[122:123] op_sel_hi:[1,0]
	v_pk_mul_f32 v[2:3], v[2:3], v[122:123] op_sel_hi:[1,0]
	v_pk_mul_f32 v[0:1], v[0:1], v[122:123] op_sel_hi:[1,0]
	v_pk_mul_f32 v[62:63], v[62:63], v[122:123] op_sel_hi:[1,0]
	v_pk_mul_f32 v[60:61], v[60:61], v[122:123] op_sel_hi:[1,0]
	v_pk_mul_f32 v[58:59], v[58:59], v[122:123] op_sel_hi:[1,0]
	v_pk_mul_f32 v[56:57], v[56:57], v[122:123] op_sel_hi:[1,0]
	v_pk_mul_f32 v[54:55], v[54:55], v[122:123] op_sel_hi:[1,0]
	v_pk_mul_f32 v[52:53], v[52:53], v[122:123] op_sel_hi:[1,0]
	v_pk_mul_f32 v[50:51], v[50:51], v[122:123] op_sel_hi:[1,0]
	v_pk_mul_f32 v[48:49], v[48:49], v[122:123] op_sel_hi:[1,0]
	v_pk_mul_f32 v[30:31], v[30:31], v[122:123] op_sel_hi:[1,0]
	v_pk_mul_f32 v[28:29], v[28:29], v[122:123] op_sel_hi:[1,0]
	v_pk_mul_f32 v[26:27], v[26:27], v[122:123] op_sel_hi:[1,0]
	v_pk_mul_f32 v[24:25], v[24:25], v[122:123] op_sel_hi:[1,0]
	v_pk_mul_f32 v[22:23], v[22:23], v[122:123] op_sel_hi:[1,0]
	v_pk_mul_f32 v[20:21], v[20:21], v[122:123] op_sel_hi:[1,0]
	v_pk_mul_f32 v[18:19], v[18:19], v[122:123] op_sel_hi:[1,0]
	v_pk_mul_f32 v[16:17], v[16:17], v[122:123] op_sel_hi:[1,0]
	v_pk_mul_f32 v[46:47], v[46:47], v[122:123] op_sel_hi:[1,0]
	v_pk_mul_f32 v[44:45], v[44:45], v[122:123] op_sel_hi:[1,0]
	v_pk_mul_f32 v[42:43], v[42:43], v[122:123] op_sel_hi:[1,0]
	v_pk_mul_f32 v[40:41], v[40:41], v[122:123] op_sel_hi:[1,0]
	v_pk_mul_f32 v[38:39], v[38:39], v[122:123] op_sel_hi:[1,0]
	v_pk_mul_f32 v[36:37], v[36:37], v[122:123] op_sel_hi:[1,0]
	v_pk_mul_f32 v[34:35], v[34:35], v[122:123] op_sel_hi:[1,0]
	v_pk_mul_f32 v[32:33], v[32:33], v[122:123] op_sel_hi:[1,0]
	v_mul_f32_e32 v120, v120, v122
; DI void expsum(f32x16& p, float& l_reg, bf16x8& pa0, bf16x8& pa1) {
; #pragma unroll
;     for (int r = 0; r < 16; ++r) p[r] = __builtin_amdgcn_exp2f(p[r]);
;     float ps = 0.f;
; #pragma unroll
;     for (int r = 0; r < 16; ++r) ps += p[r];
;     l_reg += ps; asm volatile("" : "+v"(l_reg));
;     ...
;     ATT_PK4(p, 0, pa0); ATT_PK4(p, 8, pa1);
;     ...
; }
.LBB0_1953:
	s_add_i32 s3, s0, -1
	s_add_i32 s2, s22, 0xffffa000
	s_and_b32 s2, s2, 0x6000
	v_add_u32_e32 v121, s2, v114
	v_add_u32_e32 v122, v121, v115
	v_add_u32_e32 v126, v121, v116
	ds_read_b128 v[122:125], v122 offset:4096
	ds_read_b128 v[132:135], v126 offset:4096
	v_add_u32_e32 v126, v121, v117
	v_add_u32_e32 v121, v121, v118
	s_lshl_b32 s2, s23, 14
	ds_read_b128 v[136:139], v126 offset:4096
	ds_read_b128 v[140:143], v121 offset:4096
	v_add_u32_e32 v121, s2, v106
	ds_read_b64_tr_b16 v[144:145], v121 offset:0
	ds_read_b64_tr_b16 v[146:147], v121 offset:0x800
	ds_read_b64_tr_b16 v[148:149], v121 offset:0x1000
	ds_read_b64_tr_b16 v[150:151], v121 offset:0x1800
	ds_read_b64_tr_b16 v[152:153], v121 offset:0x200
	ds_read_b64_tr_b16 v[154:155], v121 offset:0xa00
	ds_read_b64_tr_b16 v[156:157], v121 offset:0x1200
	ds_read_b64_tr_b16 v[158:159], v121 offset:0x1a00
	ds_read_b64_tr_b16 v[162:163], v121 offset:0x400
	ds_read_b64_tr_b16 v[164:165], v121 offset:0xc00
	ds_read_b64_tr_b16 v[166:167], v121 offset:0x1400
	ds_read_b64_tr_b16 v[168:169], v121 offset:0x1c00
	ds_read_b64_tr_b16 v[170:171], v121 offset:0x600
	ds_read_b64_tr_b16 v[172:173], v121 offset:0xe00
	ds_read_b64_tr_b16 v[174:175], v121 offset:0x1600
	ds_read_b64_tr_b16 v[176:177], v121 offset:0x1e00
	v_exp_f32_e32 v64, v64
	v_exp_f32_e32 v65, v65
	v_exp_f32_e32 v66, v66
	v_exp_f32_e32 v67, v67
	v_exp_f32_e32 v68, v68
	v_add_f32_e32 v126, 0, v64
	v_exp_f32_e32 v69, v69
	v_add_f32_e32 v126, v65, v126
	v_exp_f32_e32 v70, v70
	v_add_f32_e32 v126, v66, v126
	v_exp_f32_e32 v71, v71
	v_add_f32_e32 v126, v67, v126
	v_exp_f32_e32 v72, v72
	v_add_f32_e32 v126, v68, v126
	v_exp_f32_e32 v73, v73
	v_add_f32_e32 v126, v69, v126
	v_exp_f32_e32 v74, v74
	v_add_f32_e32 v126, v70, v126
	v_exp_f32_e32 v75, v75
	v_add_f32_e32 v126, v71, v126
	v_exp_f32_e32 v76, v76
	v_add_f32_e32 v126, v72, v126
	v_exp_f32_e32 v77, v77
	v_add_f32_e32 v126, v73, v126
	v_exp_f32_e32 v78, v78
	v_add_f32_e32 v126, v74, v126
	v_exp_f32_e32 v79, v79
	v_add_f32_e32 v126, v75, v126
	v_add_f32_e32 v126, v76, v126
	v_add_f32_e32 v126, v77, v126
	v_add_f32_e32 v126, v78, v126
	v_add_f32_e32 v126, v79, v126
	v_add_f32_e32 v120, v126, v120
	v_cvt_pk_bf16_f32 v64, v64, v65
	v_cvt_pk_bf16_f32 v65, v66, v67
	v_cvt_pk_bf16_f32 v66, v68, v69
	v_cvt_pk_bf16_f32 v67, v70, v71
	v_cvt_pk_bf16_f32 v68, v72, v73
	v_cvt_pk_bf16_f32 v69, v74, v75
	v_cvt_pk_bf16_f32 v70, v76, v77
	v_cvt_pk_bf16_f32 v71, v78, v79
	s_nop 0
	v_permlane32_swap_b32_e32 v64, v66
	v_permlane32_swap_b32_e32 v65, v67
	v_permlane32_swap_b32_e32 v68, v70
	v_permlane32_swap_b32_e32 v69, v71
	s_waitcnt lgkmcnt(0)
	s_setprio 0
	v_mfma_f32_32x32x16_bf16 v[0:15], v[64:67], v[144:147], v[0:15]
	s_cmp_lt_i32 s3, s47
	s_cselect_b64 s[74:75], -1, 0
	s_cmp_ge_i32 s3, s52
	s_cselect_b64 s[90:91], -1, 0
	s_or_b64 s[74:75], s[74:75], s[90:91]
	s_and_b64 vcc, exec, s[74:75]
	v_mfma_f32_32x32x16_bf16 v[48:63], v[64:67], v[152:155], v[48:63]
	v_mfma_f32_32x32x16_bf16 v[16:31], v[64:67], v[162:165], v[16:31]
	v_mfma_f32_32x32x16_bf16 v[32:47], v[64:67], v[170:173], v[32:47]
	v_mfma_f32_32x32x16_bf16 v[0:15], v[68:71], v[148:151], v[0:15]
	v_mfma_f32_32x32x16_bf16 v[48:63], v[68:71], v[156:159], v[48:63]
	v_mfma_f32_32x32x16_bf16 v[16:31], v[68:71], v[166:169], v[16:31]
	v_mfma_f32_32x32x16_bf16 v[32:47], v[68:71], v[174:177], v[32:47]
	v_mfma_f32_32x32x16_bf16 v[64:79], v[122:125], v[92:95], 0
	v_mfma_f32_32x32x16_bf16 v[64:79], v[132:135], v[88:91], v[64:79]
	v_mfma_f32_32x32x16_bf16 v[64:79], v[136:139], v[84:87], v[64:79]
	v_mfma_f32_32x32x16_bf16 v[64:79], v[140:143], v[80:83], v[64:79]
	s_setprio 1
	v_add_u32_e32 v122, s7, v119
	s_cbranch_vccnz .LBB0_1955
	v_add_u32_e32 v138, 0x28908, v122
	v_add_u32_e32 v140, 0x28920, v122
	v_add_u32_e32 v142, 0x28928, v122
	v_add_u32_e32 v124, 0x28940, v122
	v_add_u32_e32 v126, 0x28948, v122
	v_add_u32_e32 v132, 0x28960, v122
	v_add_u32_e32 v134, 0x28968, v122
	v_add_u32_e32 v123, 0x28900, v122
	ds_read2_b32 v[124:125], v124 offset1:1
	ds_read2_b32 v[126:127], v126 offset1:1
	ds_read2_b32 v[132:133], v132 offset1:1
	ds_read2_b32 v[134:135], v134 offset1:1
	ds_read2_b32 v[136:137], v123 offset1:1
	ds_read2_b32 v[138:139], v138 offset1:1
	ds_read2_b32 v[140:141], v140 offset1:1
	ds_read2_b32 v[142:143], v142 offset1:1
	s_waitcnt lgkmcnt(0)
	v_pk_add_f32 v[78:79], v[78:79], v[134:135]
	v_pk_add_f32 v[76:77], v[76:77], v[132:133]
	v_pk_add_f32 v[74:75], v[74:75], v[126:127]
	v_pk_add_f32 v[72:73], v[72:73], v[124:125]
	v_pk_add_f32 v[70:71], v[70:71], v[142:143]
	v_pk_add_f32 v[68:69], v[68:69], v[140:141]
	v_pk_add_f32 v[66:67], v[66:67], v[138:139]
	v_pk_add_f32 v[64:65], v[64:65], v[136:137]

; #define SBAR() __builtin_amdgcn_sched_barrier(0)
; #define ATT_DMA_K(t) do { const bf16_t* kg_ = Kh + (size_t)(t) * 64 * LDK; LAS unsigned char* sb_ = lds + ((t) & 3) * KBUF; \
;     _Pragma("unroll") for (int i_ = 0; i_ < NKP; ++i_) __builtin_amdgcn_global_load_lds((const unsigned*)(kg_ + kgo[i_]), (LAS unsigned*)(sb_ + (wid + 8 * i_) * 1024), 16, 0, 0); } while (0)
; #define ATT_DMA_V(t, vs) do { const bf16_t* vg_ = Vh + (size_t)(t) * 64 * LDV; LAS unsigned char* sb_ = lds + V_OFF + (vs) * SHM_V; \
;     _Pragma("unroll") for (int i_ = 0; i_ < 2; ++i_) __builtin_amdgcn_global_load_lds((const unsigned*)(vg_ + vgo[i_]), (LAS unsigned*)(sb_ + (2 * wid + i_) * 1024), 16, 0, 0); } while (0)
; #define ATT_SEG(t) do { if constexpr (MODE != 0) { if (((t) == tL && tL > 0) || (t) == tR) { const float f_ = (t) == tR ? fR : fL; l_reg *= f_; \
;     _Pragma("unroll") for (int d = 0; d < 4; ++d) _Pragma("unroll") for (int r = 0; r < 16; ++r) o[d][r] *= f_; } } } while (0)
; #define ATT_TOP(N) do { asm volatile("s_waitcnt vmcnt(%0)" :: "n"(N) : "memory"); __builtin_amdgcn_s_barrier(); asm volatile("" ::: "memory"); } while (0)
; template <int DQK, int MODE, int LDQ, int LDK, int LDV> ...
;     ...
;         if (j + 2 < NT) ATT_TOP(NKP + 2); else ATT_TOP(0);
;         if (j + 3 < NT) ATT_DMA_K(j + 3);
;         if (j + 2 < NT) ATT_DMA_V(j + 2, v2);
;         ATT_SEG(j); SBAR();
.Lstg_d1_t61_20:
	s_setprio 1
	s_add_i32 s1, s0, 0x400
	v_lshl_add_u64 v[96:97], v[96:97], 1, s[56:57]
	s_mov_b32 m0, s0
	v_lshl_add_u64 v[98:99], v[98:99], 1, s[56:57]
	global_load_lds_dwordx4 v[96:97], off
	s_mov_b32 m0, s1
	s_cmp_lg_u32 s47, 61
	global_load_lds_dwordx4 v[98:99], off
	s_cselect_b64 s[0:1], -1, 0
	s_cmp_eq_u32 s45, 61
	s_cselect_b64 s[2:3], -1, 0
	s_cmp_lg_u32 s45, 61
	s_cselect_b64 s[4:5], -1, 0
	s_and_b64 s[0:1], s[4:5], s[0:1]
	s_and_b64 vcc, exec, s[0:1]
	s_cbranch_vccnz .LBB0_1961
	v_cndmask_b32_e64 v96, v112, v113, s[2:3]
	v_pk_mul_f32 v[14:15], v[14:15], v[96:97] op_sel_hi:[1,0]
	v_pk_mul_f32 v[12:13], v[12:13], v[96:97] op_sel_hi:[1,0]
	v_pk_mul_f32 v[10:11], v[10:11], v[96:97] op_sel_hi:[1,0]
	v_pk_mul_f32 v[8:9], v[8:9], v[96:97] op_sel_hi:[1,0]
	v_pk_mul_f32 v[6:7], v[6:7], v[96:97] op_sel_hi:[1,0]
	v_pk_mul_f32 v[4:5], v[4:5], v[96:97] op_sel_hi:[1,0]
	v_pk_mul_f32 v[2:3], v[2:3], v[96:97] op_sel_hi:[1,0]
	v_pk_mul_f32 v[0:1], v[0:1], v[96:97] op_sel_hi:[1,0]
	v_pk_mul_f32 v[62:63], v[62:63], v[96:97] op_sel_hi:[1,0]
	v_pk_mul_f32 v[60:61], v[60:61], v[96:97] op_sel_hi:[1,0]
	v_pk_mul_f32 v[58:59], v[58:59], v[96:97] op_sel_hi:[1,0]
	v_pk_mul_f32 v[56:57], v[56:57], v[96:97] op_sel_hi:[1,0]
	v_pk_mul_f32 v[54:55], v[54:55], v[96:97] op_sel_hi:[1,0]
	v_pk_mul_f32 v[52:53], v[52:53], v[96:97] op_sel_hi:[1,0]
	v_pk_mul_f32 v[50:51], v[50:51], v[96:97] op_sel_hi:[1,0]
	v_pk_mul_f32 v[48:49], v[48:49], v[96:97] op_sel_hi:[1,0]
	v_pk_mul_f32 v[30:31], v[30:31], v[96:97] op_sel_hi:[1,0]
	v_pk_mul_f32 v[28:29], v[28:29], v[96:97] op_sel_hi:[1,0]
	v_pk_mul_f32 v[26:27], v[26:27], v[96:97] op_sel_hi:[1,0]
	v_pk_mul_f32 v[24:25], v[24:25], v[96:97] op_sel_hi:[1,0]
	v_pk_mul_f32 v[22:23], v[22:23], v[96:97] op_sel_hi:[1,0]
	v_pk_mul_f32 v[20:21], v[20:21], v[96:97] op_sel_hi:[1,0]
	v_pk_mul_f32 v[18:19], v[18:19], v[96:97] op_sel_hi:[1,0]
	v_pk_mul_f32 v[16:17], v[16:17], v[96:97] op_sel_hi:[1,0]
	v_pk_mul_f32 v[46:47], v[46:47], v[96:97] op_sel_hi:[1,0]
	v_pk_mul_f32 v[44:45], v[44:45], v[96:97] op_sel_hi:[1,0]
	v_pk_mul_f32 v[42:43], v[42:43], v[96:97] op_sel_hi:[1,0]
	v_pk_mul_f32 v[40:41], v[40:41], v[96:97] op_sel_hi:[1,0]
	v_pk_mul_f32 v[38:39], v[38:39], v[96:97] op_sel_hi:[1,0]
	v_pk_mul_f32 v[36:37], v[36:37], v[96:97] op_sel_hi:[1,0]
	v_pk_mul_f32 v[34:35], v[34:35], v[96:97] op_sel_hi:[1,0]
	v_pk_mul_f32 v[32:33], v[32:33], v[96:97] op_sel_hi:[1,0]
	v_mul_f32_e32 v120, v120, v96
; #define SBAR() __builtin_amdgcn_sched_barrier(0)
; #define ATT_DMA_K(t) do { const bf16_t* kg_ = Kh + (size_t)(t) * 64 * LDK; LAS unsigned char* sb_ = lds + ((t) & 3) * KBUF; \
;     _Pragma("unroll") for (int i_ = 0; i_ < NKP; ++i_) __builtin_amdgcn_global_load_lds((const unsigned*)(kg_ + kgo[i_]), (LAS unsigned*)(sb_ + (wid + 8 * i_) * 1024), 16, 0, 0); } while (0)
; #define ATT_DMA_V(t, vs) do { const bf16_t* vg_ = Vh + (size_t)(t) * 64 * LDV; LAS unsigned char* sb_ = lds + V_OFF + (vs) * SHM_V; \
;     _Pragma("unroll") for (int i_ = 0; i_ < 2; ++i_) __builtin_amdgcn_global_load_lds((const unsigned*)(vg_ + vgo[i_]), (LAS unsigned*)(sb_ + (2 * wid + i_) * 1024), 16, 0, 0); } while (0)
; #define ATT_SEG(t) do { if constexpr (MODE != 0) { if (((t) == tL && tL > 0) || (t) == tR) { const float f_ = (t) == tR ? fR : fL; l_reg *= f_; \
;     _Pragma("unroll") for (int d = 0; d < 4; ++d) _Pragma("unroll") for (int r = 0; r < 16; ++r) o[d][r] *= f_; } } } while (0)
; #define ATT_TOP(N) do { asm volatile("s_waitcnt vmcnt(%0)" :: "n"(N) : "memory"); __builtin_amdgcn_s_barrier(); asm volatile("" ::: "memory"); } while (0)
; DI void expsum(f32x16& p, float& l_reg, bf16x8& pa0, bf16x8& pa1) {
; #pragma unroll
;     for (int r = 0; r < 16; ++r) p[r] = __builtin_amdgcn_exp2f(p[r]);
;     float ps = 0.f;
; #pragma unroll
;     for (int r = 0; r < 16; ++r) ps += p[r];
;     l_reg += ps; asm volatile("" : "+v"(l_reg));
;     ...
;     ATT_PK4(p, 0, pa0); ATT_PK4(p, 8, pa1);
;     ...
; }
; template <int DQK, int MODE, int LDQ, int LDK, int LDV> ...
;     ...
;     f32x16 pA, pB; bf16x8 pa0, pa1;
;     int v0 = 0, v1 = 1, v2 = 2;
;     ATT_TOP(NKP + 2);
;     { bf16x8 kf[NDA]; k_reads<DQK, 0, NDA>(kf, lds, 0, r32, hi); ATT_LGKM0(); qk_mma<0, NDA>(pA, kf, qr);
;       if constexpr (ND0 > NDA) { bf16x8 kg[ND0 - NDA]; k_reads<DQK, NDA, ND0>(kg, lds, 0, r32, hi); ATT_LGKM0(); qk_mma<NDA, ND0>(pA, kg, qr); }
;       ATT_BIAS(pA, 0, 0); }
;     if (wid >= 4) __builtin_amdgcn_s_setprio(1);
;     for (int j = 0; j < NT; ++j) {
;         if (j + 2 < NT) ATT_TOP(NKP + 2); else ATT_TOP(0);
;         if (j + 3 < NT) ATT_DMA_K(j + 3);
;         if (j + 2 < NT) ATT_DMA_V(j + 2, v2);
;         ATT_SEG(j); SBAR();
;         ATT_STEP(pA, pB, 0, v0, true, 1, j);
;         ATT_STEP(pB, pA, 1, v0, (j + 1 < NT), 0, j + 1);
.LBB0_1961:
	ds_read_b128 v[98:101], v107 offset:12288
	ds_read_b128 v[102:105], v108 offset:12288
	ds_read_b128 v[114:117], v109 offset:12288
	ds_read_b128 v[122:125], v110 offset:12288
	v_lshl_add_u32 v96, s49, 14, v106
	ds_read_b64_tr_b16 v[132:133], v96 offset:0
	ds_read_b64_tr_b16 v[134:135], v96 offset:0x800
	ds_read_b64_tr_b16 v[136:137], v96 offset:0x1000
	ds_read_b64_tr_b16 v[138:139], v96 offset:0x1800
	ds_read_b64_tr_b16 v[140:141], v96 offset:0x200
	ds_read_b64_tr_b16 v[142:143], v96 offset:0xa00
	ds_read_b64_tr_b16 v[144:145], v96 offset:0x1200
	ds_read_b64_tr_b16 v[146:147], v96 offset:0x1a00
	ds_read_b64_tr_b16 v[148:149], v96 offset:0x400
	ds_read_b64_tr_b16 v[150:151], v96 offset:0xc00
	ds_read_b64_tr_b16 v[152:153], v96 offset:0x1400
	ds_read_b64_tr_b16 v[154:155], v96 offset:0x1c00
	ds_read_b64_tr_b16 v[156:157], v96 offset:0x600
	ds_read_b64_tr_b16 v[158:159], v96 offset:0xe00
	ds_read_b64_tr_b16 v[162:163], v96 offset:0x1600
	ds_read_b64_tr_b16 v[164:165], v96 offset:0x1e00
	v_exp_f32_e32 v64, v64
	v_exp_f32_e32 v65, v65
	v_exp_f32_e32 v66, v66
	v_exp_f32_e32 v67, v67
	v_exp_f32_e32 v68, v68
	v_add_f32_e32 v97, 0, v64
	v_exp_f32_e32 v69, v69
	v_add_f32_e32 v97, v65, v97
	v_exp_f32_e32 v70, v70
	v_add_f32_e32 v97, v66, v97
	v_exp_f32_e32 v71, v71
	v_add_f32_e32 v97, v67, v97
	v_exp_f32_e32 v72, v72
	v_add_f32_e32 v97, v68, v97
	v_exp_f32_e32 v73, v73
	v_add_f32_e32 v97, v69, v97
	v_exp_f32_e32 v74, v74
	v_add_f32_e32 v97, v70, v97
	v_exp_f32_e32 v75, v75
	v_add_f32_e32 v97, v71, v97
	v_exp_f32_e32 v76, v76
	v_add_f32_e32 v97, v72, v97
	v_exp_f32_e32 v77, v77
	v_add_f32_e32 v97, v73, v97
	v_exp_f32_e32 v78, v78
	v_add_f32_e32 v97, v74, v97
	v_exp_f32_e32 v79, v79
	v_add_f32_e32 v97, v75, v97
	v_add_f32_e32 v97, v76, v97
	v_add_f32_e32 v97, v77, v97
	v_add_f32_e32 v97, v78, v97
	v_add_f32_e32 v97, v79, v97
	v_add_f32_e32 v97, v97, v120
	v_cvt_pk_bf16_f32 v64, v64, v65
	v_cvt_pk_bf16_f32 v65, v66, v67
	v_cvt_pk_bf16_f32 v66, v68, v69
	v_cvt_pk_bf16_f32 v67, v70, v71
	v_cvt_pk_bf16_f32 v68, v72, v73
	v_cvt_pk_bf16_f32 v69, v74, v75
	v_cvt_pk_bf16_f32 v70, v76, v77
	v_cvt_pk_bf16_f32 v71, v78, v79
	s_nop 0
	v_permlane32_swap_b32_e32 v64, v66
	v_permlane32_swap_b32_e32 v65, v67
	v_permlane32_swap_b32_e32 v68, v70
	v_permlane32_swap_b32_e32 v69, v71
	s_waitcnt lgkmcnt(0)
	s_setprio 0
	v_mfma_f32_32x32x16_bf16 v[0:15], v[64:67], v[132:135], v[0:15]
	s_cmp_gt_i32 s47, 61
	s_cselect_b64 s[0:1], -1, 0
	s_cmp_lt_i32 s45, 62
	s_cselect_b64 s[2:3], -1, 0
	s_or_b64 s[0:1], s[0:1], s[2:3]
	s_and_b64 vcc, exec, s[0:1]
	v_mfma_f32_32x32x16_bf16 v[48:63], v[64:67], v[140:143], v[48:63]
	v_mfma_f32_32x32x16_bf16 v[16:31], v[64:67], v[148:151], v[16:31]
	v_mfma_f32_32x32x16_bf16 v[32:47], v[64:67], v[156:159], v[32:47]
	v_mfma_f32_32x32x16_bf16 v[0:15], v[68:71], v[136:139], v[0:15]
	v_mfma_f32_32x32x16_bf16 v[48:63], v[68:71], v[144:147], v[48:63]
	v_mfma_f32_32x32x16_bf16 v[16:31], v[68:71], v[152:155], v[16:31]
	v_mfma_f32_32x32x16_bf16 v[32:47], v[68:71], v[162:165], v[32:47]
	s_waitcnt lgkmcnt(0)
	v_mfma_f32_32x32x16_bf16 v[64:79], v[98:101], v[92:95], 0
	v_mfma_f32_32x32x16_bf16 v[64:79], v[102:105], v[88:91], v[64:79]
	v_mfma_f32_32x32x16_bf16 v[64:79], v[114:117], v[84:87], v[64:79]
	v_mfma_f32_32x32x16_bf16 v[64:79], v[122:125], v[80:83], v[64:79]
	s_setprio 1
	s_cbranch_vccnz .LBB0_1963
	v_sub_u32_e32 v98, 0xf40, v111
	v_lshlrev_b32_e32 v98, 2, v98
	v_add3_u32 v98, s88, v98, v130
	v_add_u32_e32 v114, 0x400, v98
	v_add_u32_e32 v116, 0x408, v98
	v_add_u32_e32 v118, 0x420, v98
	v_add_u32_e32 v120, 0x428, v98
	v_add_u32_e32 v99, 0x440, v98
	v_add_u32_e32 v100, 0x448, v98
	v_add_u32_e32 v102, 0x460, v98
	v_add_u32_e32 v104, 0x468, v98
	ds_read2_b32 v[98:99], v99 offset1:1
	ds_read2_b32 v[100:101], v100 offset1:1
	ds_read2_b32 v[102:103], v102 offset1:1
	ds_read2_b32 v[104:105], v104 offset1:1
	ds_read2_b32 v[114:115], v114 offset1:1
	ds_read2_b32 v[116:117], v116 offset1:1
	ds_read2_b32 v[118:119], v118 offset1:1
	ds_read2_b32 v[120:121], v120 offset1:1
	s_waitcnt lgkmcnt(0)
	v_pk_add_f32 v[78:79], v[78:79], v[104:105]
	v_pk_add_f32 v[76:77], v[76:77], v[102:103]
	v_pk_add_f32 v[74:75], v[74:75], v[100:101]
	v_pk_add_f32 v[72:73], v[72:73], v[98:99]
	v_pk_add_f32 v[70:71], v[70:71], v[120:121]
	v_pk_add_f32 v[68:69], v[68:69], v[118:119]
	v_pk_add_f32 v[66:67], v[66:67], v[116:117]
	v_pk_add_f32 v[64:65], v[64:65], v[114:115]
.LBB0_1963:
	ds_read_b128 v[98:101], v107 offset:16384
	ds_read_b128 v[102:105], v108 offset:16384
	ds_read_b128 v[114:117], v109 offset:16384
	ds_read_b128 v[118:121], v110 offset:16384
	ds_read_b64_tr_b16 v[122:123], v96 offset:0x2000
	ds_read_b64_tr_b16 v[124:125], v96 offset:0x2800
	ds_read_b64_tr_b16 v[132:133], v96 offset:0x3000
	ds_read_b64_tr_b16 v[134:135], v96 offset:0x3800
	ds_read_b64_tr_b16 v[136:137], v96 offset:0x2200
	ds_read_b64_tr_b16 v[138:139], v96 offset:0x2a00
	ds_read_b64_tr_b16 v[140:141], v96 offset:0x3200
	ds_read_b64_tr_b16 v[142:143], v96 offset:0x3a00
	ds_read_b64_tr_b16 v[144:145], v96 offset:0x2400
	ds_read_b64_tr_b16 v[146:147], v96 offset:0x2c00
	ds_read_b64_tr_b16 v[148:149], v96 offset:0x3400
	ds_read_b64_tr_b16 v[150:151], v96 offset:0x3c00
	ds_read_b64_tr_b16 v[152:153], v96 offset:0x2600
	ds_read_b64_tr_b16 v[154:155], v96 offset:0x2e00
	ds_read_b64_tr_b16 v[156:157], v96 offset:0x3600
	ds_read_b64_tr_b16 v[158:159], v96 offset:0x3e00
	s_nop 6
	v_exp_f32_e32 v64, v64
	v_exp_f32_e32 v65, v65
	v_exp_f32_e32 v66, v66
	v_exp_f32_e32 v67, v67
	v_exp_f32_e32 v68, v68
	v_add_f32_e32 v96, 0, v64
	v_exp_f32_e32 v69, v69
	v_add_f32_e32 v96, v65, v96
	v_exp_f32_e32 v70, v70
	v_add_f32_e32 v96, v66, v96
	v_exp_f32_e32 v71, v71
	v_add_f32_e32 v96, v67, v96
	v_exp_f32_e32 v72, v72
	v_add_f32_e32 v96, v68, v96
	v_exp_f32_e32 v73, v73
	v_add_f32_e32 v96, v69, v96
	v_exp_f32_e32 v74, v74
	v_add_f32_e32 v96, v70, v96
	v_exp_f32_e32 v75, v75
	v_add_f32_e32 v96, v71, v96
	v_exp_f32_e32 v76, v76
	v_add_f32_e32 v96, v72, v96
	v_exp_f32_e32 v77, v77
	v_add_f32_e32 v96, v73, v96
	v_exp_f32_e32 v78, v78
	v_add_f32_e32 v96, v74, v96
	v_exp_f32_e32 v79, v79
	v_add_f32_e32 v96, v75, v96
	v_add_f32_e32 v96, v76, v96
	v_add_f32_e32 v96, v77, v96
	v_add_f32_e32 v96, v78, v96
	v_add_f32_e32 v96, v79, v96
	v_add_f32_e32 v96, v97, v96
	v_cvt_pk_bf16_f32 v64, v64, v65
	v_cvt_pk_bf16_f32 v65, v66, v67
	v_cvt_pk_bf16_f32 v66, v68, v69
	v_cvt_pk_bf16_f32 v67, v70, v71
	v_cvt_pk_bf16_f32 v68, v72, v73
	v_cvt_pk_bf16_f32 v69, v74, v75
	v_cvt_pk_bf16_f32 v70, v76, v77
	v_cvt_pk_bf16_f32 v71, v78, v79
	s_nop 0
	v_permlane32_swap_b32_e32 v64, v66
	v_permlane32_swap_b32_e32 v65, v67
	v_permlane32_swap_b32_e32 v68, v70
	v_permlane32_swap_b32_e32 v69, v71
	s_waitcnt lgkmcnt(0)
	s_setprio 0
	s_cmp_lt_u32 s33, 0x100
	s_cbranch_scc1 .Lstg_d1_m61_21
	s_waitcnt vmcnt(0)
	s_barrier

; DI int v_rd_base(int lane) { return ((lane & 3) << 3) | (((lane >> 2) & 3) << 6) | (((lane >> 4) & 1) << 5) | (((lane >> 5) & 1) << 8); }
; DI void expsum(f32x16& p, float& l_reg, bf16x8& pa0, bf16x8& pa1) {
; #pragma unroll
;     for (int r = 0; r < 16; ++r) p[r] = __builtin_amdgcn_exp2f(p[r]);
;     float ps = 0.f;
; #pragma unroll
;     for (int r = 0; r < 16; ++r) ps += p[r];
;     l_reg += ps; asm volatile("" : "+v"(l_reg));
;     ...
;     ATT_PK4(p, 0, pa0); ATT_PK4(p, 8, pa1);
;     ...
; }
; template <int DQK, int MODE, int LDQ, int LDK, int LDV> ...
;     ...
;     const int vbase = (int)(unsigned)(size_t)lds + V_OFF + v_rd_base(lane);
;     ...
;     constexpr int NDA = ND0 > 6 ? 6 : ND0;
.Lstg_d1_t62_22:
	s_setprio 1
	s_cmp_lg_u32 s45, 62
	s_cselect_b64 s[6:7], -1, 0
	s_and_b64 s[0:1], s[6:7], s[0:1]
	s_and_b64 vcc, exec, s[0:1]
	s_cbranch_vccnz .LBB0_1967
	v_cndmask_b32_e64 v98, v112, v113, s[4:5]
	v_pk_mul_f32 v[14:15], v[98:99], v[14:15] op_sel_hi:[0,1]
	v_pk_mul_f32 v[12:13], v[98:99], v[12:13] op_sel_hi:[0,1]
	v_pk_mul_f32 v[10:11], v[98:99], v[10:11] op_sel_hi:[0,1]
	v_pk_mul_f32 v[8:9], v[98:99], v[8:9] op_sel_hi:[0,1]
	v_pk_mul_f32 v[6:7], v[98:99], v[6:7] op_sel_hi:[0,1]
	v_pk_mul_f32 v[4:5], v[98:99], v[4:5] op_sel_hi:[0,1]
	v_pk_mul_f32 v[2:3], v[98:99], v[2:3] op_sel_hi:[0,1]
	v_pk_mul_f32 v[0:1], v[98:99], v[0:1] op_sel_hi:[0,1]
	v_pk_mul_f32 v[62:63], v[98:99], v[62:63] op_sel_hi:[0,1]
	v_pk_mul_f32 v[60:61], v[98:99], v[60:61] op_sel_hi:[0,1]
	v_pk_mul_f32 v[58:59], v[98:99], v[58:59] op_sel_hi:[0,1]
	v_pk_mul_f32 v[56:57], v[98:99], v[56:57] op_sel_hi:[0,1]
	v_pk_mul_f32 v[54:55], v[98:99], v[54:55] op_sel_hi:[0,1]
	v_pk_mul_f32 v[52:53], v[98:99], v[52:53] op_sel_hi:[0,1]
	v_pk_mul_f32 v[50:51], v[98:99], v[50:51] op_sel_hi:[0,1]
	v_pk_mul_f32 v[48:49], v[98:99], v[48:49] op_sel_hi:[0,1]
	v_pk_mul_f32 v[30:31], v[98:99], v[30:31] op_sel_hi:[0,1]
	v_pk_mul_f32 v[28:29], v[98:99], v[28:29] op_sel_hi:[0,1]
	v_pk_mul_f32 v[26:27], v[98:99], v[26:27] op_sel_hi:[0,1]
	v_pk_mul_f32 v[24:25], v[98:99], v[24:25] op_sel_hi:[0,1]
	v_pk_mul_f32 v[22:23], v[98:99], v[22:23] op_sel_hi:[0,1]
	v_pk_mul_f32 v[20:21], v[98:99], v[20:21] op_sel_hi:[0,1]
	v_pk_mul_f32 v[18:19], v[98:99], v[18:19] op_sel_hi:[0,1]
	v_pk_mul_f32 v[16:17], v[98:99], v[16:17] op_sel_hi:[0,1]
	v_pk_mul_f32 v[46:47], v[98:99], v[46:47] op_sel_hi:[0,1]
	v_pk_mul_f32 v[44:45], v[98:99], v[44:45] op_sel_hi:[0,1]
	v_pk_mul_f32 v[42:43], v[98:99], v[42:43] op_sel_hi:[0,1]
	v_pk_mul_f32 v[40:41], v[98:99], v[40:41] op_sel_hi:[0,1]
	v_pk_mul_f32 v[38:39], v[98:99], v[38:39] op_sel_hi:[0,1]
	v_pk_mul_f32 v[36:37], v[98:99], v[36:37] op_sel_hi:[0,1]
	v_pk_mul_f32 v[34:35], v[98:99], v[34:35] op_sel_hi:[0,1]
	v_pk_mul_f32 v[32:33], v[98:99], v[32:33] op_sel_hi:[0,1]
	v_mul_f32_e32 v96, v98, v96
.LBB0_1967:
	ds_read_b128 v[100:103], v107 offset:20480
	ds_read_b128 v[114:117], v108 offset:20480
	ds_read_b128 v[118:121], v109 offset:20480
	ds_read_b128 v[122:125], v110 offset:20480
	v_add_u32_e32 v98, 0x8000, v106
	ds_read_b64_tr_b16 v[132:133], v98 offset:0
	ds_read_b64_tr_b16 v[134:135], v98 offset:0x800
	ds_read_b64_tr_b16 v[136:137], v98 offset:0x1000
	ds_read_b64_tr_b16 v[138:139], v98 offset:0x1800
	ds_read_b64_tr_b16 v[140:141], v98 offset:0x200
	ds_read_b64_tr_b16 v[142:143], v98 offset:0xa00
	ds_read_b64_tr_b16 v[144:145], v98 offset:0x1200
	ds_read_b64_tr_b16 v[146:147], v98 offset:0x1a00
	ds_read_b64_tr_b16 v[148:149], v98 offset:0x400
	ds_read_b64_tr_b16 v[150:151], v98 offset:0xc00
	ds_read_b64_tr_b16 v[152:153], v98 offset:0x1400
	ds_read_b64_tr_b16 v[154:155], v98 offset:0x1c00
	ds_read_b64_tr_b16 v[156:157], v98 offset:0x600
	ds_read_b64_tr_b16 v[158:159], v98 offset:0xe00
	ds_read_b64_tr_b16 v[162:163], v98 offset:0x1600
	ds_read_b64_tr_b16 v[164:165], v98 offset:0x1e00
	v_exp_f32_e32 v64, v64
	v_exp_f32_e32 v65, v65
	v_exp_f32_e32 v66, v66
	v_exp_f32_e32 v67, v67
	v_exp_f32_e32 v68, v68
	v_add_f32_e32 v99, 0, v64
	v_exp_f32_e32 v69, v69
	v_add_f32_e32 v99, v65, v99
	v_exp_f32_e32 v70, v70
	v_add_f32_e32 v99, v66, v99
	v_exp_f32_e32 v71, v71
	v_add_f32_e32 v99, v67, v99
	v_exp_f32_e32 v72, v72
	v_add_f32_e32 v99, v68, v99
	v_exp_f32_e32 v73, v73
	v_add_f32_e32 v99, v69, v99
	v_exp_f32_e32 v74, v74
	v_add_f32_e32 v99, v70, v99
	v_exp_f32_e32 v75, v75
	v_add_f32_e32 v99, v71, v99
	v_exp_f32_e32 v76, v76
	v_add_f32_e32 v99, v72, v99
	v_exp_f32_e32 v77, v77
	v_add_f32_e32 v99, v73, v99
	v_exp_f32_e32 v78, v78
	v_add_f32_e32 v99, v74, v99
	v_exp_f32_e32 v79, v79
	v_add_f32_e32 v99, v75, v99
	v_add_f32_e32 v99, v76, v99
	v_add_f32_e32 v99, v77, v99
	v_add_f32_e32 v99, v78, v99
	v_add_f32_e32 v99, v79, v99
	v_add_f32_e32 v96, v99, v96
	v_cvt_pk_bf16_f32 v64, v64, v65
	v_cvt_pk_bf16_f32 v65, v66, v67
	v_cvt_pk_bf16_f32 v66, v68, v69
	v_cvt_pk_bf16_f32 v67, v70, v71
	v_cvt_pk_bf16_f32 v68, v72, v73
	v_cvt_pk_bf16_f32 v69, v74, v75
	v_cvt_pk_bf16_f32 v70, v76, v77
	v_cvt_pk_bf16_f32 v71, v78, v79
	s_nop 0
	v_permlane32_swap_b32_e32 v64, v66
	v_permlane32_swap_b32_e32 v65, v67
	v_permlane32_swap_b32_e32 v68, v70
	v_permlane32_swap_b32_e32 v69, v71
	s_waitcnt lgkmcnt(0)
	s_setprio 0
	v_mfma_f32_32x32x16_bf16 v[0:15], v[64:67], v[132:135], v[0:15]
	s_and_b64 vcc, exec, s[2:3]
	v_mfma_f32_32x32x16_bf16 v[48:63], v[64:67], v[140:143], v[48:63]
	v_mfma_f32_32x32x16_bf16 v[16:31], v[64:67], v[148:151], v[16:31]
	v_mfma_f32_32x32x16_bf16 v[32:47], v[64:67], v[156:159], v[32:47]
	v_mfma_f32_32x32x16_bf16 v[0:15], v[68:71], v[136:139], v[0:15]
	v_mfma_f32_32x32x16_bf16 v[48:63], v[68:71], v[144:147], v[48:63]
	v_mfma_f32_32x32x16_bf16 v[16:31], v[68:71], v[152:155], v[16:31]
	v_mfma_f32_32x32x16_bf16 v[32:47], v[68:71], v[162:165], v[32:47]
	s_waitcnt lgkmcnt(0)
	v_mfma_f32_32x32x16_bf16 v[64:79], v[100:103], v[92:95], 0
	v_mfma_f32_32x32x16_bf16 v[64:79], v[114:117], v[88:91], v[64:79]
	v_mfma_f32_32x32x16_bf16 v[64:79], v[118:121], v[84:87], v[64:79]
	v_mfma_f32_32x32x16_bf16 v[64:79], v[122:125], v[80:83], v[64:79]
	s_setprio 1
	s_cbranch_vccnz .LBB0_1969
	v_add3_u32 v97, s88, v97, v130
	v_add_u32_e32 v118, 0x408, v97
	v_add_u32_e32 v120, 0x420, v97
	v_add_u32_e32 v122, 0x428, v97
	v_add_u32_e32 v100, 0x440, v97
	v_add_u32_e32 v102, 0x448, v97
	v_add_u32_e32 v104, 0x460, v97
	v_add_u32_e32 v99, 0x400, v97
	v_add_u32_e32 v97, 0x468, v97
	ds_read2_b32 v[100:101], v100 offset1:1
	ds_read2_b32 v[102:103], v102 offset1:1
	ds_read2_b32 v[104:105], v104 offset1:1
	ds_read2_b32 v[114:115], v97 offset1:1
	ds_read2_b32 v[116:117], v99 offset1:1
	ds_read2_b32 v[118:119], v118 offset1:1
	ds_read2_b32 v[120:121], v120 offset1:1
	ds_read2_b32 v[122:123], v122 offset1:1
	s_waitcnt lgkmcnt(0)
	v_pk_add_f32 v[78:79], v[78:79], v[114:115]
	v_pk_add_f32 v[76:77], v[76:77], v[104:105]
	v_pk_add_f32 v[74:75], v[74:75], v[102:103]
	v_pk_add_f32 v[72:73], v[72:73], v[100:101]
	v_pk_add_f32 v[70:71], v[70:71], v[122:123]
	v_pk_add_f32 v[68:69], v[68:69], v[120:121]
	v_pk_add_f32 v[66:67], v[66:67], v[118:119]
	v_pk_add_f32 v[64:65], v[64:65], v[116:117]

; DI int v_rd_base(int lane) { return ((lane & 3) << 3) | (((lane >> 2) & 3) << 6) | (((lane >> 4) & 1) << 5) | (((lane >> 5) & 1) << 8); }
; DI void expsum(f32x16& p, float& l_reg, bf16x8& pa0, bf16x8& pa1) {
; #pragma unroll
;     for (int r = 0; r < 16; ++r) p[r] = __builtin_amdgcn_exp2f(p[r]);
;     float ps = 0.f;
; #pragma unroll
;     for (int r = 0; r < 16; ++r) ps += p[r];
;     l_reg += ps; asm volatile("" : "+v"(l_reg));
;     ...
;     ATT_PK4(p, 0, pa0); ATT_PK4(p, 8, pa1);
;     ...
; }
; template <int DQK, int MODE, int LDQ, int LDK, int LDV> ...
;     ...
;     const int vbase = (int)(unsigned)(size_t)lds + V_OFF + v_rd_base(lane);
;     ...
;     constexpr int NDA = ND0 > 6 ? 6 : ND0;
.Lstg_d1_t63_24:
	s_setprio 1
	s_cmp_lg_u32 s45, 63
	s_cselect_b64 s[6:7], -1, 0
	s_and_b64 s[0:1], s[6:7], s[0:1]
	s_and_b64 vcc, exec, s[0:1]
	s_cbranch_vccnz .LBB0_1973
	v_cndmask_b32_e64 v98, v112, v113, s[4:5]
	v_pk_mul_f32 v[14:15], v[98:99], v[14:15] op_sel_hi:[0,1]
	v_pk_mul_f32 v[12:13], v[98:99], v[12:13] op_sel_hi:[0,1]
	v_pk_mul_f32 v[10:11], v[98:99], v[10:11] op_sel_hi:[0,1]
	v_pk_mul_f32 v[8:9], v[98:99], v[8:9] op_sel_hi:[0,1]
	v_pk_mul_f32 v[6:7], v[98:99], v[6:7] op_sel_hi:[0,1]
	v_pk_mul_f32 v[4:5], v[98:99], v[4:5] op_sel_hi:[0,1]
	v_pk_mul_f32 v[2:3], v[98:99], v[2:3] op_sel_hi:[0,1]
	v_pk_mul_f32 v[0:1], v[98:99], v[0:1] op_sel_hi:[0,1]
	v_pk_mul_f32 v[62:63], v[98:99], v[62:63] op_sel_hi:[0,1]
	v_pk_mul_f32 v[60:61], v[98:99], v[60:61] op_sel_hi:[0,1]
	v_pk_mul_f32 v[58:59], v[98:99], v[58:59] op_sel_hi:[0,1]
	v_pk_mul_f32 v[56:57], v[98:99], v[56:57] op_sel_hi:[0,1]
	v_pk_mul_f32 v[54:55], v[98:99], v[54:55] op_sel_hi:[0,1]
	v_pk_mul_f32 v[52:53], v[98:99], v[52:53] op_sel_hi:[0,1]
	v_pk_mul_f32 v[50:51], v[98:99], v[50:51] op_sel_hi:[0,1]
	v_pk_mul_f32 v[48:49], v[98:99], v[48:49] op_sel_hi:[0,1]
	v_pk_mul_f32 v[30:31], v[98:99], v[30:31] op_sel_hi:[0,1]
	v_pk_mul_f32 v[28:29], v[98:99], v[28:29] op_sel_hi:[0,1]
	v_pk_mul_f32 v[26:27], v[98:99], v[26:27] op_sel_hi:[0,1]
	v_pk_mul_f32 v[24:25], v[98:99], v[24:25] op_sel_hi:[0,1]
	v_pk_mul_f32 v[22:23], v[98:99], v[22:23] op_sel_hi:[0,1]
	v_pk_mul_f32 v[20:21], v[98:99], v[20:21] op_sel_hi:[0,1]
	v_pk_mul_f32 v[18:19], v[98:99], v[18:19] op_sel_hi:[0,1]
	v_pk_mul_f32 v[16:17], v[98:99], v[16:17] op_sel_hi:[0,1]
	v_pk_mul_f32 v[46:47], v[98:99], v[46:47] op_sel_hi:[0,1]
	v_pk_mul_f32 v[44:45], v[98:99], v[44:45] op_sel_hi:[0,1]
	v_pk_mul_f32 v[42:43], v[98:99], v[42:43] op_sel_hi:[0,1]
	v_pk_mul_f32 v[40:41], v[98:99], v[40:41] op_sel_hi:[0,1]
	v_pk_mul_f32 v[38:39], v[98:99], v[38:39] op_sel_hi:[0,1]
	v_pk_mul_f32 v[36:37], v[98:99], v[36:37] op_sel_hi:[0,1]
	v_pk_mul_f32 v[34:35], v[98:99], v[34:35] op_sel_hi:[0,1]
	v_pk_mul_f32 v[32:33], v[98:99], v[32:33] op_sel_hi:[0,1]
	v_mul_f32_e32 v96, v98, v96
.LBB0_1973:
	ds_read_b128 v[98:101], v107 offset:28672
	ds_read_b128 v[102:105], v108 offset:28672
	ds_read_b128 v[112:115], v109 offset:28672
	ds_read_b128 v[108:111], v110 offset:28672
	ds_read_b64_tr_b16 v[116:117], v106 offset:0
	ds_read_b64_tr_b16 v[118:119], v106 offset:0x800
	ds_read_b64_tr_b16 v[120:121], v106 offset:0x1000
	ds_read_b64_tr_b16 v[122:123], v106 offset:0x1800
	ds_read_b64_tr_b16 v[124:125], v106 offset:0x200
	ds_read_b64_tr_b16 v[126:127], v106 offset:0xa00
	ds_read_b64_tr_b16 v[132:133], v106 offset:0x1200
	ds_read_b64_tr_b16 v[134:135], v106 offset:0x1a00
	ds_read_b64_tr_b16 v[136:137], v106 offset:0x400
	ds_read_b64_tr_b16 v[138:139], v106 offset:0xc00
	ds_read_b64_tr_b16 v[140:141], v106 offset:0x1400
	ds_read_b64_tr_b16 v[142:143], v106 offset:0x1c00
	ds_read_b64_tr_b16 v[144:145], v106 offset:0x600
	ds_read_b64_tr_b16 v[146:147], v106 offset:0xe00
	ds_read_b64_tr_b16 v[148:149], v106 offset:0x1600
	ds_read_b64_tr_b16 v[150:151], v106 offset:0x1e00
	v_exp_f32_e32 v64, v64
	v_exp_f32_e32 v65, v65
	v_exp_f32_e32 v66, v66
	v_exp_f32_e32 v67, v67
	v_exp_f32_e32 v68, v68
	v_add_f32_e32 v107, 0, v64
	v_exp_f32_e32 v69, v69
	v_add_f32_e32 v107, v65, v107
	v_exp_f32_e32 v70, v70
	v_add_f32_e32 v107, v66, v107
	v_exp_f32_e32 v71, v71
	v_add_f32_e32 v107, v67, v107
	v_exp_f32_e32 v72, v72
	v_add_f32_e32 v107, v68, v107
	v_exp_f32_e32 v73, v73
	v_add_f32_e32 v107, v69, v107
	v_exp_f32_e32 v74, v74
	v_add_f32_e32 v107, v70, v107
	v_exp_f32_e32 v75, v75
	v_add_f32_e32 v107, v71, v107
	v_exp_f32_e32 v76, v76
	v_add_f32_e32 v107, v72, v107
	v_exp_f32_e32 v77, v77
	v_add_f32_e32 v107, v73, v107
	v_exp_f32_e32 v78, v78
	v_add_f32_e32 v107, v74, v107
	v_exp_f32_e32 v79, v79
	v_add_f32_e32 v107, v75, v107
	v_add_f32_e32 v107, v76, v107
	v_add_f32_e32 v107, v77, v107
	v_add_f32_e32 v107, v78, v107
	v_add_f32_e32 v107, v79, v107
	v_add_f32_e32 v96, v107, v96
	v_cvt_pk_bf16_f32 v64, v64, v65
	v_cvt_pk_bf16_f32 v65, v66, v67
	v_cvt_pk_bf16_f32 v66, v68, v69
	v_cvt_pk_bf16_f32 v67, v70, v71
	v_cvt_pk_bf16_f32 v68, v72, v73
	v_cvt_pk_bf16_f32 v69, v74, v75
	v_cvt_pk_bf16_f32 v70, v76, v77
	v_cvt_pk_bf16_f32 v71, v78, v79
	s_nop 0
	v_permlane32_swap_b32_e32 v64, v66
	v_permlane32_swap_b32_e32 v65, v67
	v_permlane32_swap_b32_e32 v68, v70
	v_permlane32_swap_b32_e32 v69, v71
	s_waitcnt lgkmcnt(0)
	s_setprio 0
	v_mfma_f32_32x32x16_bf16 v[0:15], v[64:67], v[116:119], v[0:15]
	s_and_b64 vcc, exec, s[2:3]
	v_mfma_f32_32x32x16_bf16 v[48:63], v[64:67], v[124:127], v[48:63]
	v_mfma_f32_32x32x16_bf16 v[16:31], v[64:67], v[136:139], v[16:31]
	v_mfma_f32_32x32x16_bf16 v[32:47], v[64:67], v[144:147], v[32:47]
	v_mfma_f32_32x32x16_bf16 v[0:15], v[68:71], v[120:123], v[0:15]
	v_mfma_f32_32x32x16_bf16 v[48:63], v[68:71], v[132:135], v[48:63]
	v_mfma_f32_32x32x16_bf16 v[16:31], v[68:71], v[140:143], v[16:31]
	v_mfma_f32_32x32x16_bf16 v[32:47], v[68:71], v[148:151], v[32:47]
	s_waitcnt lgkmcnt(0)
	v_mfma_f32_32x32x16_bf16 v[64:79], v[98:101], v[92:95], 0
	v_mfma_f32_32x32x16_bf16 v[64:79], v[102:105], v[88:91], v[64:79]
	v_mfma_f32_32x32x16_bf16 v[64:79], v[112:115], v[84:87], v[64:79]
	v_mfma_f32_32x32x16_bf16 v[64:79], v[108:111], v[80:83], v[64:79]
	s_setprio 1
	s_cbranch_vccnz .LBB0_1975
	v_add3_u32 v80, s88, v97, v130
	v_add_u32_e32 v88, 0x400, v80
	v_add_u32_e32 v90, 0x408, v80
	v_add_u32_e32 v92, 0x420, v80
	v_add_u32_e32 v94, 0x428, v80
	v_add_u32_e32 v81, 0x440, v80
	v_add_u32_e32 v82, 0x448, v80
	v_add_u32_e32 v84, 0x460, v80
	v_add_u32_e32 v86, 0x468, v80
	ds_read2_b32 v[80:81], v81 offset1:1
	ds_read2_b32 v[82:83], v82 offset1:1
	ds_read2_b32 v[84:85], v84 offset1:1
	ds_read2_b32 v[86:87], v86 offset1:1
	ds_read2_b32 v[88:89], v88 offset1:1
	ds_read2_b32 v[90:91], v90 offset1:1
	ds_read2_b32 v[92:93], v92 offset1:1
	ds_read2_b32 v[94:95], v94 offset1:1
	s_waitcnt lgkmcnt(0)
	v_pk_add_f32 v[78:79], v[78:79], v[86:87]
	v_pk_add_f32 v[76:77], v[76:77], v[84:85]
	v_pk_add_f32 v[74:75], v[74:75], v[82:83]
	v_pk_add_f32 v[72:73], v[72:73], v[80:81]
	v_pk_add_f32 v[70:71], v[70:71], v[94:95]
	v_pk_add_f32 v[68:69], v[68:69], v[92:93]
	v_pk_add_f32 v[66:67], v[66:67], v[90:91]
	v_pk_add_f32 v[64:65], v[64:65], v[88:89]
; template <int TAG = 0> DI int fresh_tid(int wv) { int l; asm volatile("v_mbcnt_lo_u32_b32 %0, -1, 0\n\tv_mbcnt_hi_u32_b32 %0, -1, %0 ; site %1" : "=v"(l) : "n"(TAG)); return wv * 64 + l; }
; DI int crow(int r, int hi) { return (r & 3) + 8 * (r >> 2) + 4 * hi; }
; DI float swap_sum(float v) { auto rr = __builtin_amdgcn_permlane32_swap(__float_as_uint(v), __float_as_uint(v), false, false); return __uint_as_float(rr[0]) + __uint_as_float(rr[1]); }
; template <int DQK, int MODE, int LDQ, int LDK, int LDV> ...
;     ...
;     __builtin_amdgcn_s_setprio(0);
;     ...
;     l_reg = swap_sum(l_reg);
;     { const int lane2 = fresh_tid<110 + MODE>(wv) & 63, r32 = lane2 & 31, hi = lane2 >> 5;
;     if (hi == 0) li_l[r32] = l_reg;
;     asm volatile("s_waitcnt lgkmcnt(0)" ::: "memory");
;     float s0v[MODE == 2 ? 16 : 1][4];
;     if constexpr (MODE == 2) {
; #pragma unroll
;         for (int r = 0; r < 16; ++r)
; #pragma unroll
;             for (int d0 = 0; d0 < 4; ++d0) s0v[r][d0] = S0[(size_t)(wid * 32 + crow(r, hi)) * 512 + d0 * 32 + r32];
;     }
; #pragma unroll
;     for (int r = 0; r < 16; ++r) { const int orow = wid * 32 + crow(r, hi); const float rl = __builtin_amdgcn_rcpf(li_l[crow(r, hi)]);
.LBB0_1975:
	s_lshl_b32 s0, s44, 2
	s_add_i32 s0, s0, 0
	s_add_i32 s0, s0, 0x24000
	ds_read_b64_tr_b16 v[80:81], v106 offset:0x2000
	ds_read_b64_tr_b16 v[82:83], v106 offset:0x2800
	ds_read_b64_tr_b16 v[84:85], v106 offset:0x3000
	ds_read_b64_tr_b16 v[86:87], v106 offset:0x3800
	ds_read_b64_tr_b16 v[88:89], v106 offset:0x2200
	ds_read_b64_tr_b16 v[90:91], v106 offset:0x2a00
	ds_read_b64_tr_b16 v[92:93], v106 offset:0x3200
	ds_read_b64_tr_b16 v[94:95], v106 offset:0x3a00
	ds_read_b64_tr_b16 v[98:99], v106 offset:0x2400
	ds_read_b64_tr_b16 v[100:101], v106 offset:0x2c00
	ds_read_b64_tr_b16 v[102:103], v106 offset:0x3400
	ds_read_b64_tr_b16 v[104:105], v106 offset:0x3c00
	ds_read_b64_tr_b16 v[108:109], v106 offset:0x2600
	ds_read_b64_tr_b16 v[110:111], v106 offset:0x2e00
	ds_read_b64_tr_b16 v[112:113], v106 offset:0x3600
	ds_read_b64_tr_b16 v[114:115], v106 offset:0x3e00
	s_nop 7
	v_exp_f32_e32 v97, v64
	v_exp_f32_e32 v65, v65
	v_exp_f32_e32 v106, v66
	v_exp_f32_e32 v67, v67
	v_exp_f32_e32 v68, v68
	v_add_f32_e32 v64, 0, v97
	v_exp_f32_e32 v69, v69
	v_add_f32_e32 v64, v65, v64
	v_exp_f32_e32 v70, v70
	v_add_f32_e32 v64, v106, v64
	v_exp_f32_e32 v71, v71
	v_add_f32_e32 v64, v67, v64
	v_exp_f32_e32 v72, v72
	v_add_f32_e32 v64, v68, v64
	v_exp_f32_e32 v73, v73
	v_add_f32_e32 v64, v69, v64
	v_exp_f32_e32 v74, v74
	v_add_f32_e32 v64, v70, v64
	v_exp_f32_e32 v75, v75
	v_add_f32_e32 v64, v71, v64
	v_exp_f32_e32 v76, v76
	v_add_f32_e32 v64, v72, v64
	v_exp_f32_e32 v77, v77
	v_add_f32_e32 v64, v73, v64
	v_exp_f32_e32 v78, v78
	v_add_f32_e32 v64, v74, v64
	v_exp_f32_e32 v79, v79
	v_add_f32_e32 v64, v75, v64
	v_add_f32_e32 v64, v76, v64
	v_add_f32_e32 v64, v77, v64
	v_add_f32_e32 v64, v78, v64
	v_add_f32_e32 v64, v79, v64
	v_add_f32_e32 v64, v96, v64
	v_cvt_pk_bf16_f32 v66, v97, v65
	v_cvt_pk_bf16_f32 v67, v106, v67
	v_cvt_pk_bf16_f32 v68, v68, v69
	v_cvt_pk_bf16_f32 v69, v70, v71
	v_cvt_pk_bf16_f32 v70, v72, v73
	v_cvt_pk_bf16_f32 v71, v74, v75
	v_cvt_pk_bf16_f32 v72, v76, v77
	v_cvt_pk_bf16_f32 v73, v78, v79
	s_nop 0
	v_permlane32_swap_b32_e32 v66, v68
	v_permlane32_swap_b32_e32 v67, v69
	v_permlane32_swap_b32_e32 v70, v72
	v_permlane32_swap_b32_e32 v71, v73
	s_waitcnt lgkmcnt(0)
	s_setprio 0
	v_mfma_f32_32x32x16_bf16 v[0:15], v[66:69], v[80:83], v[0:15]
	v_mfma_f32_32x32x16_bf16 v[48:63], v[66:69], v[88:91], v[48:63]
	v_mfma_f32_32x32x16_bf16 v[16:31], v[66:69], v[98:101], v[16:31]
	v_mfma_f32_32x32x16_bf16 v[32:47], v[66:69], v[108:111], v[32:47]
	v_mfma_f32_32x32x16_bf16 v[0:15], v[70:73], v[84:87], v[0:15]
	v_mfma_f32_32x32x16_bf16 v[48:63], v[70:73], v[92:95], v[48:63]
	v_mfma_f32_32x32x16_bf16 v[16:31], v[70:73], v[102:105], v[16:31]
	v_mfma_f32_32x32x16_bf16 v[32:47], v[70:73], v[112:115], v[32:47]
	s_setprio 0
	v_mov_b32_e32 v66, v64
	v_mbcnt_lo_u32_b32 v65, -1, 0
	v_mbcnt_hi_u32_b32 v65, -1, v65
	s_nop 1
	v_permlane32_swap_b32_e32 v64, v66
	v_and_b32_e32 v114, 63, v65
	v_and_b32_e32 v170, 31, v65
	v_cmp_gt_u32_e32 vcc, 32, v114
	s_and_saveexec_b64 s[2:3], vcc
	v_lshl_add_u32 v67, v170, 2, s0
	v_add_f32_e32 v64, v64, v66
	ds_write_b32 v67, v64
	s_or_b64 exec, exec, s[2:3]
	v_lshrrev_b32_e32 v64, 3, v65
	v_and_b32_e32 v69, 4, v64
	v_or_b32_e32 v102, s46, v69
	v_lshlrev_b32_e32 v130, 2, v170
	v_ashrrev_i32_e32 v103, 31, v102
	v_or_b32_e32 v66, 1, v102
	v_lshl_add_u64 v[92:93], s[54:55], 0, v[130:131]
	v_lshlrev_b64 v[156:157], 11, v[102:103]
	v_ashrrev_i32_e32 v67, 31, v66
	s_waitcnt lgkmcnt(0)
	v_lshl_add_u64 v[64:65], v[92:93], 0, v[156:157]
	v_lshlrev_b64 v[148:149], 11, v[66:67]
	v_lshl_add_u64 v[66:67], v[92:93], 0, v[148:149]
	global_load_dword v110, v[64:65], off
	global_load_dword v111, v[64:65], off offset:128
	global_load_dword v109, v[64:65], off offset:256
	global_load_dword v108, v[64:65], off offset:384
	global_load_dword v106, v[66:67], off
	global_load_dword v107, v[66:67], off offset:128
	global_load_dword v105, v[66:67], off offset:256
	global_load_dword v104, v[66:67], off offset:384
	v_or_b32_e32 v64, 2, v102
	v_or_b32_e32 v66, 3, v102
	v_ashrrev_i32_e32 v65, 31, v64
	v_ashrrev_i32_e32 v67, 31, v66
	v_lshlrev_b64 v[146:147], 11, v[64:65]
	v_lshlrev_b64 v[136:137], 11, v[66:67]
	v_lshl_add_u64 v[64:65], v[92:93], 0, v[146:147]
	v_lshl_add_u64 v[66:67], v[92:93], 0, v[136:137]
	global_load_dword v158, v[64:65], off
	global_load_dword v159, v[64:65], off offset:128
	global_load_dword v155, v[64:65], off offset:256
	global_load_dword v154, v[64:65], off offset:384
	global_load_dword v152, v[66:67], off
	global_load_dword v153, v[66:67], off offset:128
	global_load_dword v151, v[66:67], off offset:256
	global_load_dword v150, v[66:67], off offset:384
	v_or_b32_e32 v64, 8, v102
	v_or_b32_e32 v66, 9, v102
	v_ashrrev_i32_e32 v65, 31, v64
	v_ashrrev_i32_e32 v67, 31, v66
	v_lshlrev_b64 v[134:135], 11, v[64:65]
	v_lshlrev_b64 v[120:121], 11, v[66:67]
	v_lshl_add_u64 v[64:65], v[92:93], 0, v[134:135]
	v_lshl_add_u64 v[66:67], v[92:93], 0, v[120:121]
	global_load_dword v144, v[64:65], off
	global_load_dword v145, v[64:65], off offset:128
	global_load_dword v143, v[64:65], off offset:256
	global_load_dword v142, v[64:65], off offset:384
	global_load_dword v140, v[66:67], off
	global_load_dword v141, v[66:67], off offset:128
	global_load_dword v139, v[66:67], off offset:256
	global_load_dword v138, v[66:67], off offset:384
	v_or_b32_e32 v64, 10, v102
	v_or_b32_e32 v66, 11, v102
	v_ashrrev_i32_e32 v65, 31, v64
	v_ashrrev_i32_e32 v67, 31, v66
	v_lshlrev_b64 v[118:119], 11, v[64:65]
	v_lshlrev_b64 v[90:91], 11, v[66:67]
	v_lshl_add_u64 v[64:65], v[92:93], 0, v[118:119]
	v_lshl_add_u64 v[66:67], v[92:93], 0, v[90:91]
	global_load_dword v132, v[64:65], off
; DI unsigned short f2bf(float x) { unsigned u = __float_as_uint(x); u += 0x7fffu + ((u >> 16) & 1u); return (unsigned short)(u >> 16); }
; DI float shx(float v, int mask, int lane) { return __int_as_float(__builtin_amdgcn_ds_bpermute((lane ^ mask) << 2, __float_as_int(v))); }
; DI int crow(int r, int hi) { return (r & 3) + 8 * (r >> 2) + 4 * hi; }
; template <int DQK, int MODE, int LDQ, int LDK, int LDV> ...
;     ...
;     for (int r = 0; r < 16; ++r) { const int orow = wid * 32 + crow(r, hi); const float rl = __builtin_amdgcn_rcpf(li_l[crow(r, hi)]);
;         if constexpr (MODE == 0) {
; #pragma unroll
;             for (int d0 = 0; d0 < 4; ++d0) AOb[(size_t)orow * 1024 + d0 * 32 + r32] = f2bf(o[d0][r] * rl);
;         } else if constexpr (MODE == 1) {
; #pragma unroll
;             for (int d0 = 0; d0 < 4; ++d0) S0[(size_t)orow * 512 + d0 * 32 + r32] = o[d0][r] * rl;
;         } else {
;             float v[4]; float ss = 0.f;
; #pragma unroll
;             for (int d0 = 0; d0 < 4; ++d0) { v[d0] = s0v[r][d0] - lam * (o[d0][r] * rl); ss += v[d0] * v[d0]; }
; #pragma unroll
;             for (int mk = 1; mk <= 16; mk <<= 1) ss += shx(ss, mk, lane2);
;             const float rs = rsqrtf(ss * (1.f / 128.f) + EPS) * 0.8f;
; #pragma unroll
;             for (int d0 = 0; d0 < 4; ++d0) AOb[(size_t)orow * 1024 + d0 * 32 + r32] = f2bf(v[d0] * rs * gout[d0 * 32 + r32]);
;         } }
	global_load_dword v133, v[64:65], off offset:128
	global_load_dword v127, v[64:65], off offset:256
	global_load_dword v126, v[64:65], off offset:384
	global_load_dword v124, v[66:67], off
	global_load_dword v125, v[66:67], off offset:128
	global_load_dword v123, v[66:67], off offset:256
	global_load_dword v122, v[66:67], off offset:384
	v_or_b32_e32 v64, 16, v102
	v_or_b32_e32 v66, 17, v102
	v_ashrrev_i32_e32 v65, 31, v64
	v_ashrrev_i32_e32 v67, 31, v66
	v_lshlrev_b64 v[86:87], 11, v[64:65]
	v_lshlrev_b64 v[78:79], 11, v[66:67]
	v_lshl_add_u64 v[64:65], v[92:93], 0, v[86:87]
	v_lshl_add_u64 v[66:67], v[92:93], 0, v[78:79]
	global_load_dword v100, v[64:65], off
	global_load_dword v101, v[64:65], off offset:128
	global_load_dword v99, v[64:65], off offset:256
	global_load_dword v98, v[64:65], off offset:384
	global_load_dword v96, v[66:67], off
	global_load_dword v97, v[66:67], off offset:128
	global_load_dword v95, v[66:67], off offset:256
	global_load_dword v94, v[66:67], off offset:384
	v_or_b32_e32 v64, 18, v102
	v_or_b32_e32 v66, 19, v102
	v_ashrrev_i32_e32 v65, 31, v64
	v_ashrrev_i32_e32 v67, 31, v66
	v_lshlrev_b64 v[76:77], 11, v[64:65]
	v_lshlrev_b64 v[72:73], 11, v[66:67]
	v_lshl_add_u64 v[64:65], v[92:93], 0, v[76:77]
	v_lshl_add_u64 v[66:67], v[92:93], 0, v[72:73]
	v_lshl_add_u32 v169, v69, 2, s0
	global_load_dword v88, v[64:65], off
	global_load_dword v89, v[64:65], off offset:128
	global_load_dword v85, v[64:65], off offset:256
	global_load_dword v84, v[64:65], off offset:384
	global_load_dword v82, v[66:67], off
	global_load_dword v83, v[66:67], off offset:128
	global_load_dword v81, v[66:67], off offset:256
	global_load_dword v80, v[66:67], off offset:384
	ds_read_b128 v[64:67], v169
	v_or_b32_e32 v68, 24, v102
	v_ashrrev_i32_e32 v69, 31, v68
	v_lshlrev_b64 v[74:75], 11, v[68:69]
	ds_read_b128 v[68:71], v169 offset:32
	s_waitcnt lgkmcnt(0)
	v_rcp_f32_e32 v64, v64
	v_mov_b32_e32 v162, v0
	v_mov_b32_e32 v163, v48
	v_rcp_f32_e32 v0, v65
	v_pk_mul_f32 v[162:163], v[162:163], v[64:65] op_sel_hi:[1,0]
	v_mov_b32_e32 v48, v1
	v_lshlrev_b32_e32 v166, 2, v114
	v_pk_mul_f32 v[48:49], v[48:49], v[0:1] op_sel_hi:[1,0]
	v_xor_b32_e32 v164, 4, v166
	v_xor_b32_e32 v165, 8, v166
	v_xor_b32_e32 v168, 16, v166
	v_xor_b32_e32 v167, 32, v166
	v_or_b32_e32 v116, 25, v102
	v_ashrrev_i32_e32 v117, 31, v116
	v_xor_b32_e32 v166, 64, v166
	v_lshl_add_u64 v[112:113], v[92:93], 0, v[74:75]
	s_add_u32 s1, s60, s58
	s_mov_b32 s0, 0x358637bd
	s_addc_u32 s3, s61, s59
	s_lshl_b32 s2, s87, 1
	s_add_u32 s2, s1, s2
	s_addc_u32 s3, s3, 0
	s_waitcnt vmcnt(0)
	v_pk_fma_f32 v[172:173], v[128:129], v[162:163], v[110:111] neg_lo:[1,0,0] neg_hi:[1,0,0]
	v_mov_b32_e32 v162, v32
	v_mov_b32_e32 v163, v16
	v_pk_mul_f32 v[162:163], v[162:163], v[64:65] op_sel_hi:[1,0]
	v_mov_b32_e32 v16, v33
	v_pk_fma_f32 v[174:175], v[128:129], v[162:163], v[108:109] neg_lo:[1,0,0] neg_hi:[1,0,0]
	global_load_dword v163, v130, s[50:51]
	global_load_dword v162, v130, s[50:51] offset:128
	global_load_dword v161, v130, s[50:51] offset:256
	s_nop 0
	global_load_dword v130, v130, s[50:51] offset:384
	v_pk_fma_f32 v[176:177], v[128:129], v[48:49], v[106:107] neg_lo:[1,0,0] neg_hi:[1,0,0]
	v_pk_mul_f32 v[0:1], v[16:17], v[0:1] op_sel_hi:[1,0]
	v_pk_mul_f32 v[110:111], v[172:173], v[172:173]
	v_pk_mul_f32 v[48:49], v[176:177], v[176:177]
	v_pk_fma_f32 v[0:1], v[128:129], v[0:1], v[104:105] neg_lo:[1,0,0] neg_hi:[1,0,0]
	v_pk_mul_f32 v[108:109], v[174:175], v[174:175]
	v_pk_mul_f32 v[16:17], v[0:1], v[0:1]
	v_mov_b32_e32 v32, v48
	v_mov_b32_e32 v33, v110
	v_mov_b32_e32 v110, v49
	v_pk_add_f32 v[32:33], v[32:33], v[110:111]
	v_mov_b32_e32 v48, v17
	v_mov_b32_e32 v49, v109
	v_pk_add_f32 v[32:33], v[48:49], v[32:33]
	v_mov_b32_e32 v17, v108
	v_pk_add_f32 v[16:17], v[16:17], v[32:33]
	ds_bpermute_b32 v33, v164, v17
	ds_bpermute_b32 v32, v164, v16
	v_lshlrev_b64 v[64:65], 11, v[116:117]
	v_lshl_add_u64 v[48:49], v[92:93], 0, v[64:65]
	global_load_dword v116, v[112:113], off
	global_load_dword v117, v[112:113], off offset:128
	global_load_dword v115, v[112:113], off offset:256
	global_load_dword v114, v[112:113], off offset:384
	s_nop 0
	global_load_dword v112, v[48:49], off
	global_load_dword v113, v[48:49], off offset:128
	global_load_dword v111, v[48:49], off offset:256
	global_load_dword v110, v[48:49], off offset:384
	v_or_b32_e32 v48, 26, v102
	s_waitcnt lgkmcnt(0)
	v_pk_add_f32 v[16:17], v[16:17], v[32:33]
	ds_bpermute_b32 v33, v165, v17
	ds_bpermute_b32 v32, v165, v16
	v_or_b32_e32 v102, 27, v102
	v_ashrrev_i32_e32 v49, 31, v48
	v_ashrrev_i32_e32 v103, 31, v102
	v_lshlrev_b64 v[48:49], 11, v[48:49]
	s_waitcnt lgkmcnt(0)
	v_pk_add_f32 v[16:17], v[16:17], v[32:33]
	ds_bpermute_b32 v33, v168, v17
	ds_bpermute_b32 v32, v168, v16
	v_lshl_add_u64 v[104:105], v[92:93], 0, v[48:49]
	v_lshlrev_b32_e32 v170, 1, v170
	v_mov_b32_e32 v171, v131
	v_rcp_f32_e32 v66, v66
	s_waitcnt lgkmcnt(0)
	v_pk_add_f32 v[32:33], v[16:17], v[32:33]
	ds_bpermute_b32 v107, v167, v33
	ds_bpermute_b32 v106, v167, v32
	v_lshlrev_b64 v[16:17], 11, v[102:103]
	v_lshl_add_u64 v[92:93], v[92:93], 0, v[16:17]
	s_waitcnt lgkmcnt(0)
	v_pk_add_f32 v[32:33], v[32:33], v[106:107]
	ds_bpermute_b32 v179, v166, v33
	ds_bpermute_b32 v178, v166, v32
	global_load_dword v108, v[104:105], off
	global_load_dword v109, v[104:105], off offset:128
	global_load_dword v107, v[104:105], off offset:256
	global_load_dword v106, v[104:105], off offset:384
	s_nop 0
	global_load_dword v104, v[92:93], off
	global_load_dword v105, v[92:93], off offset:128
	global_load_dword v103, v[92:93], off offset:256
	global_load_dword v102, v[92:93], off offset:384
	v_mov_b64_e32 v[92:93], s[0:1]
	s_waitcnt lgkmcnt(0)
; DI unsigned short f2bf(float x) { unsigned u = __float_as_uint(x); u += 0x7fffu + ((u >> 16) & 1u); return (unsigned short)(u >> 16); }
; DI float shx(float v, int mask, int lane) { return __int_as_float(__builtin_amdgcn_ds_bpermute((lane ^ mask) << 2, __float_as_int(v))); }
; template <int DQK, int MODE, int LDQ, int LDK, int LDV> ...
;     ...
;             float v[4]; float ss = 0.f;
; #pragma unroll
;             for (int d0 = 0; d0 < 4; ++d0) { v[d0] = s0v[r][d0] - lam * (o[d0][r] * rl); ss += v[d0] * v[d0]; }
; #pragma unroll
;             for (int mk = 1; mk <= 16; mk <<= 1) ss += shx(ss, mk, lane2);
;             const float rs = rsqrtf(ss * (1.f / 128.f) + EPS) * 0.8f;
; #pragma unroll
;             for (int d0 = 0; d0 < 4; ++d0) AOb[(size_t)orow * 1024 + d0 * 32 + r32] = f2bf(v[d0] * rs * gout[d0 * 32 + r32]);
;         } }
	v_pk_add_f32 v[32:33], v[32:33], v[178:179]
	s_nop 0
	v_pk_fma_f32 v[178:179], v[32:33], s[24:25], v[92:93] op_sel_hi:[1,0,0]
	s_nop 0
	v_mul_f32_e32 v32, 0x4b800000, v179
	v_cmp_gt_f32_e32 vcc, s67, v179
	s_nop 1
	v_cndmask_b32_e32 v32, v179, v32, vcc
	v_rsq_f32_e32 v179, v32
	v_lshl_add_u64 v[32:33], s[2:3], 0, v[170:171]
	v_lshl_add_u64 v[156:157], v[32:33], 0, v[156:157]
	v_lshl_add_u64 v[148:149], v[32:33], 0, v[148:149]
	v_mul_f32_e32 v170, 0x45800000, v179
	v_cndmask_b32_e32 v170, v179, v170, vcc
	v_mul_f32_e32 v170, 0x3f4ccccd, v170
	v_mul_f32_e32 v171, v172, v170
	v_cmp_gt_f32_e32 vcc, s67, v178
	s_mov_b64 s[2:3], 0
	s_waitcnt vmcnt(19)
	v_mul_f32_e32 v171, v163, v171
	v_bfe_u32 v172, v171, 16, 1
	v_add3_u32 v171, v171, v172, s68
	global_store_short_d16_hi v[156:157], v171, off offset:1024
	v_mul_f32_e32 v171, v173, v170
	s_waitcnt vmcnt(19)
	v_mul_f32_e32 v171, v162, v171
	v_bfe_u32 v172, v171, 16, 1
	v_add3_u32 v171, v171, v172, s68
	global_store_short_d16_hi v[156:157], v171, off offset:1088
	v_mul_f32_e32 v171, v175, v170
	s_waitcnt vmcnt(19)
	v_mul_f32_e32 v171, v161, v171
	v_bfe_u32 v172, v171, 16, 1
	v_add3_u32 v171, v171, v172, s68
	global_store_short_d16_hi v[156:157], v171, off offset:1152
	v_mul_f32_e32 v171, 0x4b800000, v178
	v_cndmask_b32_e32 v171, v178, v171, vcc
	v_mul_f32_e32 v170, v174, v170
	v_rsq_f32_e32 v171, v171
	s_waitcnt vmcnt(19)
	v_mul_f32_e32 v170, v130, v170
	v_bfe_u32 v172, v170, 16, 1
	v_add3_u32 v170, v170, v172, s68
	global_store_short_d16_hi v[156:157], v170, off offset:1216
	v_mul_f32_e32 v156, 0x45800000, v171
	v_cndmask_b32_e32 v172, v171, v156, vcc
	v_mov_b32_e32 v156, v2
	v_rcp_f32_e32 v2, v67
	v_mov_b32_e32 v157, v50
	v_mov_b32_e32 v50, v3
	v_pk_mul_f32 v[156:157], v[156:157], v[66:67] op_sel_hi:[1,0]
	v_mov_b32_e32 v170, v34
	v_mov_b32_e32 v171, v18
	v_pk_mul_f32 v[50:51], v[50:51], v[2:3] op_sel_hi:[1,0]
	v_mov_b32_e32 v18, v35
	v_pk_fma_f32 v[156:157], v[128:129], v[156:157], v[158:159] neg_lo:[1,0,0] neg_hi:[1,0,0]
	v_pk_mul_f32 v[170:171], v[170:171], v[66:67] op_sel_hi:[1,0]
	v_pk_fma_f32 v[50:51], v[128:129], v[50:51], v[152:153] neg_lo:[1,0,0] neg_hi:[1,0,0]
	v_pk_mul_f32 v[2:3], v[18:19], v[2:3] op_sel_hi:[1,0]
	v_pk_mul_f32 v[158:159], v[156:157], v[156:157]
	v_pk_fma_f32 v[66:67], v[128:129], v[170:171], v[154:155] neg_lo:[1,0,0] neg_hi:[1,0,0]
	v_pk_mul_f32 v[152:153], v[50:51], v[50:51]
	v_pk_fma_f32 v[2:3], v[128:129], v[2:3], v[150:151] neg_lo:[1,0,0] neg_hi:[1,0,0]
	v_pk_mul_f32 v[154:155], v[66:67], v[66:67]
	v_pk_mul_f32 v[18:19], v[2:3], v[2:3]
	v_mov_b32_e32 v34, v152
	v_mov_b32_e32 v35, v158
	v_mov_b32_e32 v158, v153
	v_pk_add_f32 v[34:35], v[34:35], v[158:159]
	v_mov_b32_e32 v150, v19
	v_mov_b32_e32 v151, v155
	v_pk_add_f32 v[34:35], v[150:151], v[34:35]
	v_mov_b32_e32 v19, v154
	v_pk_add_f32 v[18:19], v[18:19], v[34:35]
	ds_bpermute_b32 v35, v164, v19
	ds_bpermute_b32 v34, v164, v18
	v_mul_f32_e32 v150, 0x3f4ccccd, v172
	v_mul_f32_e32 v151, v176, v150
	v_mul_f32_e32 v151, v163, v151
	v_bfe_u32 v152, v151, 16, 1
	s_waitcnt lgkmcnt(0)
	v_pk_add_f32 v[18:19], v[18:19], v[34:35]
	ds_bpermute_b32 v35, v165, v19
	ds_bpermute_b32 v34, v165, v18
	v_add3_u32 v151, v151, v152, s68
	global_store_short_d16_hi v[148:149], v151, off offset:1024
	v_mul_f32_e32 v151, v177, v150
	v_mul_f32_e32 v151, v162, v151
	s_waitcnt lgkmcnt(0)
	v_pk_add_f32 v[18:19], v[18:19], v[34:35]
	ds_bpermute_b32 v35, v168, v19
	ds_bpermute_b32 v34, v168, v18
	v_bfe_u32 v152, v151, 16, 1
	v_mul_f32_e32 v1, v1, v150
	v_add3_u32 v151, v151, v152, s68
	v_mul_f32_e32 v1, v161, v1
	s_waitcnt lgkmcnt(0)
	v_pk_add_f32 v[18:19], v[18:19], v[34:35]
	ds_bpermute_b32 v35, v167, v19
	ds_bpermute_b32 v34, v167, v18
	global_store_short_d16_hi v[148:149], v151, off offset:1088
	v_bfe_u32 v151, v1, 16, 1
	v_add3_u32 v1, v1, v151, s68
	v_mul_f32_e32 v0, v0, v150
	s_waitcnt lgkmcnt(0)
	v_pk_add_f32 v[18:19], v[18:19], v[34:35]
	ds_bpermute_b32 v35, v166, v19
	ds_bpermute_b32 v34, v166, v18
	global_store_short_d16_hi v[148:149], v1, off offset:1152
	v_mul_f32_e32 v150, v130, v0
	v_bfe_u32 v151, v150, 16, 1
	s_waitcnt lgkmcnt(0)
	v_pk_add_f32 v[0:1], v[18:19], v[34:35]
	s_nop 0
	v_pk_fma_f32 v[0:1], v[0:1], s[24:25], v[92:93] op_sel_hi:[1,0,0]
	s_nop 0
	v_mul_f32_e32 v18, 0x4b800000, v1
	v_cmp_gt_f32_e32 vcc, s67, v1
	s_nop 1
	v_cndmask_b32_e32 v1, v1, v18, vcc
	v_rsq_f32_e32 v1, v1
	v_add3_u32 v18, v150, v151, s68
	global_store_short_d16_hi v[148:149], v18, off offset:1216
	v_lshl_add_u64 v[18:19], v[32:33], 0, v[146:147]
	v_mul_f32_e32 v34, 0x45800000, v1
	v_cndmask_b32_e32 v1, v1, v34, vcc
	v_mul_f32_e32 v1, 0x3f4ccccd, v1
	v_mul_f32_e32 v34, v156, v1
	v_mul_f32_e32 v34, v163, v34
	v_bfe_u32 v35, v34, 16, 1
	v_add3_u32 v34, v34, v35, s68
	global_store_short_d16_hi v[18:19], v34, off offset:1024
	v_mul_f32_e32 v34, v157, v1
	v_mul_f32_e32 v34, v162, v34
	v_bfe_u32 v35, v34, 16, 1
	v_add3_u32 v34, v34, v35, s68
	global_store_short_d16_hi v[18:19], v34, off offset:1088
	v_mul_f32_e32 v34, v67, v1
	v_mul_f32_e32 v34, v161, v34
	v_bfe_u32 v35, v34, 16, 1
	v_add3_u32 v34, v34, v35, s68
	global_store_short_d16_hi v[18:19], v34, off offset:1152
	v_mul_f32_e32 v1, v66, v1
	v_mul_f32_e32 v34, 0x4b800000, v0
	v_cmp_gt_f32_e32 vcc, s67, v0
	v_mul_f32_e32 v1, v130, v1
	v_mov_b32_e32 v66, v36
	v_cndmask_b32_e32 v0, v0, v34, vcc
	v_rsq_f32_e32 v34, v0
	v_bfe_u32 v0, v1, 16, 1
	v_add3_u32 v0, v1, v0, s68
	global_store_short_d16_hi v[18:19], v0, off offset:1216
	v_rcp_f32_e32 v0, v68
	v_mov_b32_e32 v18, v4
	v_rcp_f32_e32 v4, v69
	v_mul_f32_e32 v1, 0x45800000, v34
	v_mov_b32_e32 v19, v52
	v_mov_b32_e32 v52, v5
	v_pk_mul_f32 v[18:19], v[18:19], v[0:1] op_sel_hi:[1,0]
	v_mov_b32_e32 v67, v20
	v_pk_mul_f32 v[52:53], v[52:53], v[4:5] op_sel_hi:[1,0]
	v_mov_b32_e32 v20, v37
	v_cndmask_b32_e32 v146, v34, v1, vcc
	v_pk_fma_f32 v[18:19], v[128:129], v[18:19], v[144:145] neg_lo:[1,0,0] neg_hi:[1,0,0]
	v_pk_mul_f32 v[0:1], v[66:67], v[0:1] op_sel_hi:[1,0]
	v_pk_fma_f32 v[52:53], v[128:129], v[52:53], v[140:141] neg_lo:[1,0,0] neg_hi:[1,0,0]
	v_pk_mul_f32 v[4:5], v[20:21], v[4:5] op_sel_hi:[1,0]
	v_pk_mul_f32 v[34:35], v[18:19], v[18:19]
	v_pk_fma_f32 v[0:1], v[128:129], v[0:1], v[142:143] neg_lo:[1,0,0] neg_hi:[1,0,0]
	v_pk_mul_f32 v[68:69], v[52:53], v[52:53]
	v_pk_fma_f32 v[4:5], v[128:129], v[4:5], v[138:139] neg_lo:[1,0,0] neg_hi:[1,0,0]
	v_pk_mul_f32 v[66:67], v[0:1], v[0:1]
	v_pk_mul_f32 v[20:21], v[4:5], v[4:5]
	v_mov_b32_e32 v36, v68
	v_mov_b32_e32 v37, v34
	v_mov_b32_e32 v34, v69
	v_pk_add_f32 v[34:35], v[36:37], v[34:35]
	v_mov_b32_e32 v36, v21
	v_mov_b32_e32 v37, v67
	v_pk_add_f32 v[34:35], v[36:37], v[34:35]
	v_mov_b32_e32 v21, v66
	v_pk_add_f32 v[20:21], v[20:21], v[34:35]
	ds_bpermute_b32 v35, v164, v21
	ds_bpermute_b32 v34, v164, v20
	v_mul_f32_e32 v66, 0x3f4ccccd, v146
	v_mul_f32_e32 v50, v50, v66
	v_mul_f32_e32 v50, v163, v50
	v_bfe_u32 v67, v50, 16, 1
	s_waitcnt lgkmcnt(0)
; DI unsigned short f2bf(float x) { unsigned u = __float_as_uint(x); u += 0x7fffu + ((u >> 16) & 1u); return (unsigned short)(u >> 16); }
; DI float shx(float v, int mask, int lane) { return __int_as_float(__builtin_amdgcn_ds_bpermute((lane ^ mask) << 2, __float_as_int(v))); }
; template <int DQK, int MODE, int LDQ, int LDK, int LDV> ...
;     ...
;             float v[4]; float ss = 0.f;
; #pragma unroll
;             for (int d0 = 0; d0 < 4; ++d0) { v[d0] = s0v[r][d0] - lam * (o[d0][r] * rl); ss += v[d0] * v[d0]; }
; #pragma unroll
;             for (int mk = 1; mk <= 16; mk <<= 1) ss += shx(ss, mk, lane2);
;             const float rs = rsqrtf(ss * (1.f / 128.f) + EPS) * 0.8f;
; #pragma unroll
;             for (int d0 = 0; d0 < 4; ++d0) AOb[(size_t)orow * 1024 + d0 * 32 + r32] = f2bf(v[d0] * rs * gout[d0 * 32 + r32]);
;         } }
	v_pk_add_f32 v[20:21], v[20:21], v[34:35]
	ds_bpermute_b32 v35, v165, v21
	ds_bpermute_b32 v34, v165, v20
	v_lshl_add_u64 v[36:37], v[32:33], 0, v[136:137]
	v_add3_u32 v50, v50, v67, s68
	global_store_short_d16_hi v[36:37], v50, off offset:1024
	v_mul_f32_e32 v50, v51, v66
	s_waitcnt lgkmcnt(0)
	v_pk_add_f32 v[20:21], v[20:21], v[34:35]
	ds_bpermute_b32 v35, v168, v21
	ds_bpermute_b32 v34, v168, v20
	v_mul_f32_e32 v50, v162, v50
	v_bfe_u32 v51, v50, 16, 1
	v_mul_f32_e32 v3, v3, v66
	v_add3_u32 v50, v50, v51, s68
	s_waitcnt lgkmcnt(0)
	v_pk_add_f32 v[20:21], v[20:21], v[34:35]
	ds_bpermute_b32 v35, v167, v21
	ds_bpermute_b32 v34, v167, v20
	v_mul_f32_e32 v3, v161, v3
	global_store_short_d16_hi v[36:37], v50, off offset:1088
	v_bfe_u32 v50, v3, 16, 1
	v_add3_u32 v3, v3, v50, s68
	s_waitcnt lgkmcnt(0)
	v_pk_add_f32 v[20:21], v[20:21], v[34:35]
	ds_bpermute_b32 v35, v166, v21
	ds_bpermute_b32 v34, v166, v20
	v_mul_f32_e32 v2, v2, v66
	global_store_short_d16_hi v[36:37], v3, off offset:1152
	v_mul_f32_e32 v50, v130, v2
	v_bfe_u32 v51, v50, 16, 1
	s_waitcnt lgkmcnt(0)
	v_pk_add_f32 v[2:3], v[20:21], v[34:35]
	s_nop 0
	v_pk_fma_f32 v[2:3], v[2:3], s[24:25], v[92:93] op_sel_hi:[1,0,0]
	s_nop 0
	v_mul_f32_e32 v20, 0x4b800000, v3
	v_cmp_gt_f32_e32 vcc, s67, v3
	s_nop 1
	v_cndmask_b32_e32 v3, v3, v20, vcc
	v_rsq_f32_e32 v3, v3
	v_add3_u32 v20, v50, v51, s68
	global_store_short_d16_hi v[36:37], v20, off offset:1216
	v_lshl_add_u64 v[20:21], v[32:33], 0, v[134:135]
	v_mul_f32_e32 v34, 0x45800000, v3
	v_cndmask_b32_e32 v3, v3, v34, vcc
	v_mul_f32_e32 v3, 0x3f4ccccd, v3
	v_mul_f32_e32 v18, v18, v3
	v_mul_f32_e32 v18, v163, v18
	v_bfe_u32 v34, v18, 16, 1
	v_add3_u32 v18, v18, v34, s68
	global_store_short_d16_hi v[20:21], v18, off offset:1024
	v_mul_f32_e32 v18, v19, v3
	v_mul_f32_e32 v18, v162, v18
	v_bfe_u32 v19, v18, 16, 1
	v_mul_f32_e32 v1, v1, v3
	v_add3_u32 v18, v18, v19, s68
	v_mul_f32_e32 v1, v161, v1
	global_store_short_d16_hi v[20:21], v18, off offset:1088
	v_bfe_u32 v18, v1, 16, 1
	v_add3_u32 v1, v1, v18, s68
	global_store_short_d16_hi v[20:21], v1, off offset:1152
	v_mul_f32_e32 v1, 0x4b800000, v2
	v_cmp_gt_f32_e32 vcc, s67, v2
	v_mul_f32_e32 v0, v0, v3
	v_mul_f32_e32 v0, v130, v0
	v_cndmask_b32_e32 v1, v2, v1, vcc
	v_rsq_f32_e32 v1, v1
	v_bfe_u32 v2, v0, 16, 1
	v_add3_u32 v0, v0, v2, s68
	global_store_short_d16_hi v[20:21], v0, off offset:1216
	v_mul_f32_e32 v2, 0x45800000, v1
	v_rcp_f32_e32 v0, v70
	v_cndmask_b32_e32 v66, v1, v2, vcc
	v_mov_b32_e32 v2, v6
	v_rcp_f32_e32 v6, v71
	v_mov_b32_e32 v3, v54
	v_mov_b32_e32 v18, v38
	v_mov_b32_e32 v19, v22
	v_mov_b32_e32 v54, v7
	v_pk_mul_f32 v[2:3], v[2:3], v[0:1] op_sel_hi:[1,0]
	v_pk_mul_f32 v[0:1], v[18:19], v[0:1] op_sel_hi:[1,0]
	v_pk_mul_f32 v[18:19], v[54:55], v[6:7] op_sel_hi:[1,0]
	v_mov_b32_e32 v22, v39
	v_pk_fma_f32 v[2:3], v[128:129], v[2:3], v[132:133] neg_lo:[1,0,0] neg_hi:[1,0,0]
	v_pk_fma_f32 v[20:21], v[128:129], v[18:19], v[124:125] neg_lo:[1,0,0] neg_hi:[1,0,0]
	v_pk_mul_f32 v[6:7], v[22:23], v[6:7] op_sel_hi:[1,0]
	v_pk_mul_f32 v[34:35], v[2:3], v[2:3]
	v_pk_fma_f32 v[0:1], v[128:129], v[0:1], v[126:127] neg_lo:[1,0,0] neg_hi:[1,0,0]
	v_pk_mul_f32 v[50:51], v[20:21], v[20:21]
	v_pk_fma_f32 v[18:19], v[128:129], v[6:7], v[122:123] neg_lo:[1,0,0] neg_hi:[1,0,0]
	v_pk_mul_f32 v[36:37], v[0:1], v[0:1]
	v_pk_mul_f32 v[6:7], v[18:19], v[18:19]
	v_mov_b32_e32 v22, v50
	v_mov_b32_e32 v23, v34
	v_mov_b32_e32 v34, v51
	v_pk_add_f32 v[22:23], v[22:23], v[34:35]
	v_mov_b32_e32 v34, v7
	v_mov_b32_e32 v35, v37
	v_pk_add_f32 v[22:23], v[34:35], v[22:23]
	v_mov_b32_e32 v7, v36
	v_pk_add_f32 v[6:7], v[6:7], v[22:23]
	ds_bpermute_b32 v23, v164, v7
	ds_bpermute_b32 v22, v164, v6
	v_mul_f32_e32 v36, 0x3f4ccccd, v66
	v_mul_f32_e32 v37, v52, v36
	v_mul_f32_e32 v37, v163, v37
	v_bfe_u32 v38, v37, 16, 1
	s_waitcnt lgkmcnt(0)
	v_pk_add_f32 v[6:7], v[6:7], v[22:23]
	ds_bpermute_b32 v23, v165, v7
	ds_bpermute_b32 v22, v165, v6
	v_lshl_add_u64 v[34:35], v[32:33], 0, v[120:121]
	v_add3_u32 v37, v37, v38, s68
	global_store_short_d16_hi v[34:35], v37, off offset:1024
	v_mul_f32_e32 v37, v53, v36
	s_waitcnt lgkmcnt(0)
	v_pk_add_f32 v[6:7], v[6:7], v[22:23]
	ds_bpermute_b32 v23, v168, v7
	ds_bpermute_b32 v22, v168, v6
	v_mul_f32_e32 v37, v162, v37
	v_bfe_u32 v38, v37, 16, 1
	v_mul_f32_e32 v5, v5, v36
	v_add3_u32 v37, v37, v38, s68
	s_waitcnt lgkmcnt(0)
	v_pk_add_f32 v[6:7], v[6:7], v[22:23]
	ds_bpermute_b32 v23, v167, v7
	ds_bpermute_b32 v22, v167, v6
	v_mul_f32_e32 v5, v161, v5
	global_store_short_d16_hi v[34:35], v37, off offset:1088
	v_bfe_u32 v37, v5, 16, 1
	v_add3_u32 v5, v5, v37, s68
	s_waitcnt lgkmcnt(0)
	v_pk_add_f32 v[6:7], v[6:7], v[22:23]
	ds_bpermute_b32 v23, v166, v7
	ds_bpermute_b32 v22, v166, v6
	v_mul_f32_e32 v4, v4, v36
	global_store_short_d16_hi v[34:35], v5, off offset:1152
	v_mul_f32_e32 v36, v130, v4
	v_bfe_u32 v37, v36, 16, 1
	s_waitcnt lgkmcnt(0)
	v_pk_add_f32 v[4:5], v[6:7], v[22:23]
	v_lshl_add_u64 v[22:23], v[32:33], 0, v[118:119]
	v_pk_fma_f32 v[4:5], v[4:5], s[24:25], v[92:93] op_sel_hi:[1,0,0]
	s_nop 0
	v_mul_f32_e32 v6, 0x4b800000, v5
	v_cmp_gt_f32_e32 vcc, s67, v5
	s_nop 1
	v_cndmask_b32_e32 v5, v5, v6, vcc
	v_rsq_f32_e32 v5, v5
	v_add3_u32 v6, v36, v37, s68
	global_store_short_d16_hi v[34:35], v6, off offset:1216
	v_mov_b32_e32 v36, v40
	v_mul_f32_e32 v6, 0x45800000, v5
	v_cndmask_b32_e32 v5, v5, v6, vcc
	v_mul_f32_e32 v5, 0x3f4ccccd, v5
	v_mul_f32_e32 v2, v2, v5
	v_mul_f32_e32 v2, v163, v2
	v_bfe_u32 v6, v2, 16, 1
	v_add3_u32 v2, v2, v6, s68
	global_store_short_d16_hi v[22:23], v2, off offset:1024
	v_mul_f32_e32 v2, v3, v5
	v_mul_f32_e32 v2, v162, v2
	v_bfe_u32 v3, v2, 16, 1
	v_mul_f32_e32 v1, v1, v5
	v_add3_u32 v2, v2, v3, s68
	v_mul_f32_e32 v1, v161, v1
	global_store_short_d16_hi v[22:23], v2, off offset:1088
	v_bfe_u32 v2, v1, 16, 1
	v_add3_u32 v1, v1, v2, s68
	v_mul_f32_e32 v2, 0x4b800000, v4
	v_cmp_gt_f32_e32 vcc, s67, v4
	v_mul_f32_e32 v0, v0, v5
	v_mul_f32_e32 v0, v130, v0
	v_cndmask_b32_e32 v2, v4, v2, vcc
	ds_read_b128 v[4:7], v169 offset:64
	global_store_short_d16_hi v[22:23], v1, off offset:1152
	v_bfe_u32 v1, v0, 16, 1
	v_rsq_f32_e32 v34, v2
	v_add3_u32 v0, v0, v1, s68
	global_store_short_d16_hi v[22:23], v0, off offset:1216
	ds_read_b128 v[0:3], v169 offset:96
	s_waitcnt lgkmcnt(1)
; DI unsigned short f2bf(float x) { unsigned u = __float_as_uint(x); u += 0x7fffu + ((u >> 16) & 1u); return (unsigned short)(u >> 16); }
; DI float shx(float v, int mask, int lane) { return __int_as_float(__builtin_amdgcn_ds_bpermute((lane ^ mask) << 2, __float_as_int(v))); }
; template <int DQK, int MODE, int LDQ, int LDK, int LDV> ...
;     ...
;             float v[4]; float ss = 0.f;
; #pragma unroll
;             for (int d0 = 0; d0 < 4; ++d0) { v[d0] = s0v[r][d0] - lam * (o[d0][r] * rl); ss += v[d0] * v[d0]; }
; #pragma unroll
;             for (int mk = 1; mk <= 16; mk <<= 1) ss += shx(ss, mk, lane2);
;             const float rs = rsqrtf(ss * (1.f / 128.f) + EPS) * 0.8f;
; #pragma unroll
;             for (int d0 = 0; d0 < 4; ++d0) AOb[(size_t)orow * 1024 + d0 * 32 + r32] = f2bf(v[d0] * rs * gout[d0 * 32 + r32]);
;         } }
	v_rcp_f32_e32 v4, v4
	v_mul_f32_e32 v22, 0x45800000, v34
	v_cndmask_b32_e32 v52, v34, v22, vcc
	v_mov_b32_e32 v22, v8
	v_mov_b32_e32 v23, v56
	v_mov_b32_e32 v37, v24
	v_pk_mul_f32 v[22:23], v[22:23], v[4:5] op_sel_hi:[1,0]
	v_pk_mul_f32 v[36:37], v[36:37], v[4:5] op_sel_hi:[1,0]
	v_rcp_f32_e32 v4, v5
	v_mov_b32_e32 v56, v9
	v_mov_b32_e32 v24, v41
	v_pk_fma_f32 v[22:23], v[128:129], v[22:23], v[100:101] neg_lo:[1,0,0] neg_hi:[1,0,0]
	v_pk_mul_f32 v[8:9], v[56:57], v[4:5] op_sel_hi:[1,0]
	v_pk_mul_f32 v[4:5], v[24:25], v[4:5] op_sel_hi:[1,0]
	v_pk_fma_f32 v[8:9], v[128:129], v[8:9], v[96:97] neg_lo:[1,0,0] neg_hi:[1,0,0]
	v_pk_mul_f32 v[34:35], v[22:23], v[22:23]
	v_pk_fma_f32 v[36:37], v[128:129], v[36:37], v[98:99] neg_lo:[1,0,0] neg_hi:[1,0,0]
	v_pk_mul_f32 v[50:51], v[8:9], v[8:9]
	v_pk_fma_f32 v[4:5], v[128:129], v[4:5], v[94:95] neg_lo:[1,0,0] neg_hi:[1,0,0]
	v_pk_mul_f32 v[38:39], v[36:37], v[36:37]
	v_pk_mul_f32 v[24:25], v[4:5], v[4:5]
	v_mov_b32_e32 v40, v50
	v_mov_b32_e32 v41, v34
	v_mov_b32_e32 v34, v51
	v_pk_add_f32 v[34:35], v[40:41], v[34:35]
	v_mov_b32_e32 v40, v25
	v_mov_b32_e32 v41, v39
	v_pk_add_f32 v[34:35], v[40:41], v[34:35]
	v_mov_b32_e32 v25, v38
	v_pk_add_f32 v[24:25], v[24:25], v[34:35]
	ds_bpermute_b32 v35, v164, v25
	ds_bpermute_b32 v34, v164, v24
	v_mul_f32_e32 v40, 0x3f4ccccd, v52
	v_mul_f32_e32 v20, v20, v40
	v_mul_f32_e32 v20, v163, v20
	v_bfe_u32 v41, v20, 16, 1
	s_waitcnt lgkmcnt(0)
	v_pk_add_f32 v[24:25], v[24:25], v[34:35]
	ds_bpermute_b32 v35, v165, v25
	ds_bpermute_b32 v34, v165, v24
	v_lshl_add_u64 v[38:39], v[32:33], 0, v[90:91]
	v_add3_u32 v20, v20, v41, s68
	global_store_short_d16_hi v[38:39], v20, off offset:1024
	v_mul_f32_e32 v41, v21, v40
	s_waitcnt lgkmcnt(0)
	v_pk_add_f32 v[20:21], v[24:25], v[34:35]
	ds_bpermute_b32 v25, v168, v21
	ds_bpermute_b32 v24, v168, v20
	v_mul_f32_e32 v34, v162, v41
	v_bfe_u32 v35, v34, 16, 1
	v_mul_f32_e32 v19, v19, v40
	v_add3_u32 v34, v34, v35, s68
	s_waitcnt lgkmcnt(0)
	v_pk_add_f32 v[20:21], v[20:21], v[24:25]
	ds_bpermute_b32 v25, v167, v21
	ds_bpermute_b32 v24, v167, v20
	v_mul_f32_e32 v19, v161, v19
	global_store_short_d16_hi v[38:39], v34, off offset:1088
	v_bfe_u32 v34, v19, 16, 1
	v_add3_u32 v19, v19, v34, s68
	s_waitcnt lgkmcnt(0)
	v_pk_add_f32 v[20:21], v[20:21], v[24:25]
	ds_bpermute_b32 v25, v166, v21
	ds_bpermute_b32 v24, v166, v20
	v_mul_f32_e32 v18, v18, v40
	global_store_short_d16_hi v[38:39], v19, off offset:1152
	v_mul_f32_e32 v34, v130, v18
	v_bfe_u32 v35, v34, 16, 1
	s_waitcnt lgkmcnt(0)
	v_pk_add_f32 v[18:19], v[20:21], v[24:25]
	v_rcp_f32_e32 v6, v6
	v_pk_fma_f32 v[18:19], v[18:19], s[24:25], v[92:93] op_sel_hi:[1,0,0]
	v_rcp_f32_e32 v0, v0
	v_mul_f32_e32 v20, 0x4b800000, v19
	v_cmp_gt_f32_e32 vcc, s67, v19
	v_rcp_f32_e32 v2, v2
	s_nop 0
	v_cndmask_b32_e32 v19, v19, v20, vcc
	v_rsq_f32_e32 v19, v19
	v_add3_u32 v20, v34, v35, s68
	global_store_short_d16_hi v[38:39], v20, off offset:1216
	v_lshl_add_u64 v[20:21], v[32:33], 0, v[86:87]
	v_mul_f32_e32 v24, 0x45800000, v19
	v_cndmask_b32_e32 v19, v19, v24, vcc
	v_mul_f32_e32 v19, 0x3f4ccccd, v19
	v_mul_f32_e32 v22, v22, v19
	v_mul_f32_e32 v22, v163, v22
	v_bfe_u32 v24, v22, 16, 1
	v_add3_u32 v22, v22, v24, s68
	global_store_short_d16_hi v[20:21], v22, off offset:1024
	v_mul_f32_e32 v22, v23, v19
	v_mul_f32_e32 v22, v162, v22
	v_bfe_u32 v23, v22, 16, 1
	v_add3_u32 v22, v22, v23, s68
	global_store_short_d16_hi v[20:21], v22, off offset:1088
	v_mul_f32_e32 v22, v37, v19
	v_mul_f32_e32 v22, v161, v22
	v_bfe_u32 v23, v22, 16, 1
	v_add3_u32 v22, v22, v23, s68
	global_store_short_d16_hi v[20:21], v22, off offset:1152
	v_mul_f32_e32 v22, 0x4b800000, v18
	v_cmp_gt_f32_e32 vcc, s67, v18
	v_mul_f32_e32 v19, v36, v19
	v_mul_f32_e32 v19, v130, v19
	v_cndmask_b32_e32 v18, v18, v22, vcc
	v_rsq_f32_e32 v18, v18
	v_bfe_u32 v22, v19, 16, 1
	v_add3_u32 v19, v19, v22, s68
	global_store_short_d16_hi v[20:21], v19, off offset:1216
	v_mul_f32_e32 v19, 0x45800000, v18
	v_cndmask_b32_e32 v38, v18, v19, vcc
	v_mov_b32_e32 v18, v10
	v_mov_b32_e32 v19, v58
	v_mov_b32_e32 v22, v42
	v_mov_b32_e32 v23, v26
	v_pk_mul_f32 v[18:19], v[18:19], v[6:7] op_sel_hi:[1,0]
	v_pk_mul_f32 v[22:23], v[22:23], v[6:7] op_sel_hi:[1,0]
	v_rcp_f32_e32 v6, v7
	v_mov_b32_e32 v58, v11
	v_mov_b32_e32 v26, v43
	v_pk_fma_f32 v[18:19], v[128:129], v[18:19], v[88:89] neg_lo:[1,0,0] neg_hi:[1,0,0]
	v_pk_mul_f32 v[10:11], v[58:59], v[6:7] op_sel_hi:[1,0]
	v_pk_mul_f32 v[6:7], v[26:27], v[6:7] op_sel_hi:[1,0]
	v_pk_fma_f32 v[10:11], v[128:129], v[10:11], v[82:83] neg_lo:[1,0,0] neg_hi:[1,0,0]
	v_pk_mul_f32 v[20:21], v[18:19], v[18:19]
	v_pk_fma_f32 v[22:23], v[128:129], v[22:23], v[84:85] neg_lo:[1,0,0] neg_hi:[1,0,0]
	v_pk_mul_f32 v[34:35], v[10:11], v[10:11]
	v_pk_fma_f32 v[6:7], v[128:129], v[6:7], v[80:81] neg_lo:[1,0,0] neg_hi:[1,0,0]
	v_pk_mul_f32 v[24:25], v[22:23], v[22:23]
	v_pk_mul_f32 v[26:27], v[6:7], v[6:7]
	v_mov_b32_e32 v36, v34
	v_mov_b32_e32 v37, v20
	v_mov_b32_e32 v20, v35
	v_pk_add_f32 v[20:21], v[36:37], v[20:21]
	v_mov_b32_e32 v34, v27
	v_mov_b32_e32 v35, v25
	v_pk_add_f32 v[20:21], v[34:35], v[20:21]
	v_mov_b32_e32 v27, v24
	v_pk_add_f32 v[20:21], v[26:27], v[20:21]
	ds_bpermute_b32 v25, v164, v21
	ds_bpermute_b32 v24, v164, v20
	v_mul_f32_e32 v34, 0x3f4ccccd, v38
	v_mul_f32_e32 v8, v8, v34
	v_mul_f32_e32 v8, v163, v8
	v_bfe_u32 v35, v8, 16, 1
	s_waitcnt lgkmcnt(0)
	v_pk_add_f32 v[20:21], v[20:21], v[24:25]
	ds_bpermute_b32 v25, v165, v21
	ds_bpermute_b32 v24, v165, v20
	v_lshl_add_u64 v[26:27], v[32:33], 0, v[78:79]
	v_add3_u32 v8, v8, v35, s68
	global_store_short_d16_hi v[26:27], v8, off offset:1024
	v_mul_f32_e32 v35, v9, v34
	s_waitcnt lgkmcnt(0)
; DI unsigned short f2bf(float x) { unsigned u = __float_as_uint(x); u += 0x7fffu + ((u >> 16) & 1u); return (unsigned short)(u >> 16); }
; DI float shx(float v, int mask, int lane) { return __int_as_float(__builtin_amdgcn_ds_bpermute((lane ^ mask) << 2, __float_as_int(v))); }
; template <int DQK, int MODE, int LDQ, int LDK, int LDV> ...
;     ...
;             float v[4]; float ss = 0.f;
; #pragma unroll
;             for (int d0 = 0; d0 < 4; ++d0) { v[d0] = s0v[r][d0] - lam * (o[d0][r] * rl); ss += v[d0] * v[d0]; }
; #pragma unroll
;             for (int mk = 1; mk <= 16; mk <<= 1) ss += shx(ss, mk, lane2);
;             const float rs = rsqrtf(ss * (1.f / 128.f) + EPS) * 0.8f;
; #pragma unroll
;             for (int d0 = 0; d0 < 4; ++d0) AOb[(size_t)orow * 1024 + d0 * 32 + r32] = f2bf(v[d0] * rs * gout[d0 * 32 + r32]);
;         } }
	v_pk_add_f32 v[8:9], v[20:21], v[24:25]
	ds_bpermute_b32 v21, v168, v9
	ds_bpermute_b32 v20, v168, v8
	v_mul_f32_e32 v24, v162, v35
	v_bfe_u32 v25, v24, 16, 1
	v_mul_f32_e32 v5, v5, v34
	v_add3_u32 v24, v24, v25, s68
	s_waitcnt lgkmcnt(0)
	v_pk_add_f32 v[8:9], v[8:9], v[20:21]
	ds_bpermute_b32 v21, v167, v9
	ds_bpermute_b32 v20, v167, v8
	v_mul_f32_e32 v5, v161, v5
	global_store_short_d16_hi v[26:27], v24, off offset:1088
	v_bfe_u32 v24, v5, 16, 1
	v_add3_u32 v5, v5, v24, s68
	s_waitcnt lgkmcnt(0)
	v_pk_add_f32 v[8:9], v[8:9], v[20:21]
	ds_bpermute_b32 v21, v166, v9
	ds_bpermute_b32 v20, v166, v8
	v_mul_f32_e32 v4, v4, v34
	global_store_short_d16_hi v[26:27], v5, off offset:1152
	v_mul_f32_e32 v24, v130, v4
	v_bfe_u32 v25, v24, 16, 1
	s_waitcnt lgkmcnt(0)
	v_pk_add_f32 v[4:5], v[8:9], v[20:21]
	s_nop 0
	v_pk_fma_f32 v[4:5], v[4:5], s[24:25], v[92:93] op_sel_hi:[1,0,0]
	s_nop 0
	v_mul_f32_e32 v8, 0x4b800000, v5
	v_cmp_gt_f32_e32 vcc, s67, v5
	s_nop 1
	v_cndmask_b32_e32 v5, v5, v8, vcc
	v_rsq_f32_e32 v5, v5
	v_add3_u32 v8, v24, v25, s68
	global_store_short_d16_hi v[26:27], v8, off offset:1216
	v_lshl_add_u64 v[8:9], v[32:33], 0, v[76:77]
	v_mul_f32_e32 v20, 0x45800000, v5
	v_cndmask_b32_e32 v5, v5, v20, vcc
	v_mul_f32_e32 v5, 0x3f4ccccd, v5
	v_mul_f32_e32 v18, v18, v5
	v_mul_f32_e32 v18, v163, v18
	v_bfe_u32 v20, v18, 16, 1
	v_add3_u32 v18, v18, v20, s68
	global_store_short_d16_hi v[8:9], v18, off offset:1024
	v_mul_f32_e32 v18, v19, v5
	v_mul_f32_e32 v18, v162, v18
	v_bfe_u32 v19, v18, 16, 1
	v_add3_u32 v18, v18, v19, s68
	global_store_short_d16_hi v[8:9], v18, off offset:1088
	v_mul_f32_e32 v18, v23, v5
	v_mul_f32_e32 v18, v161, v18
	v_bfe_u32 v19, v18, 16, 1
	v_add3_u32 v18, v18, v19, s68
	global_store_short_d16_hi v[8:9], v18, off offset:1152
	v_mul_f32_e32 v18, 0x4b800000, v4
	v_cmp_gt_f32_e32 vcc, s67, v4
	v_mul_f32_e32 v5, v22, v5
	v_mul_f32_e32 v5, v130, v5
	v_cndmask_b32_e32 v4, v4, v18, vcc
	v_rsq_f32_e32 v4, v4
	v_bfe_u32 v18, v5, 16, 1
	v_add3_u32 v5, v5, v18, s68
	global_store_short_d16_hi v[8:9], v5, off offset:1216
	v_mul_f32_e32 v5, 0x45800000, v4
	v_cndmask_b32_e32 v34, v4, v5, vcc
	v_mov_b32_e32 v4, v12
	v_mov_b32_e32 v5, v60
	v_mov_b32_e32 v18, v44
	v_mov_b32_e32 v19, v28
	v_pk_mul_f32 v[4:5], v[4:5], v[0:1] op_sel_hi:[1,0]
	v_pk_mul_f32 v[18:19], v[18:19], v[0:1] op_sel_hi:[1,0]
	v_rcp_f32_e32 v0, v1
	v_mov_b32_e32 v60, v13
	v_mov_b32_e32 v28, v45
	s_waitcnt vmcnt(58)
	v_pk_fma_f32 v[4:5], v[128:129], v[4:5], v[116:117] neg_lo:[1,0,0] neg_hi:[1,0,0]
	v_pk_mul_f32 v[12:13], v[60:61], v[0:1] op_sel_hi:[1,0]
	v_pk_mul_f32 v[0:1], v[28:29], v[0:1] op_sel_hi:[1,0]
	s_waitcnt vmcnt(54)
	v_pk_fma_f32 v[12:13], v[128:129], v[12:13], v[112:113] neg_lo:[1,0,0] neg_hi:[1,0,0]
	v_pk_mul_f32 v[8:9], v[4:5], v[4:5]
	v_pk_fma_f32 v[18:19], v[128:129], v[18:19], v[114:115] neg_lo:[1,0,0] neg_hi:[1,0,0]
	v_pk_mul_f32 v[22:23], v[12:13], v[12:13]
	s_waitcnt vmcnt(52)
	v_pk_fma_f32 v[0:1], v[128:129], v[0:1], v[110:111] neg_lo:[1,0,0] neg_hi:[1,0,0]
	v_pk_mul_f32 v[20:21], v[18:19], v[18:19]
	v_pk_mul_f32 v[24:25], v[0:1], v[0:1]
	v_mov_b32_e32 v26, v22
	v_mov_b32_e32 v27, v8
	v_mov_b32_e32 v8, v23
	v_pk_add_f32 v[8:9], v[26:27], v[8:9]
	v_mov_b32_e32 v22, v25
	v_mov_b32_e32 v23, v21
	v_pk_add_f32 v[8:9], v[22:23], v[8:9]
	v_mov_b32_e32 v25, v20
	v_pk_add_f32 v[8:9], v[24:25], v[8:9]
	ds_bpermute_b32 v21, v164, v9
	ds_bpermute_b32 v20, v164, v8
	v_mul_f32_e32 v24, 0x3f4ccccd, v34
	v_mul_f32_e32 v10, v10, v24
	v_mul_f32_e32 v10, v163, v10
	v_bfe_u32 v25, v10, 16, 1
	s_waitcnt lgkmcnt(0)
	v_pk_add_f32 v[8:9], v[8:9], v[20:21]
	ds_bpermute_b32 v21, v165, v9
	ds_bpermute_b32 v20, v165, v8
	v_lshl_add_u64 v[22:23], v[32:33], 0, v[72:73]
	v_add3_u32 v10, v10, v25, s68
	global_store_short_d16_hi v[22:23], v10, off offset:1024
	v_mul_f32_e32 v25, v11, v24
	s_waitcnt lgkmcnt(0)
	v_pk_add_f32 v[8:9], v[8:9], v[20:21]
	ds_bpermute_b32 v11, v168, v9
	ds_bpermute_b32 v10, v168, v8
	v_mul_f32_e32 v20, v162, v25
	v_bfe_u32 v21, v20, 16, 1
	v_mul_f32_e32 v7, v7, v24
	v_add3_u32 v20, v20, v21, s68
	s_waitcnt lgkmcnt(0)
	v_pk_add_f32 v[8:9], v[8:9], v[10:11]
	ds_bpermute_b32 v11, v167, v9
	ds_bpermute_b32 v10, v167, v8
	v_mul_f32_e32 v7, v161, v7
	global_store_short_d16_hi v[22:23], v20, off offset:1088
	v_bfe_u32 v20, v7, 16, 1
	v_add3_u32 v7, v7, v20, s68
	s_waitcnt lgkmcnt(0)
	v_pk_add_f32 v[8:9], v[8:9], v[10:11]
	ds_bpermute_b32 v11, v166, v9
	ds_bpermute_b32 v10, v166, v8
	v_mul_f32_e32 v6, v6, v24
	global_store_short_d16_hi v[22:23], v7, off offset:1152
	v_mul_f32_e32 v20, v130, v6
	v_bfe_u32 v21, v20, 16, 1
	s_waitcnt lgkmcnt(0)
; DI unsigned short f2bf(float x) { unsigned u = __float_as_uint(x); u += 0x7fffu + ((u >> 16) & 1u); return (unsigned short)(u >> 16); }
; DI float shx(float v, int mask, int lane) { return __int_as_float(__builtin_amdgcn_ds_bpermute((lane ^ mask) << 2, __float_as_int(v))); }
; template <int DQK, int MODE, int LDQ, int LDK, int LDV> ...
;     ...
;             float v[4]; float ss = 0.f;
; #pragma unroll
;             for (int d0 = 0; d0 < 4; ++d0) { v[d0] = s0v[r][d0] - lam * (o[d0][r] * rl); ss += v[d0] * v[d0]; }
; #pragma unroll
;             for (int mk = 1; mk <= 16; mk <<= 1) ss += shx(ss, mk, lane2);
;             const float rs = rsqrtf(ss * (1.f / 128.f) + EPS) * 0.8f;
; #pragma unroll
;             for (int d0 = 0; d0 < 4; ++d0) AOb[(size_t)orow * 1024 + d0 * 32 + r32] = f2bf(v[d0] * rs * gout[d0 * 32 + r32]);
;         } }
	v_pk_add_f32 v[6:7], v[8:9], v[10:11]
	s_nop 0
	v_pk_fma_f32 v[6:7], v[6:7], s[24:25], v[92:93] op_sel_hi:[1,0,0]
	s_nop 0
	v_mul_f32_e32 v8, 0x4b800000, v7
	v_cmp_gt_f32_e32 vcc, s67, v7
	s_nop 1
	v_cndmask_b32_e32 v7, v7, v8, vcc
	v_rsq_f32_e32 v7, v7
	v_add3_u32 v8, v20, v21, s68
	global_store_short_d16_hi v[22:23], v8, off offset:1216
	v_lshl_add_u64 v[8:9], v[32:33], 0, v[74:75]
	v_mul_f32_e32 v10, 0x45800000, v7
	v_cndmask_b32_e32 v7, v7, v10, vcc
	v_mul_f32_e32 v7, 0x3f4ccccd, v7
	v_mul_f32_e32 v4, v4, v7
	v_mul_f32_e32 v4, v163, v4
	v_bfe_u32 v10, v4, 16, 1
	v_add3_u32 v4, v4, v10, s68
	global_store_short_d16_hi v[8:9], v4, off offset:1024
	v_mul_f32_e32 v4, v5, v7
	v_mul_f32_e32 v4, v162, v4
	v_bfe_u32 v5, v4, 16, 1
	v_add3_u32 v4, v4, v5, s68
	global_store_short_d16_hi v[8:9], v4, off offset:1088
	v_mul_f32_e32 v4, v19, v7
	v_mul_f32_e32 v4, v161, v4
	v_bfe_u32 v5, v4, 16, 1
	v_add3_u32 v4, v4, v5, s68
	v_mul_f32_e32 v5, 0x4b800000, v6
	v_cmp_gt_f32_e32 vcc, s67, v6
	global_store_short_d16_hi v[8:9], v4, off offset:1152
	v_mul_f32_e32 v4, v18, v7
	v_cndmask_b32_e32 v5, v6, v5, vcc
	v_rsq_f32_e32 v5, v5
	v_mul_f32_e32 v4, v130, v4
	v_bfe_u32 v6, v4, 16, 1
	v_add3_u32 v4, v4, v6, s68
	global_store_short_d16_hi v[8:9], v4, off offset:1216
	v_mul_f32_e32 v4, 0x45800000, v5
	v_cndmask_b32_e32 v24, v5, v4, vcc
	v_mov_b32_e32 v4, v14
	v_mov_b32_e32 v5, v62
	v_mov_b32_e32 v8, v46
	v_mov_b32_e32 v9, v30
	v_pk_mul_f32 v[4:5], v[4:5], v[2:3] op_sel_hi:[1,0]
	v_pk_mul_f32 v[8:9], v[8:9], v[2:3] op_sel_hi:[1,0]
	v_rcp_f32_e32 v2, v3
	v_mov_b32_e32 v62, v15
	v_mov_b32_e32 v30, v47
	s_waitcnt vmcnt(58)
	v_pk_fma_f32 v[4:5], v[128:129], v[4:5], v[108:109] neg_lo:[1,0,0] neg_hi:[1,0,0]
	v_pk_mul_f32 v[14:15], v[62:63], v[2:3] op_sel_hi:[1,0]
	v_pk_mul_f32 v[2:3], v[30:31], v[2:3] op_sel_hi:[1,0]
	s_waitcnt vmcnt(54)
	v_pk_fma_f32 v[14:15], v[128:129], v[14:15], v[104:105] neg_lo:[1,0,0] neg_hi:[1,0,0]
	v_pk_mul_f32 v[6:7], v[4:5], v[4:5]
	v_pk_fma_f32 v[8:9], v[128:129], v[8:9], v[106:107] neg_lo:[1,0,0] neg_hi:[1,0,0]
	v_pk_mul_f32 v[18:19], v[14:15], v[14:15]
	s_waitcnt vmcnt(52)
	v_pk_fma_f32 v[2:3], v[128:129], v[2:3], v[102:103] neg_lo:[1,0,0] neg_hi:[1,0,0]
	v_pk_mul_f32 v[10:11], v[8:9], v[8:9]
	v_pk_mul_f32 v[20:21], v[2:3], v[2:3]
	v_mov_b32_e32 v22, v18
	v_mov_b32_e32 v23, v6
	v_mov_b32_e32 v6, v19
	v_pk_add_f32 v[6:7], v[22:23], v[6:7]
	v_mov_b32_e32 v18, v21
	v_mov_b32_e32 v19, v11
	v_pk_add_f32 v[6:7], v[18:19], v[6:7]
	v_mov_b32_e32 v21, v10
	v_pk_add_f32 v[6:7], v[20:21], v[6:7]
	ds_bpermute_b32 v11, v164, v7
	ds_bpermute_b32 v10, v164, v6
	v_mul_f32_e32 v20, 0x3f4ccccd, v24
	v_mul_f32_e32 v12, v12, v20
	v_mul_f32_e32 v12, v163, v12
	v_bfe_u32 v21, v12, 16, 1
	s_waitcnt lgkmcnt(0)
	v_pk_add_f32 v[6:7], v[6:7], v[10:11]
	ds_bpermute_b32 v11, v165, v7
	ds_bpermute_b32 v10, v165, v6
	v_lshl_add_u64 v[18:19], v[32:33], 0, v[64:65]
	v_add3_u32 v12, v12, v21, s68
	global_store_short_d16_hi v[18:19], v12, off offset:1024
	v_mul_f32_e32 v12, v13, v20
	s_waitcnt lgkmcnt(0)
	v_pk_add_f32 v[6:7], v[6:7], v[10:11]
	ds_bpermute_b32 v11, v168, v7
	ds_bpermute_b32 v10, v168, v6
	v_mul_f32_e32 v12, v162, v12
	v_bfe_u32 v13, v12, 16, 1
	v_mul_f32_e32 v1, v1, v20
	v_add3_u32 v12, v12, v13, s68
	s_waitcnt lgkmcnt(0)
	v_pk_add_f32 v[6:7], v[6:7], v[10:11]
	ds_bpermute_b32 v11, v167, v7
	ds_bpermute_b32 v10, v167, v6
	v_mul_f32_e32 v1, v161, v1
	global_store_short_d16_hi v[18:19], v12, off offset:1088
	v_bfe_u32 v12, v1, 16, 1
	v_add3_u32 v1, v1, v12, s68
	s_waitcnt lgkmcnt(0)
	v_pk_add_f32 v[6:7], v[6:7], v[10:11]
	ds_bpermute_b32 v11, v166, v7
	ds_bpermute_b32 v10, v166, v6
	v_mul_f32_e32 v0, v0, v20
	global_store_short_d16_hi v[18:19], v1, off offset:1152
	v_mul_f32_e32 v12, v130, v0
	v_bfe_u32 v13, v12, 16, 1
	s_waitcnt lgkmcnt(0)
	v_pk_add_f32 v[0:1], v[6:7], v[10:11]
	s_nop 0
	v_pk_fma_f32 v[0:1], v[0:1], s[24:25], v[92:93] op_sel_hi:[1,0,0]
	s_nop 0
	v_mul_f32_e32 v6, 0x4b800000, v1
	v_cmp_gt_f32_e32 vcc, s67, v1
	s_nop 1
	v_cndmask_b32_e32 v1, v1, v6, vcc
	v_rsq_f32_e32 v1, v1
	v_add3_u32 v6, v12, v13, s68
	global_store_short_d16_hi v[18:19], v6, off offset:1216
	v_lshl_add_u64 v[6:7], v[32:33], 0, v[48:49]
	v_mul_f32_e32 v10, 0x45800000, v1
	v_cndmask_b32_e32 v1, v1, v10, vcc
	v_mul_f32_e32 v1, 0x3f4ccccd, v1
	v_mul_f32_e32 v4, v4, v1
	v_mul_f32_e32 v4, v163, v4
	v_bfe_u32 v10, v4, 16, 1
	v_add3_u32 v4, v4, v10, s68
	global_store_short_d16_hi v[6:7], v4, off offset:1024
	v_mul_f32_e32 v4, v5, v1
	v_mul_f32_e32 v4, v162, v4
	v_bfe_u32 v5, v4, 16, 1
	v_add3_u32 v4, v4, v5, s68
	global_store_short_d16_hi v[6:7], v4, off offset:1088
	v_mul_f32_e32 v4, v9, v1
	v_mul_f32_e32 v4, v161, v4
	v_bfe_u32 v5, v4, 16, 1
	v_add3_u32 v4, v4, v5, s68
	global_store_short_d16_hi v[6:7], v4, off offset:1152
	v_mul_f32_e32 v4, 0x4b800000, v0
	v_cmp_gt_f32_e32 vcc, s67, v0
	v_mul_f32_e32 v1, v8, v1
	v_mul_f32_e32 v1, v130, v1
	v_cndmask_b32_e32 v0, v0, v4, vcc
	v_rsq_f32_e32 v0, v0
	v_bfe_u32 v4, v1, 16, 1
	v_add3_u32 v1, v1, v4, s68
	global_store_short_d16_hi v[6:7], v1, off offset:1216
	v_mul_f32_e32 v1, 0x45800000, v0
	v_cndmask_b32_e32 v0, v0, v1, vcc
	v_mul_f32_e32 v4, 0x3f4ccccd, v0
	v_mul_f32_e32 v5, v14, v4
	v_mul_f32_e32 v5, v163, v5
	v_bfe_u32 v6, v5, 16, 1
	v_lshl_add_u64 v[0:1], v[32:33], 0, v[16:17]
	v_add3_u32 v5, v5, v6, s68
	global_store_short_d16_hi v[0:1], v5, off offset:1024
	v_mul_f32_e32 v5, v15, v4
	v_mul_f32_e32 v5, v162, v5
	v_bfe_u32 v6, v5, 16, 1
	v_mul_f32_e32 v3, v3, v4
	v_add3_u32 v5, v5, v6, s68
	v_mul_f32_e32 v3, v161, v3
	global_store_short_d16_hi v[0:1], v5, off offset:1088
	v_bfe_u32 v5, v3, 16, 1
	v_mul_f32_e32 v2, v2, v4
	v_add3_u32 v3, v3, v5, s68
	v_mul_f32_e32 v2, v130, v2
	global_store_short_d16_hi v[0:1], v3, off offset:1152
	v_bfe_u32 v3, v2, 16, 1
	v_add3_u32 v2, v2, v3, s68
	global_store_short_d16_hi v[0:1], v2, off offset:1216
	s_waitcnt vmcnt(63) expcnt(7) lgkmcnt(15)
	s_barrier

; #define SBAR() __builtin_amdgcn_sched_barrier(0)
; #define ATT_DMA_K(t) do { const bf16_t* kg_ = Kh + (size_t)(t) * 64 * LDK; LAS unsigned char* sb_ = lds + ((t) & 3) * KBUF; \
;     _Pragma("unroll") for (int i_ = 0; i_ < NKP; ++i_) __builtin_amdgcn_global_load_lds((const unsigned*)(kg_ + kgo[i_]), (LAS unsigned*)(sb_ + (wid + 8 * i_) * 1024), 16, 0, 0); } while (0)
; #define ATT_DMA_V(t, vs) do { const bf16_t* vg_ = Vh + (size_t)(t) * 64 * LDV; LAS unsigned char* sb_ = lds + V_OFF + (vs) * SHM_V; \
;     _Pragma("unroll") for (int i_ = 0; i_ < 2; ++i_) __builtin_amdgcn_global_load_lds((const unsigned*)(vg_ + vgo[i_]), (LAS unsigned*)(sb_ + (2 * wid + i_) * 1024), 16, 0, 0); } while (0)
; #define ATT_SEG(t) do { if constexpr (MODE != 0) { if (((t) == tL && tL > 0) || (t) == tR) { const float f_ = (t) == tR ? fR : fL; l_reg *= f_; \
;     _Pragma("unroll") for (int d = 0; d < 4; ++d) _Pragma("unroll") for (int r = 0; r < 16; ++r) o[d][r] *= f_; } } } while (0)
; #define ATT_BIAS(P, t, half) do { if constexpr (MODE != 0) { if ((t) >= tL && (t) < tR) { const LAS float* bp_ = bt + ((t) * 64 + (half) * 32 - qpos + 224 + 4 * hi);     \
;     _Pragma("unroll") for (int r = 0; r < 16; ++r) P[r] += bp_[(r & 3) + 8 * (r >> 2)]; } } } while (0)
; #define ATT_TOP(N) do { asm volatile("s_waitcnt vmcnt(%0)" :: "n"(N) : "memory"); __builtin_amdgcn_s_barrier(); asm volatile("" ::: "memory"); } while (0)
; #define ATT_LGKM0() do { SBAR(); asm volatile("s_waitcnt lgkmcnt(0)" ::: "memory"); SBAR(); } while (0)
; template <int DQK, int MODE, int LDQ, int LDK, int LDV> ...
;     ...
;     f32x16 pA, pB; bf16x8 pa0, pa1;
;     int v0 = 0, v1 = 1, v2 = 2;
;     ATT_TOP(NKP + 2);
;     { bf16x8 kf[NDA]; k_reads<DQK, 0, NDA>(kf, lds, 0, r32, hi); ATT_LGKM0(); qk_mma<0, NDA>(pA, kf, qr);
;       if constexpr (ND0 > NDA) { bf16x8 kg[ND0 - NDA]; k_reads<DQK, NDA, ND0>(kg, lds, 0, r32, hi); ATT_LGKM0(); qk_mma<NDA, ND0>(pA, kg, qr); }
;       ATT_BIAS(pA, 0, 0); }
;     if (wid >= 4) __builtin_amdgcn_s_setprio(1);
;     for (int j = 0; j < NT; ++j) {
;         if (j + 2 < NT) ATT_TOP(NKP + 2); else ATT_TOP(0);
;         if (j + 3 < NT) ATT_DMA_K(j + 3);
;         if (j + 2 < NT) ATT_DMA_V(j + 2, v2);
;         ATT_SEG(j); SBAR();
;         ATT_STEP(pA, pB, 0, v0, true, 1, j);
.Lstg_mla_top_2:
	s_setprio 1
	s_mov_b32 m0, s1
	s_mov_b32 s0, s5
	s_mov_b32 s5, s44
	s_mov_b32 s44, s4
	s_lshl_b32 s4, s4, 14
	global_load_lds_dwordx4 v136, s[34:35]
	s_add_i32 m0, s1, 0x2000
	s_add_i32 s4, s52, s4
	global_load_lds_dwordx4 v138, s[34:35]
	s_add_i32 m0, s1, 0x4000
	s_add_i32 s6, s4, 0x400
	global_load_lds_dwordx4 v140, s[34:35]
	s_mov_b32 m0, s4
	s_add_i32 s1, s43, -3
	global_load_lds_dwordx4 v144, s[34:35]
	s_mov_b32 m0, s6
	s_nop 0
	global_load_lds_dwordx4 v142, s[34:35]
	s_and_b32 s1, s1, 3
	s_mulk_i32 s1, 0x6000
	v_add_u32_e32 v246, s1, v158
	v_add_u32_e32 v174, v246, v151
	v_add_u32_e32 v178, v246, v149
	v_add_u32_e32 v182, v246, v148
	v_add_u32_e32 v186, v246, v147
	v_add_u32_e32 v190, v246, v146
	v_add_u32_e32 v194, v246, v150
	s_lshl_b32 s1, s0, 14
	ds_read_b128 v[174:177], v174 offset:12288
	ds_read_b128 v[178:181], v178 offset:12288
	ds_read_b128 v[182:185], v182 offset:12288
	ds_read_b128 v[186:189], v186 offset:12288
	ds_read_b128 v[190:193], v190 offset:12288
	ds_read_b128 v[194:197], v194 offset:12288
	v_add_u32_e32 v254, s1, v130
	ds_read_b64_tr_b16 v[198:199], v254 offset:0
	ds_read_b64_tr_b16 v[200:201], v254 offset:0x800
	ds_read_b64_tr_b16 v[202:203], v254 offset:0x1000
	ds_read_b64_tr_b16 v[204:205], v254 offset:0x1800
	ds_read_b64_tr_b16 v[206:207], v254 offset:0x200
	ds_read_b64_tr_b16 v[208:209], v254 offset:0xa00
	ds_read_b64_tr_b16 v[210:211], v254 offset:0x1200
	ds_read_b64_tr_b16 v[212:213], v254 offset:0x1a00
	ds_read_b64_tr_b16 v[214:215], v254 offset:0x400
	ds_read_b64_tr_b16 v[216:217], v254 offset:0xc00
	ds_read_b64_tr_b16 v[218:219], v254 offset:0x1400
	ds_read_b64_tr_b16 v[220:221], v254 offset:0x1c00
	ds_read_b64_tr_b16 v[222:223], v254 offset:0x600
	ds_read_b64_tr_b16 v[224:225], v254 offset:0xe00
	ds_read_b64_tr_b16 v[226:227], v254 offset:0x1600
	ds_read_b64_tr_b16 v[228:229], v254 offset:0x1e00
	v_exp_f32_e32 v64, v64
	v_exp_f32_e32 v65, v65
	v_exp_f32_e32 v66, v66
	v_exp_f32_e32 v67, v67
	v_exp_f32_e32 v68, v68
	v_add_f32_e32 v230, 0, v64
	v_exp_f32_e32 v69, v69
	v_add_f32_e32 v230, v65, v230
	v_exp_f32_e32 v70, v70
	v_add_f32_e32 v230, v66, v230
	v_exp_f32_e32 v71, v71
	v_add_f32_e32 v230, v67, v230
	v_exp_f32_e32 v72, v72
	v_add_f32_e32 v230, v68, v230
	v_exp_f32_e32 v73, v73
	v_add_f32_e32 v230, v69, v230
	v_exp_f32_e32 v74, v74
	v_add_f32_e32 v230, v70, v230
	v_exp_f32_e32 v75, v75
	v_add_f32_e32 v230, v71, v230
	v_exp_f32_e32 v76, v76
	v_add_f32_e32 v230, v72, v230
	v_exp_f32_e32 v77, v77
	v_add_f32_e32 v230, v73, v230
	v_exp_f32_e32 v78, v78
	v_add_f32_e32 v230, v74, v230
	v_exp_f32_e32 v79, v79
	v_add_f32_e32 v230, v75, v230
	v_add_f32_e32 v230, v76, v230
	v_add_f32_e32 v230, v77, v230
	v_add_f32_e32 v230, v78, v230
	v_add_f32_e32 v230, v79, v230
	v_add_f32_e32 v173, v173, v230
	v_cvt_pk_bf16_f32 v64, v64, v65
	v_cvt_pk_bf16_f32 v65, v66, v67
	v_cvt_pk_bf16_f32 v66, v68, v69
	v_cvt_pk_bf16_f32 v67, v70, v71
	v_cvt_pk_bf16_f32 v68, v72, v73
	v_cvt_pk_bf16_f32 v69, v74, v75
	v_cvt_pk_bf16_f32 v70, v76, v77
	v_cvt_pk_bf16_f32 v71, v78, v79
	s_nop 0
	v_permlane32_swap_b32_e32 v64, v66
	v_permlane32_swap_b32_e32 v65, v67
	v_permlane32_swap_b32_e32 v68, v70
	v_permlane32_swap_b32_e32 v69, v71
	s_waitcnt lgkmcnt(0)
	v_add_u32_e32 v72, v246, v152
	v_add_u32_e32 v73, v246, v153
	ds_read_b128 v[230:233], v72 offset:12288
	ds_read_b128 v[234:237], v73 offset:12288
	v_add_u32_e32 v72, v246, v154
	v_add_u32_e32 v73, v246, v155
	ds_read_b128 v[238:241], v72 offset:12288
	ds_read_b128 v[242:245], v73 offset:12288
	v_add_u32_e32 v72, v246, v156
	v_add_u32_e32 v73, v246, v157
	ds_read_b128 v[246:249], v72 offset:12288
	ds_read_b128 v[250:253], v73 offset:12288
	s_setprio 0
	v_mfma_f32_32x32x16_bf16 v[48:63], v[64:67], v[198:201], v[48:63]
	v_mfma_f32_32x32x16_bf16 v[32:47], v[64:67], v[206:209], v[32:47]
	v_mfma_f32_32x32x16_bf16 v[16:31], v[64:67], v[214:217], v[16:31]
	v_mfma_f32_32x32x16_bf16 v[0:15], v[64:67], v[222:225], v[0:15]
	v_mfma_f32_32x32x16_bf16 v[48:63], v[68:71], v[202:205], v[48:63]
	v_mfma_f32_32x32x16_bf16 v[32:47], v[68:71], v[210:213], v[32:47]
	v_mfma_f32_32x32x16_bf16 v[16:31], v[68:71], v[218:221], v[16:31]
	v_mfma_f32_32x32x16_bf16 v[0:15], v[68:71], v[226:229], v[0:15]
	s_waitcnt lgkmcnt(0)
; #define SBAR() __builtin_amdgcn_sched_barrier(0)
; #define ATT_DMA_K(t) do { const bf16_t* kg_ = Kh + (size_t)(t) * 64 * LDK; LAS unsigned char* sb_ = lds + ((t) & 3) * KBUF; \
;     _Pragma("unroll") for (int i_ = 0; i_ < NKP; ++i_) __builtin_amdgcn_global_load_lds((const unsigned*)(kg_ + kgo[i_]), (LAS unsigned*)(sb_ + (wid + 8 * i_) * 1024), 16, 0, 0); } while (0)
; #define ATT_DMA_V(t, vs) do { const bf16_t* vg_ = Vh + (size_t)(t) * 64 * LDV; LAS unsigned char* sb_ = lds + V_OFF + (vs) * SHM_V; \
;     _Pragma("unroll") for (int i_ = 0; i_ < 2; ++i_) __builtin_amdgcn_global_load_lds((const unsigned*)(vg_ + vgo[i_]), (LAS unsigned*)(sb_ + (2 * wid + i_) * 1024), 16, 0, 0); } while (0)
; #define ATT_SEG(t) do { if constexpr (MODE != 0) { if (((t) == tL && tL > 0) || (t) == tR) { const float f_ = (t) == tR ? fR : fL; l_reg *= f_; \
;     _Pragma("unroll") for (int d = 0; d < 4; ++d) _Pragma("unroll") for (int r = 0; r < 16; ++r) o[d][r] *= f_; } } } while (0)
; #define ATT_TOP(N) do { asm volatile("s_waitcnt vmcnt(%0)" :: "n"(N) : "memory"); __builtin_amdgcn_s_barrier(); asm volatile("" ::: "memory"); } while (0)
; template <int D0A, int D0B> DI void qk_mma(f32x16& p, const bf16x8* kf, const bf16x8* qr) {
; #pragma unroll
;     for (int d0 = D0A; d0 < D0B; ++d0) {
;         if (d0 == 0) { f32x16 z; _Pragma("unroll") for (int r = 0; r < 16; ++r) z[r] = 0.f; p = __builtin_amdgcn_mfma_f32_32x32x16_bf16(kf[0], qr[0], z, 0, 0, 0); }
;         else p = __builtin_amdgcn_mfma_f32_32x32x16_bf16(kf[d0 - D0A], qr[d0], p, 0, 0, 0); }
; }
; template <int DQK, int MODE, int LDQ, int LDK, int LDV> ...
;     ...
;     f32x16 pA, pB; bf16x8 pa0, pa1;
;     int v0 = 0, v1 = 1, v2 = 2;
;     ATT_TOP(NKP + 2);
;     { bf16x8 kf[NDA]; k_reads<DQK, 0, NDA>(kf, lds, 0, r32, hi); ATT_LGKM0(); qk_mma<0, NDA>(pA, kf, qr);
;       if constexpr (ND0 > NDA) { bf16x8 kg[ND0 - NDA]; k_reads<DQK, NDA, ND0>(kg, lds, 0, r32, hi); ATT_LGKM0(); qk_mma<NDA, ND0>(pA, kg, qr); }
;       ATT_BIAS(pA, 0, 0); }
;     if (wid >= 4) __builtin_amdgcn_s_setprio(1);
;     for (int j = 0; j < NT; ++j) {
;         if (j + 2 < NT) ATT_TOP(NKP + 2); else ATT_TOP(0);
;         if (j + 3 < NT) ATT_DMA_K(j + 3);
;         if (j + 2 < NT) ATT_DMA_V(j + 2, v2);
;         ATT_SEG(j); SBAR();
;         ATT_STEP(pA, pB, 0, v0, true, 1, j);
;         ATT_STEP(pB, pA, 1, v0, (j + 1 < NT), 0, j + 1);
	v_mfma_f32_32x32x16_bf16 v[64:79], v[174:177], v[80:83], 0
	v_mfma_f32_32x32x16_bf16 v[64:79], v[178:181], v[84:87], v[64:79]
	v_mfma_f32_32x32x16_bf16 v[64:79], v[182:185], v[88:91], v[64:79]
	v_mfma_f32_32x32x16_bf16 v[64:79], v[186:189], v[92:95], v[64:79]
	v_mfma_f32_32x32x16_bf16 v[64:79], v[190:193], v[96:99], v[64:79]
	v_mfma_f32_32x32x16_bf16 v[64:79], v[194:197], v[100:103], v[64:79]
	v_mfma_f32_32x32x16_bf16 v[64:79], v[230:233], v[104:107], v[64:79]
	v_mfma_f32_32x32x16_bf16 v[64:79], v[234:237], v[108:111], v[64:79]
	v_mfma_f32_32x32x16_bf16 v[64:79], v[238:241], v[112:115], v[64:79]
	v_mfma_f32_32x32x16_bf16 v[64:79], v[242:245], v[116:119], v[64:79]
	v_mfma_f32_32x32x16_bf16 v[64:79], v[246:249], v[120:123], v[64:79]
	v_mfma_f32_32x32x16_bf16 v[64:79], v[250:253], v[124:127], v[64:79]
	s_setprio 1
	s_add_i32 s4, s43, -2
	s_and_b32 s4, s4, 3
	s_mulk_i32 s4, 0x6000
	v_add_u32_e32 v246, s4, v158
	v_add_u32_e32 v174, v246, v151
	v_add_u32_e32 v178, v246, v149
	v_add_u32_e32 v182, v246, v148
	v_add_u32_e32 v186, v246, v147
	v_add_u32_e32 v190, v246, v146
	v_add_u32_e32 v194, v246, v150
	ds_read_b128 v[174:177], v174
	ds_read_b128 v[178:181], v178
	ds_read_b128 v[182:185], v182
	ds_read_b128 v[186:189], v186
	ds_read_b128 v[190:193], v190
	ds_read_b128 v[194:197], v194
	ds_read_b64_tr_b16 v[198:199], v254 offset:0x2000
	ds_read_b64_tr_b16 v[200:201], v254 offset:0x2800
	ds_read_b64_tr_b16 v[202:203], v254 offset:0x3000
	ds_read_b64_tr_b16 v[204:205], v254 offset:0x3800
	ds_read_b64_tr_b16 v[206:207], v254 offset:0x2200
	ds_read_b64_tr_b16 v[208:209], v254 offset:0x2a00
	ds_read_b64_tr_b16 v[210:211], v254 offset:0x3200
	ds_read_b64_tr_b16 v[212:213], v254 offset:0x3a00
	ds_read_b64_tr_b16 v[214:215], v254 offset:0x2400
	ds_read_b64_tr_b16 v[216:217], v254 offset:0x2c00
	ds_read_b64_tr_b16 v[218:219], v254 offset:0x3400
	ds_read_b64_tr_b16 v[220:221], v254 offset:0x3c00
	ds_read_b64_tr_b16 v[222:223], v254 offset:0x2600
	ds_read_b64_tr_b16 v[224:225], v254 offset:0x2e00
	ds_read_b64_tr_b16 v[226:227], v254 offset:0x3600
	ds_read_b64_tr_b16 v[228:229], v254 offset:0x3e00
	v_exp_f32_e32 v64, v64
	v_exp_f32_e32 v65, v65
	v_exp_f32_e32 v66, v66
	v_exp_f32_e32 v67, v67
	v_exp_f32_e32 v68, v68
	v_add_f32_e32 v230, 0, v64
	v_exp_f32_e32 v69, v69
	v_add_f32_e32 v230, v65, v230
	v_exp_f32_e32 v70, v70
	v_add_f32_e32 v230, v66, v230
	v_exp_f32_e32 v71, v71
	v_add_f32_e32 v230, v67, v230
	v_exp_f32_e32 v72, v72
	v_add_f32_e32 v230, v68, v230
	v_exp_f32_e32 v73, v73
	v_add_f32_e32 v230, v69, v230
	v_exp_f32_e32 v74, v74
	v_add_f32_e32 v230, v70, v230
	v_exp_f32_e32 v75, v75
	v_add_f32_e32 v230, v71, v230
	v_exp_f32_e32 v76, v76
	v_add_f32_e32 v230, v72, v230
	v_exp_f32_e32 v77, v77
	v_add_f32_e32 v230, v73, v230
	v_exp_f32_e32 v78, v78
	v_add_f32_e32 v230, v74, v230
	v_exp_f32_e32 v79, v79
	v_add_f32_e32 v230, v75, v230
	v_add_f32_e32 v230, v76, v230
	v_add_f32_e32 v230, v77, v230
	v_add_f32_e32 v230, v78, v230
	v_add_f32_e32 v230, v79, v230
	v_add_f32_e32 v173, v173, v230
	v_cvt_pk_bf16_f32 v64, v64, v65
	v_cvt_pk_bf16_f32 v65, v66, v67
	v_cvt_pk_bf16_f32 v66, v68, v69
	v_cvt_pk_bf16_f32 v67, v70, v71
	v_cvt_pk_bf16_f32 v68, v72, v73
	v_cvt_pk_bf16_f32 v69, v74, v75
	v_cvt_pk_bf16_f32 v70, v76, v77
	v_cvt_pk_bf16_f32 v71, v78, v79
	s_nop 0
	v_permlane32_swap_b32_e32 v64, v66
	v_permlane32_swap_b32_e32 v65, v67
	v_permlane32_swap_b32_e32 v68, v70
	v_permlane32_swap_b32_e32 v69, v71
	s_waitcnt lgkmcnt(0)
	v_add_u32_e32 v72, v246, v152
	v_add_u32_e32 v73, v246, v153
	ds_read_b128 v[230:233], v72
	ds_read_b128 v[234:237], v73
	v_add_u32_e32 v72, v246, v154
	v_add_u32_e32 v73, v246, v155
	ds_read_b128 v[238:241], v72
	ds_read_b128 v[242:245], v73
	v_add_u32_e32 v72, v246, v156
	v_add_u32_e32 v73, v246, v157
	ds_read_b128 v[246:249], v72
	ds_read_b128 v[250:253], v73
	s_setprio 0
	s_cmp_lt_u32 s33, 0x100
	s_cbranch_scc1 .Lstg_mla_mid_3
	s_waitcnt vmcnt(5)
	s_barrier

; #define SBAR() __builtin_amdgcn_sched_barrier(0)
; #define ATT_DMA_K(t) do { const bf16_t* kg_ = Kh + (size_t)(t) * 64 * LDK; LAS unsigned char* sb_ = lds + ((t) & 3) * KBUF; \
;     _Pragma("unroll") for (int i_ = 0; i_ < NKP; ++i_) __builtin_amdgcn_global_load_lds((const unsigned*)(kg_ + kgo[i_]), (LAS unsigned*)(sb_ + (wid + 8 * i_) * 1024), 16, 0, 0); } while (0)
; #define ATT_DMA_V(t, vs) do { const bf16_t* vg_ = Vh + (size_t)(t) * 64 * LDV; LAS unsigned char* sb_ = lds + V_OFF + (vs) * SHM_V; \
;     _Pragma("unroll") for (int i_ = 0; i_ < 2; ++i_) __builtin_amdgcn_global_load_lds((const unsigned*)(vg_ + vgo[i_]), (LAS unsigned*)(sb_ + (2 * wid + i_) * 1024), 16, 0, 0); } while (0)
; #define ATT_SEG(t) do { if constexpr (MODE != 0) { if (((t) == tL && tL > 0) || (t) == tR) { const float f_ = (t) == tR ? fR : fL; l_reg *= f_; \
;     _Pragma("unroll") for (int d = 0; d < 4; ++d) _Pragma("unroll") for (int r = 0; r < 16; ++r) o[d][r] *= f_; } } } while (0)
; #define ATT_BIAS(P, t, half) do { if constexpr (MODE != 0) { if ((t) >= tL && (t) < tR) { const LAS float* bp_ = bt + ((t) * 64 + (half) * 32 - qpos + 224 + 4 * hi);     \
;     _Pragma("unroll") for (int r = 0; r < 16; ++r) P[r] += bp_[(r & 3) + 8 * (r >> 2)]; } } } while (0)
; #define ATT_TOP(N) do { asm volatile("s_waitcnt vmcnt(%0)" :: "n"(N) : "memory"); __builtin_amdgcn_s_barrier(); asm volatile("" ::: "memory"); } while (0)
; #define ATT_LGKM0() do { SBAR(); asm volatile("s_waitcnt lgkmcnt(0)" ::: "memory"); SBAR(); } while (0)
; template <int DQK, int MODE, int LDQ, int LDK, int LDV> ...
;     ...
;     f32x16 pA, pB; bf16x8 pa0, pa1;
;     int v0 = 0, v1 = 1, v2 = 2;
;     ATT_TOP(NKP + 2);
;     { bf16x8 kf[NDA]; k_reads<DQK, 0, NDA>(kf, lds, 0, r32, hi); ATT_LGKM0(); qk_mma<0, NDA>(pA, kf, qr);
;       if constexpr (ND0 > NDA) { bf16x8 kg[ND0 - NDA]; k_reads<DQK, NDA, ND0>(kg, lds, 0, r32, hi); ATT_LGKM0(); qk_mma<NDA, ND0>(pA, kg, qr); }
;       ATT_BIAS(pA, 0, 0); }
;     if (wid >= 4) __builtin_amdgcn_s_setprio(1);
;     for (int j = 0; j < NT; ++j) {
;         if (j + 2 < NT) ATT_TOP(NKP + 2); else ATT_TOP(0);
;         if (j + 3 < NT) ATT_DMA_K(j + 3);
;         if (j + 2 < NT) ATT_DMA_V(j + 2, v2);
;         ATT_SEG(j); SBAR();
;         ATT_STEP(pA, pB, 0, v0, true, 1, j);
.Lstg_mla_t61_4:
	s_setprio 1
	v_lshl_add_u64 v[132:133], v[132:133], 1, s[0:1]
	s_mov_b32 m0, s6
	v_lshl_add_u64 v[134:135], v[134:135], 1, s[0:1]
	global_load_lds_dwordx4 v[132:133], off
	s_mov_b32 m0, s7
	s_nop 0
	global_load_lds_dwordx4 v[134:135], off
	ds_read_b128 v[132:135], v161 offset:36864
	ds_read_b128 v[136:139], v162 offset:36864
	ds_read_b128 v[140:143], v163 offset:36864
	ds_read_b128 v[174:177], v164 offset:36864
	ds_read_b128 v[178:181], v165 offset:36864
	ds_read_b128 v[182:185], v166 offset:36864
	v_lshl_add_u32 v144, s5, 14, v130
	ds_read_b64_tr_b16 v[186:187], v144 offset:0
	ds_read_b64_tr_b16 v[188:189], v144 offset:0x800
	ds_read_b64_tr_b16 v[190:191], v144 offset:0x1000
	ds_read_b64_tr_b16 v[192:193], v144 offset:0x1800
	ds_read_b64_tr_b16 v[194:195], v144 offset:0x200
	ds_read_b64_tr_b16 v[196:197], v144 offset:0xa00
	ds_read_b64_tr_b16 v[198:199], v144 offset:0x1200
	ds_read_b64_tr_b16 v[200:201], v144 offset:0x1a00
	ds_read_b64_tr_b16 v[202:203], v144 offset:0x400
	ds_read_b64_tr_b16 v[204:205], v144 offset:0xc00
	ds_read_b64_tr_b16 v[206:207], v144 offset:0x1400
	ds_read_b64_tr_b16 v[208:209], v144 offset:0x1c00
	ds_read_b64_tr_b16 v[210:211], v144 offset:0x600
	ds_read_b64_tr_b16 v[212:213], v144 offset:0xe00
	ds_read_b64_tr_b16 v[214:215], v144 offset:0x1600
	ds_read_b64_tr_b16 v[216:217], v144 offset:0x1e00
	v_exp_f32_e32 v64, v64
	v_exp_f32_e32 v65, v65
	v_exp_f32_e32 v66, v66
	v_exp_f32_e32 v67, v67
	v_exp_f32_e32 v68, v68
	v_add_f32_e32 v145, 0, v64
	v_exp_f32_e32 v69, v69
	v_add_f32_e32 v145, v65, v145
	v_exp_f32_e32 v70, v70
	v_add_f32_e32 v145, v66, v145
	v_exp_f32_e32 v71, v71
	v_add_f32_e32 v145, v67, v145
	v_exp_f32_e32 v72, v72
	v_add_f32_e32 v145, v68, v145
	v_exp_f32_e32 v73, v73
	v_add_f32_e32 v145, v69, v145
	v_exp_f32_e32 v74, v74
	v_add_f32_e32 v145, v70, v145
	v_exp_f32_e32 v75, v75
	v_add_f32_e32 v145, v71, v145
	v_exp_f32_e32 v76, v76
	v_add_f32_e32 v145, v72, v145
	v_exp_f32_e32 v77, v77
	v_add_f32_e32 v145, v73, v145
	v_exp_f32_e32 v78, v78
	v_add_f32_e32 v145, v74, v145
	v_exp_f32_e32 v79, v79
	v_add_f32_e32 v145, v75, v145
	v_add_f32_e32 v145, v76, v145
	v_add_f32_e32 v145, v77, v145
	v_add_f32_e32 v145, v78, v145
	v_add_f32_e32 v145, v79, v145
	v_add_f32_e32 v145, v173, v145
	v_cvt_pk_bf16_f32 v64, v64, v65
	v_cvt_pk_bf16_f32 v65, v66, v67
	v_cvt_pk_bf16_f32 v66, v68, v69
	v_cvt_pk_bf16_f32 v67, v70, v71
	v_cvt_pk_bf16_f32 v68, v72, v73
	v_cvt_pk_bf16_f32 v69, v74, v75
	v_cvt_pk_bf16_f32 v70, v76, v77
	v_cvt_pk_bf16_f32 v71, v78, v79
	s_nop 0
	v_permlane32_swap_b32_e32 v64, v66
	v_permlane32_swap_b32_e32 v65, v67
	v_permlane32_swap_b32_e32 v68, v70
	v_permlane32_swap_b32_e32 v69, v71
	s_waitcnt lgkmcnt(0)
	ds_read_b128 v[218:221], v167 offset:36864
	ds_read_b128 v[222:225], v168 offset:36864
	ds_read_b128 v[226:229], v169 offset:36864
	ds_read_b128 v[230:233], v170 offset:36864
	ds_read_b128 v[234:237], v171 offset:36864
	ds_read_b128 v[238:241], v172 offset:36864
	s_setprio 0
	v_mfma_f32_32x32x16_bf16 v[48:63], v[64:67], v[186:189], v[48:63]
	v_mfma_f32_32x32x16_bf16 v[32:47], v[64:67], v[194:197], v[32:47]
	v_mfma_f32_32x32x16_bf16 v[16:31], v[64:67], v[202:205], v[16:31]
	v_mfma_f32_32x32x16_bf16 v[0:15], v[64:67], v[210:213], v[0:15]
	v_mfma_f32_32x32x16_bf16 v[48:63], v[68:71], v[190:193], v[48:63]
	v_mfma_f32_32x32x16_bf16 v[32:47], v[68:71], v[198:201], v[32:47]
	v_mfma_f32_32x32x16_bf16 v[16:31], v[68:71], v[206:209], v[16:31]
	v_mfma_f32_32x32x16_bf16 v[0:15], v[68:71], v[214:217], v[0:15]
	s_waitcnt lgkmcnt(0)
; #define LAS __attribute__((address_space(3)))
; DI void expsum(f32x16& p, float& l_reg, bf16x8& pa0, bf16x8& pa1) {
; #pragma unroll
;     for (int r = 0; r < 16; ++r) p[r] = __builtin_amdgcn_exp2f(p[r]);
;     float ps = 0.f;
; #pragma unroll
;     for (int r = 0; r < 16; ++r) ps += p[r];
;     l_reg += ps; asm volatile("" : "+v"(l_reg));
;     ...
;     ATT_PK4(p, 0, pa0); ATT_PK4(p, 8, pa1);
;     ...
; }
; DI int v_rd_base(int lane) { return ((lane & 3) << 3) | (((lane >> 2) & 3) << 6) | (((lane >> 4) & 1) << 5) | (((lane >> 5) & 1) << 8); }
; template <int OFF> DI s16x4 tr_read(int vb) { s16x4 r; asm volatile("ds_read_b64_tr_b16 %0, %1 offset:%2" : "=&v"(r) : "v"(vb), "i"(OFF) : "memory"); return r; }
; template <int H> DI void v_reads(s16x4* vf, int vb) {
;     vf[0] = tr_read<v_rd_off(0, 2 * H, 0)>(vb); vf[1] = tr_read<v_rd_off(0, 2 * H, 1)>(vb); vf[2] = tr_read<v_rd_off(0, 2 * H + 1, 0)>(vb); vf[3] = tr_read<v_rd_off(0, 2 * H + 1, 1)>(vb);
;     vf[4] = tr_read<v_rd_off(1, 2 * H, 0)>(vb); vf[5] = tr_read<v_rd_off(1, 2 * H, 1)>(vb); vf[6] = tr_read<v_rd_off(1, 2 * H + 1, 0)>(vb); vf[7] = tr_read<v_rd_off(1, 2 * H + 1, 1)>(vb);
;     vf[8] = tr_read<v_rd_off(2, 2 * H, 0)>(vb); vf[9] = tr_read<v_rd_off(2, 2 * H, 1)>(vb); vf[10] = tr_read<v_rd_off(2, 2 * H + 1, 0)>(vb); vf[11] = tr_read<v_rd_off(2, 2 * H + 1, 1)>(vb);
;     vf[12] = tr_read<v_rd_off(3, 2 * H, 0)>(vb); vf[13] = tr_read<v_rd_off(3, 2 * H, 1)>(vb); vf[14] = tr_read<v_rd_off(3, 2 * H + 1, 0)>(vb); vf[15] = tr_read<v_rd_off(3, 2 * H + 1, 1)>(vb);
; }
; DI void pv_mma(f32x16* o, const s16x4* vf, bf16x8 pa0, bf16x8 pa1) {
;     ...
; #pragma unroll
;     for (int d0 = 0; d0 < 4; ++d0) {
;         o[d0] = __builtin_amdgcn_mfma_f32_32x32x16_bf16(pa0, ATT_PK(vf[4 * d0], vf[4 * d0 + 1]), o[d0], 0, 0, 0);
;         o[d0] = __builtin_amdgcn_mfma_f32_32x32x16_bf16(pa1, ATT_PK(vf[4 * d0 + 2], vf[4 * d0 + 3]), o[d0], 0, 0, 0); }
;     ...
; }
; template <int DQK, int D0A, int D0B> DI void k_reads(bf16x8* kf, const LAS unsigned char* Ks, int half, int r32, int hi) {
; #pragma unroll
;     for (int d0 = D0A; d0 < D0B; ++d0) kf[d0 - D0A] = *(const LAS bf16x8*)(Ks + half * (32 * DQK * 2) + kswz<DQK>(r32, (d0 * 16 + hi * 8) * 2));
; }
; template <int D0A, int D0B> DI void qk_mma(f32x16& p, const bf16x8* kf, const bf16x8* qr) {
; #pragma unroll
;     for (int d0 = D0A; d0 < D0B; ++d0) {
	v_mfma_f32_32x32x16_bf16 v[64:79], v[132:135], v[80:83], 0
	v_mfma_f32_32x32x16_bf16 v[64:79], v[136:139], v[84:87], v[64:79]
	v_mfma_f32_32x32x16_bf16 v[64:79], v[140:143], v[88:91], v[64:79]
	v_mfma_f32_32x32x16_bf16 v[64:79], v[174:177], v[92:95], v[64:79]
	v_mfma_f32_32x32x16_bf16 v[64:79], v[178:181], v[96:99], v[64:79]
	v_mfma_f32_32x32x16_bf16 v[64:79], v[182:185], v[100:103], v[64:79]
	s_waitcnt lgkmcnt(0)
	v_mfma_f32_32x32x16_bf16 v[64:79], v[218:221], v[104:107], v[64:79]
	v_mfma_f32_32x32x16_bf16 v[64:79], v[222:225], v[108:111], v[64:79]
	v_mfma_f32_32x32x16_bf16 v[64:79], v[226:229], v[112:115], v[64:79]
	v_mfma_f32_32x32x16_bf16 v[64:79], v[230:233], v[116:119], v[64:79]
	v_mfma_f32_32x32x16_bf16 v[64:79], v[234:237], v[120:123], v[64:79]
	v_mfma_f32_32x32x16_bf16 v[64:79], v[238:241], v[124:127], v[64:79]
	s_setprio 1
	ds_read_b128 v[132:135], v161 offset:49152
	ds_read_b128 v[136:139], v162 offset:49152
	ds_read_b128 v[140:143], v163 offset:49152
	ds_read_b128 v[174:177], v164 offset:49152
	ds_read_b128 v[178:181], v165 offset:49152
	ds_read_b128 v[182:185], v166 offset:49152
	ds_read_b64_tr_b16 v[186:187], v144 offset:0x2000
	ds_read_b64_tr_b16 v[188:189], v144 offset:0x2800
	ds_read_b64_tr_b16 v[190:191], v144 offset:0x3000
	ds_read_b64_tr_b16 v[192:193], v144 offset:0x3800
	ds_read_b64_tr_b16 v[194:195], v144 offset:0x2200
	ds_read_b64_tr_b16 v[196:197], v144 offset:0x2a00
	ds_read_b64_tr_b16 v[198:199], v144 offset:0x3200
	ds_read_b64_tr_b16 v[200:201], v144 offset:0x3a00
	ds_read_b64_tr_b16 v[202:203], v144 offset:0x2400
	ds_read_b64_tr_b16 v[204:205], v144 offset:0x2c00
	ds_read_b64_tr_b16 v[206:207], v144 offset:0x3400
	ds_read_b64_tr_b16 v[208:209], v144 offset:0x3c00
	ds_read_b64_tr_b16 v[210:211], v144 offset:0x2600
	ds_read_b64_tr_b16 v[212:213], v144 offset:0x2e00
	ds_read_b64_tr_b16 v[214:215], v144 offset:0x3600
	ds_read_b64_tr_b16 v[216:217], v144 offset:0x3e00
	s_nop 5
	v_exp_f32_e32 v64, v64
	v_exp_f32_e32 v65, v65
	v_exp_f32_e32 v66, v66
	v_exp_f32_e32 v67, v67
	v_exp_f32_e32 v68, v68
	v_add_f32_e32 v144, 0, v64
	v_exp_f32_e32 v69, v69
	v_add_f32_e32 v144, v65, v144
	v_exp_f32_e32 v70, v70
	v_add_f32_e32 v144, v66, v144
	v_exp_f32_e32 v71, v71
	v_add_f32_e32 v144, v67, v144
	v_exp_f32_e32 v72, v72
	v_add_f32_e32 v144, v68, v144
	v_exp_f32_e32 v73, v73
	v_add_f32_e32 v144, v69, v144
	v_exp_f32_e32 v74, v74
	v_add_f32_e32 v144, v70, v144
	v_exp_f32_e32 v75, v75
	v_add_f32_e32 v144, v71, v144
	v_exp_f32_e32 v76, v76
	v_add_f32_e32 v144, v72, v144
	v_exp_f32_e32 v77, v77
	v_add_f32_e32 v144, v73, v144
	v_exp_f32_e32 v78, v78
	v_add_f32_e32 v144, v74, v144
	v_exp_f32_e32 v79, v79
	v_add_f32_e32 v144, v75, v144
	v_add_f32_e32 v144, v76, v144
	v_add_f32_e32 v144, v77, v144
	v_add_f32_e32 v144, v78, v144
	v_add_f32_e32 v144, v79, v144
	v_add_f32_e32 v144, v145, v144
	v_cvt_pk_bf16_f32 v64, v64, v65
	v_cvt_pk_bf16_f32 v65, v66, v67
	v_cvt_pk_bf16_f32 v66, v68, v69
	v_cvt_pk_bf16_f32 v67, v70, v71
	v_cvt_pk_bf16_f32 v68, v72, v73
	v_cvt_pk_bf16_f32 v69, v74, v75
	v_cvt_pk_bf16_f32 v70, v76, v77
	v_cvt_pk_bf16_f32 v71, v78, v79
	s_nop 0
	v_permlane32_swap_b32_e32 v64, v66
	v_permlane32_swap_b32_e32 v65, v67
	v_permlane32_swap_b32_e32 v68, v70
	v_permlane32_swap_b32_e32 v69, v71
	s_waitcnt lgkmcnt(0)
	ds_read_b128 v[218:221], v167 offset:49152
	ds_read_b128 v[222:225], v168 offset:49152
	ds_read_b128 v[226:229], v169 offset:49152
	ds_read_b128 v[230:233], v170 offset:49152
	ds_read_b128 v[234:237], v171 offset:49152
	ds_read_b128 v[238:241], v172 offset:49152
	s_setprio 0
	s_cmp_lt_u32 s33, 0x100
	s_cbranch_scc1 .Lstg_mla_m61_5
	s_waitcnt vmcnt(0)
	s_barrier

; #define LAS __attribute__((address_space(3)))
; DI void expsum(f32x16& p, float& l_reg, bf16x8& pa0, bf16x8& pa1) {
; #pragma unroll
;     for (int r = 0; r < 16; ++r) p[r] = __builtin_amdgcn_exp2f(p[r]);
;     float ps = 0.f;
; #pragma unroll
;     for (int r = 0; r < 16; ++r) ps += p[r];
;     l_reg += ps; asm volatile("" : "+v"(l_reg));
;     ...
;     ATT_PK4(p, 0, pa0); ATT_PK4(p, 8, pa1);
;     ...
; }
; DI int v_rd_base(int lane) { return ((lane & 3) << 3) | (((lane >> 2) & 3) << 6) | (((lane >> 4) & 1) << 5) | (((lane >> 5) & 1) << 8); }
; template <int OFF> DI s16x4 tr_read(int vb) { s16x4 r; asm volatile("ds_read_b64_tr_b16 %0, %1 offset:%2" : "=&v"(r) : "v"(vb), "i"(OFF) : "memory"); return r; }
; template <int H> DI void v_reads(s16x4* vf, int vb) {
;     vf[0] = tr_read<v_rd_off(0, 2 * H, 0)>(vb); vf[1] = tr_read<v_rd_off(0, 2 * H, 1)>(vb); vf[2] = tr_read<v_rd_off(0, 2 * H + 1, 0)>(vb); vf[3] = tr_read<v_rd_off(0, 2 * H + 1, 1)>(vb);
;     vf[4] = tr_read<v_rd_off(1, 2 * H, 0)>(vb); vf[5] = tr_read<v_rd_off(1, 2 * H, 1)>(vb); vf[6] = tr_read<v_rd_off(1, 2 * H + 1, 0)>(vb); vf[7] = tr_read<v_rd_off(1, 2 * H + 1, 1)>(vb);
;     vf[8] = tr_read<v_rd_off(2, 2 * H, 0)>(vb); vf[9] = tr_read<v_rd_off(2, 2 * H, 1)>(vb); vf[10] = tr_read<v_rd_off(2, 2 * H + 1, 0)>(vb); vf[11] = tr_read<v_rd_off(2, 2 * H + 1, 1)>(vb);
;     vf[12] = tr_read<v_rd_off(3, 2 * H, 0)>(vb); vf[13] = tr_read<v_rd_off(3, 2 * H, 1)>(vb); vf[14] = tr_read<v_rd_off(3, 2 * H + 1, 0)>(vb); vf[15] = tr_read<v_rd_off(3, 2 * H + 1, 1)>(vb);
; }
; DI void pv_mma(f32x16* o, const s16x4* vf, bf16x8 pa0, bf16x8 pa1) {
;     ...
; #pragma unroll
;     for (int d0 = 0; d0 < 4; ++d0) {
;         o[d0] = __builtin_amdgcn_mfma_f32_32x32x16_bf16(pa0, ATT_PK(vf[4 * d0], vf[4 * d0 + 1]), o[d0], 0, 0, 0);
;         o[d0] = __builtin_amdgcn_mfma_f32_32x32x16_bf16(pa1, ATT_PK(vf[4 * d0 + 2], vf[4 * d0 + 3]), o[d0], 0, 0, 0); }
;     ...
; }
; template <int DQK, int D0A, int D0B> DI void k_reads(bf16x8* kf, const LAS unsigned char* Ks, int half, int r32, int hi) {
; #pragma unroll
;     for (int d0 = D0A; d0 < D0B; ++d0) kf[d0 - D0A] = *(const LAS bf16x8*)(Ks + half * (32 * DQK * 2) + kswz<DQK>(r32, (d0 * 16 + hi * 8) * 2));
; }
; template <int D0A, int D0B> DI void qk_mma(f32x16& p, const bf16x8* kf, const bf16x8* qr) {
; #pragma unroll
;     for (int d0 = D0A; d0 < D0B; ++d0) {
.Lstg_mla_t62_6:
	s_setprio 1
	ds_read_b128 v[132:135], v161 offset:61440
	ds_read_b128 v[136:139], v162 offset:61440
	ds_read_b128 v[140:143], v163 offset:61440
	ds_read_b128 v[174:177], v164 offset:61440
	ds_read_b128 v[162:165], v165 offset:61440
	ds_read_b128 v[178:181], v166 offset:61440
	v_add_u32_e32 v145, 0x8000, v130
	ds_read_b64_tr_b16 v[182:183], v145 offset:0
	ds_read_b64_tr_b16 v[184:185], v145 offset:0x800
	ds_read_b64_tr_b16 v[186:187], v145 offset:0x1000
	ds_read_b64_tr_b16 v[188:189], v145 offset:0x1800
	ds_read_b64_tr_b16 v[190:191], v145 offset:0x200
	ds_read_b64_tr_b16 v[192:193], v145 offset:0xa00
	ds_read_b64_tr_b16 v[194:195], v145 offset:0x1200
	ds_read_b64_tr_b16 v[196:197], v145 offset:0x1a00
	ds_read_b64_tr_b16 v[198:199], v145 offset:0x400
	ds_read_b64_tr_b16 v[200:201], v145 offset:0xc00
	ds_read_b64_tr_b16 v[202:203], v145 offset:0x1400
	ds_read_b64_tr_b16 v[204:205], v145 offset:0x1c00
	ds_read_b64_tr_b16 v[206:207], v145 offset:0x600
	ds_read_b64_tr_b16 v[208:209], v145 offset:0xe00
	ds_read_b64_tr_b16 v[210:211], v145 offset:0x1600
	ds_read_b64_tr_b16 v[212:213], v145 offset:0x1e00
	s_nop 3
	v_exp_f32_e32 v64, v64
	v_exp_f32_e32 v65, v65
	v_exp_f32_e32 v66, v66
	v_exp_f32_e32 v67, v67
	v_exp_f32_e32 v68, v68
	v_add_f32_e32 v161, 0, v64
	v_exp_f32_e32 v69, v69
	v_add_f32_e32 v161, v65, v161
	v_exp_f32_e32 v70, v70
	v_add_f32_e32 v161, v66, v161
	v_exp_f32_e32 v71, v71
	v_add_f32_e32 v161, v67, v161
	v_exp_f32_e32 v72, v72
	v_add_f32_e32 v161, v68, v161
	v_exp_f32_e32 v73, v73
	v_add_f32_e32 v161, v69, v161
	v_exp_f32_e32 v74, v74
	v_add_f32_e32 v161, v70, v161
	v_exp_f32_e32 v75, v75
	v_add_f32_e32 v161, v71, v161
	v_exp_f32_e32 v76, v76
	v_add_f32_e32 v161, v72, v161
	v_exp_f32_e32 v77, v77
	v_add_f32_e32 v161, v73, v161
	v_exp_f32_e32 v78, v78
	v_add_f32_e32 v161, v74, v161
	v_exp_f32_e32 v79, v79
	v_add_f32_e32 v161, v75, v161
	v_add_f32_e32 v161, v76, v161
	v_add_f32_e32 v161, v77, v161
	v_add_f32_e32 v161, v78, v161
	v_add_f32_e32 v161, v79, v161
	v_add_f32_e32 v144, v144, v161
	v_cvt_pk_bf16_f32 v64, v64, v65
	v_cvt_pk_bf16_f32 v65, v66, v67
	v_cvt_pk_bf16_f32 v66, v68, v69
	v_cvt_pk_bf16_f32 v67, v70, v71
	v_cvt_pk_bf16_f32 v68, v72, v73
	v_cvt_pk_bf16_f32 v69, v74, v75
	v_cvt_pk_bf16_f32 v70, v76, v77
	v_cvt_pk_bf16_f32 v71, v78, v79
	s_nop 0
	v_permlane32_swap_b32_e32 v64, v66
	v_permlane32_swap_b32_e32 v65, v67
	v_permlane32_swap_b32_e32 v68, v70
	v_permlane32_swap_b32_e32 v69, v71
	s_waitcnt lgkmcnt(0)
	ds_read_b128 v[214:217], v167 offset:61440
	ds_read_b128 v[218:221], v168 offset:61440
	ds_read_b128 v[166:169], v169 offset:61440
	ds_read_b128 v[222:225], v170 offset:61440
	ds_read_b128 v[226:229], v171 offset:61440
	ds_read_b128 v[170:173], v172 offset:61440
	s_setprio 0
	v_mfma_f32_32x32x16_bf16 v[48:63], v[64:67], v[182:185], v[48:63]
	v_mfma_f32_32x32x16_bf16 v[32:47], v[64:67], v[190:193], v[32:47]
	v_mfma_f32_32x32x16_bf16 v[16:31], v[64:67], v[198:201], v[16:31]
	v_mfma_f32_32x32x16_bf16 v[0:15], v[64:67], v[206:209], v[0:15]
	v_mfma_f32_32x32x16_bf16 v[48:63], v[68:71], v[186:189], v[48:63]
	v_mfma_f32_32x32x16_bf16 v[32:47], v[68:71], v[194:197], v[32:47]
	v_mfma_f32_32x32x16_bf16 v[16:31], v[68:71], v[202:205], v[16:31]
	v_mfma_f32_32x32x16_bf16 v[0:15], v[68:71], v[210:213], v[0:15]
	s_waitcnt lgkmcnt(0)
	v_mfma_f32_32x32x16_bf16 v[64:79], v[132:135], v[80:83], 0
	v_mfma_f32_32x32x16_bf16 v[64:79], v[136:139], v[84:87], v[64:79]
	v_mfma_f32_32x32x16_bf16 v[64:79], v[140:143], v[88:91], v[64:79]
	v_mfma_f32_32x32x16_bf16 v[64:79], v[174:177], v[92:95], v[64:79]
	v_mfma_f32_32x32x16_bf16 v[64:79], v[162:165], v[96:99], v[64:79]
	v_mfma_f32_32x32x16_bf16 v[64:79], v[178:181], v[100:103], v[64:79]
	s_waitcnt lgkmcnt(0)
; #define LAS __attribute__((address_space(3)))
; DI void expsum(f32x16& p, float& l_reg, bf16x8& pa0, bf16x8& pa1) {
; #pragma unroll
;     for (int r = 0; r < 16; ++r) p[r] = __builtin_amdgcn_exp2f(p[r]);
;     float ps = 0.f;
; #pragma unroll
;     for (int r = 0; r < 16; ++r) ps += p[r];
;     l_reg += ps; asm volatile("" : "+v"(l_reg));
;     ...
;     ATT_PK4(p, 0, pa0); ATT_PK4(p, 8, pa1);
;     ...
; }
; DI int v_rd_base(int lane) { return ((lane & 3) << 3) | (((lane >> 2) & 3) << 6) | (((lane >> 4) & 1) << 5) | (((lane >> 5) & 1) << 8); }
; template <int OFF> DI s16x4 tr_read(int vb) { s16x4 r; asm volatile("ds_read_b64_tr_b16 %0, %1 offset:%2" : "=&v"(r) : "v"(vb), "i"(OFF) : "memory"); return r; }
; template <int H> DI void v_reads(s16x4* vf, int vb) {
;     vf[0] = tr_read<v_rd_off(0, 2 * H, 0)>(vb); vf[1] = tr_read<v_rd_off(0, 2 * H, 1)>(vb); vf[2] = tr_read<v_rd_off(0, 2 * H + 1, 0)>(vb); vf[3] = tr_read<v_rd_off(0, 2 * H + 1, 1)>(vb);
;     vf[4] = tr_read<v_rd_off(1, 2 * H, 0)>(vb); vf[5] = tr_read<v_rd_off(1, 2 * H, 1)>(vb); vf[6] = tr_read<v_rd_off(1, 2 * H + 1, 0)>(vb); vf[7] = tr_read<v_rd_off(1, 2 * H + 1, 1)>(vb);
;     vf[8] = tr_read<v_rd_off(2, 2 * H, 0)>(vb); vf[9] = tr_read<v_rd_off(2, 2 * H, 1)>(vb); vf[10] = tr_read<v_rd_off(2, 2 * H + 1, 0)>(vb); vf[11] = tr_read<v_rd_off(2, 2 * H + 1, 1)>(vb);
;     vf[12] = tr_read<v_rd_off(3, 2 * H, 0)>(vb); vf[13] = tr_read<v_rd_off(3, 2 * H, 1)>(vb); vf[14] = tr_read<v_rd_off(3, 2 * H + 1, 0)>(vb); vf[15] = tr_read<v_rd_off(3, 2 * H + 1, 1)>(vb);
; }
; DI void pv_mma(f32x16* o, const s16x4* vf, bf16x8 pa0, bf16x8 pa1) {
;     ...
; #pragma unroll
;     for (int d0 = 0; d0 < 4; ++d0) {
;         o[d0] = __builtin_amdgcn_mfma_f32_32x32x16_bf16(pa0, ATT_PK(vf[4 * d0], vf[4 * d0 + 1]), o[d0], 0, 0, 0);
;         o[d0] = __builtin_amdgcn_mfma_f32_32x32x16_bf16(pa1, ATT_PK(vf[4 * d0 + 2], vf[4 * d0 + 3]), o[d0], 0, 0, 0); }
;     ...
; }
; template <int DQK, int D0A, int D0B> DI void k_reads(bf16x8* kf, const LAS unsigned char* Ks, int half, int r32, int hi) {
; #pragma unroll
;     for (int d0 = D0A; d0 < D0B; ++d0) kf[d0 - D0A] = *(const LAS bf16x8*)(Ks + half * (32 * DQK * 2) + kswz<DQK>(r32, (d0 * 16 + hi * 8) * 2));
; }
; template <int D0A, int D0B> DI void qk_mma(f32x16& p, const bf16x8* kf, const bf16x8* qr) {
; #pragma unroll
;     for (int d0 = D0A; d0 < D0B; ++d0) {
	v_mfma_f32_32x32x16_bf16 v[64:79], v[214:217], v[104:107], v[64:79]
	v_mfma_f32_32x32x16_bf16 v[64:79], v[218:221], v[108:111], v[64:79]
	v_mfma_f32_32x32x16_bf16 v[64:79], v[166:169], v[112:115], v[64:79]
	v_mfma_f32_32x32x16_bf16 v[64:79], v[222:225], v[116:119], v[64:79]
	v_mfma_f32_32x32x16_bf16 v[64:79], v[226:229], v[120:123], v[64:79]
	v_mfma_f32_32x32x16_bf16 v[64:79], v[170:173], v[124:127], v[64:79]
	s_setprio 1
	v_add_u32_e32 v158, 0x12000, v158
	v_add_u32_e32 v132, v158, v151
	v_add_u32_e32 v136, v158, v149
	v_add_u32_e32 v140, v158, v148
	v_add_u32_e32 v161, v158, v147
	ds_read_b128 v[132:135], v132
	ds_read_b128 v[136:139], v136
	ds_read_b128 v[140:143], v140
	ds_read_b128 v[162:165], v161
	v_add_u32_e32 v161, v158, v146
	v_add_u32_e32 v170, v158, v150
	ds_read_b128 v[166:169], v161
	ds_read_b128 v[170:173], v170
	ds_read_b64_tr_b16 v[174:175], v145 offset:0x2000
	ds_read_b64_tr_b16 v[176:177], v145 offset:0x2800
	ds_read_b64_tr_b16 v[178:179], v145 offset:0x3000
	ds_read_b64_tr_b16 v[180:181], v145 offset:0x3800
	ds_read_b64_tr_b16 v[182:183], v145 offset:0x2200
	ds_read_b64_tr_b16 v[184:185], v145 offset:0x2a00
	ds_read_b64_tr_b16 v[186:187], v145 offset:0x3200
	ds_read_b64_tr_b16 v[188:189], v145 offset:0x3a00
	ds_read_b64_tr_b16 v[190:191], v145 offset:0x2400
	ds_read_b64_tr_b16 v[192:193], v145 offset:0x2c00
	ds_read_b64_tr_b16 v[194:195], v145 offset:0x3400
	ds_read_b64_tr_b16 v[196:197], v145 offset:0x3c00
	ds_read_b64_tr_b16 v[198:199], v145 offset:0x2600
	ds_read_b64_tr_b16 v[200:201], v145 offset:0x2e00
	ds_read_b64_tr_b16 v[202:203], v145 offset:0x3600
	ds_read_b64_tr_b16 v[204:205], v145 offset:0x3e00
	v_exp_f32_e32 v64, v64
	v_exp_f32_e32 v65, v65
	v_exp_f32_e32 v66, v66
	v_exp_f32_e32 v67, v67
	v_exp_f32_e32 v68, v68
	v_add_f32_e32 v145, 0, v64
	v_exp_f32_e32 v69, v69
	v_add_f32_e32 v145, v65, v145
	v_exp_f32_e32 v70, v70
	v_add_f32_e32 v145, v66, v145
	v_exp_f32_e32 v71, v71
	v_add_f32_e32 v145, v67, v145
	v_exp_f32_e32 v72, v72
	v_add_f32_e32 v145, v68, v145
	v_exp_f32_e32 v73, v73
	v_add_f32_e32 v145, v69, v145
	v_exp_f32_e32 v74, v74
	v_add_f32_e32 v145, v70, v145
	v_exp_f32_e32 v75, v75
	v_add_f32_e32 v145, v71, v145
	v_exp_f32_e32 v76, v76
	v_add_f32_e32 v145, v72, v145
	v_exp_f32_e32 v77, v77
	v_add_f32_e32 v145, v73, v145
	v_exp_f32_e32 v78, v78
	v_add_f32_e32 v145, v74, v145
	v_exp_f32_e32 v79, v79
	v_add_f32_e32 v145, v75, v145
	v_add_f32_e32 v145, v76, v145
	v_add_f32_e32 v145, v77, v145
	v_add_f32_e32 v145, v78, v145
	v_add_f32_e32 v145, v79, v145
	v_add_f32_e32 v161, v144, v145
	v_cvt_pk_bf16_f32 v64, v64, v65
	v_cvt_pk_bf16_f32 v65, v66, v67
	v_cvt_pk_bf16_f32 v66, v68, v69
	v_cvt_pk_bf16_f32 v67, v70, v71
	v_cvt_pk_bf16_f32 v68, v72, v73
	v_cvt_pk_bf16_f32 v69, v74, v75
	v_cvt_pk_bf16_f32 v70, v76, v77
	v_cvt_pk_bf16_f32 v71, v78, v79
	s_nop 0
	v_permlane32_swap_b32_e32 v64, v66
	v_permlane32_swap_b32_e32 v65, v67
	v_permlane32_swap_b32_e32 v68, v70
	v_permlane32_swap_b32_e32 v69, v71
	s_waitcnt lgkmcnt(0)
	v_add_u32_e32 v72, v158, v152
	v_add_u32_e32 v73, v158, v153
	ds_read_b128 v[206:209], v72
	ds_read_b128 v[210:213], v73
	v_add_u32_e32 v72, v158, v154
	v_add_u32_e32 v73, v158, v155
	ds_read_b128 v[214:217], v72
	ds_read_b128 v[218:221], v73
	v_add_u32_e32 v72, v158, v156
	v_add_u32_e32 v73, v158, v157
	ds_read_b128 v[222:225], v72
	ds_read_b128 v[226:229], v73
	s_setprio 0
	s_cmp_lt_u32 s33, 0x100
	s_cbranch_scc1 .Lstg_mla_m62_7
	s_waitcnt vmcnt(0)
	s_barrier

; #define LAS __attribute__((address_space(3)))
; DI void expsum(f32x16& p, float& l_reg, bf16x8& pa0, bf16x8& pa1) {
; #pragma unroll
;     for (int r = 0; r < 16; ++r) p[r] = __builtin_amdgcn_exp2f(p[r]);
;     float ps = 0.f;
; #pragma unroll
;     for (int r = 0; r < 16; ++r) ps += p[r];
;     l_reg += ps; asm volatile("" : "+v"(l_reg));
;     ...
;     ATT_PK4(p, 0, pa0); ATT_PK4(p, 8, pa1);
;     ...
; }
; DI int v_rd_base(int lane) { return ((lane & 3) << 3) | (((lane >> 2) & 3) << 6) | (((lane >> 4) & 1) << 5) | (((lane >> 5) & 1) << 8); }
; template <int OFF> DI s16x4 tr_read(int vb) { s16x4 r; asm volatile("ds_read_b64_tr_b16 %0, %1 offset:%2" : "=&v"(r) : "v"(vb), "i"(OFF) : "memory"); return r; }
; template <int H> DI void v_reads(s16x4* vf, int vb) {
;     vf[0] = tr_read<v_rd_off(0, 2 * H, 0)>(vb); vf[1] = tr_read<v_rd_off(0, 2 * H, 1)>(vb); vf[2] = tr_read<v_rd_off(0, 2 * H + 1, 0)>(vb); vf[3] = tr_read<v_rd_off(0, 2 * H + 1, 1)>(vb);
;     vf[4] = tr_read<v_rd_off(1, 2 * H, 0)>(vb); vf[5] = tr_read<v_rd_off(1, 2 * H, 1)>(vb); vf[6] = tr_read<v_rd_off(1, 2 * H + 1, 0)>(vb); vf[7] = tr_read<v_rd_off(1, 2 * H + 1, 1)>(vb);
;     vf[8] = tr_read<v_rd_off(2, 2 * H, 0)>(vb); vf[9] = tr_read<v_rd_off(2, 2 * H, 1)>(vb); vf[10] = tr_read<v_rd_off(2, 2 * H + 1, 0)>(vb); vf[11] = tr_read<v_rd_off(2, 2 * H + 1, 1)>(vb);
;     vf[12] = tr_read<v_rd_off(3, 2 * H, 0)>(vb); vf[13] = tr_read<v_rd_off(3, 2 * H, 1)>(vb); vf[14] = tr_read<v_rd_off(3, 2 * H + 1, 0)>(vb); vf[15] = tr_read<v_rd_off(3, 2 * H + 1, 1)>(vb);
; }
; DI void pv_mma(f32x16* o, const s16x4* vf, bf16x8 pa0, bf16x8 pa1) {
;     ...
; #pragma unroll
;     for (int d0 = 0; d0 < 4; ++d0) {
;         o[d0] = __builtin_amdgcn_mfma_f32_32x32x16_bf16(pa0, ATT_PK(vf[4 * d0], vf[4 * d0 + 1]), o[d0], 0, 0, 0);
;         o[d0] = __builtin_amdgcn_mfma_f32_32x32x16_bf16(pa1, ATT_PK(vf[4 * d0 + 2], vf[4 * d0 + 3]), o[d0], 0, 0, 0); }
;     ...
; }
; template <int DQK, int D0A, int D0B> DI void k_reads(bf16x8* kf, const LAS unsigned char* Ks, int half, int r32, int hi) {
; #pragma unroll
;     for (int d0 = D0A; d0 < D0B; ++d0) kf[d0 - D0A] = *(const LAS bf16x8*)(Ks + half * (32 * DQK * 2) + kswz<DQK>(r32, (d0 * 16 + hi * 8) * 2));
; }
; template <int D0A, int D0B> DI void qk_mma(f32x16& p, const bf16x8* kf, const bf16x8* qr) {
; #pragma unroll
;     for (int d0 = D0A; d0 < D0B; ++d0) {
.Lstg_mla_t63_8:
	s_setprio 1
	v_add_u32_e32 v158, s82, v159
	v_add_u32_e32 v132, v158, v151
	v_add_u32_e32 v136, v158, v149
	v_add_u32_e32 v140, v158, v148
	v_add_u32_e32 v144, v158, v147
	ds_read_b128 v[132:135], v132
	ds_read_b128 v[136:139], v136
	ds_read_b128 v[140:143], v140
	ds_read_b128 v[162:165], v144
	v_add_u32_e32 v144, v158, v146
	v_add_u32_e32 v148, v158, v150
	ds_read_b128 v[144:147], v144
	ds_read_b128 v[148:151], v148
	ds_read_b64_tr_b16 v[166:167], v130 offset:0
	ds_read_b64_tr_b16 v[168:169], v130 offset:0x800
	ds_read_b64_tr_b16 v[170:171], v130 offset:0x1000
	ds_read_b64_tr_b16 v[172:173], v130 offset:0x1800
	ds_read_b64_tr_b16 v[174:175], v130 offset:0x200
	ds_read_b64_tr_b16 v[176:177], v130 offset:0xa00
	ds_read_b64_tr_b16 v[178:179], v130 offset:0x1200
	ds_read_b64_tr_b16 v[180:181], v130 offset:0x1a00
	ds_read_b64_tr_b16 v[182:183], v130 offset:0x400
	ds_read_b64_tr_b16 v[184:185], v130 offset:0xc00
	ds_read_b64_tr_b16 v[186:187], v130 offset:0x1400
	ds_read_b64_tr_b16 v[188:189], v130 offset:0x1c00
	ds_read_b64_tr_b16 v[190:191], v130 offset:0x600
	ds_read_b64_tr_b16 v[192:193], v130 offset:0xe00
	ds_read_b64_tr_b16 v[194:195], v130 offset:0x1600
	ds_read_b64_tr_b16 v[196:197], v130 offset:0x1e00
	v_exp_f32_e32 v64, v64
	v_exp_f32_e32 v65, v65
	v_exp_f32_e32 v66, v66
	v_exp_f32_e32 v67, v67
	v_exp_f32_e32 v68, v68
	v_add_f32_e32 v159, 0, v64
	v_exp_f32_e32 v69, v69
	v_add_f32_e32 v159, v65, v159
	v_exp_f32_e32 v70, v70
	v_add_f32_e32 v159, v66, v159
	v_exp_f32_e32 v71, v71
	v_add_f32_e32 v159, v67, v159
	v_exp_f32_e32 v72, v72
	v_add_f32_e32 v159, v68, v159
	v_exp_f32_e32 v73, v73
	v_add_f32_e32 v159, v69, v159
	v_exp_f32_e32 v74, v74
	v_add_f32_e32 v159, v70, v159
	v_exp_f32_e32 v75, v75
	v_add_f32_e32 v159, v71, v159
	v_exp_f32_e32 v76, v76
	v_add_f32_e32 v159, v72, v159
	v_exp_f32_e32 v77, v77
	v_add_f32_e32 v159, v73, v159
	v_exp_f32_e32 v78, v78
	v_add_f32_e32 v159, v74, v159
	v_exp_f32_e32 v79, v79
	v_add_f32_e32 v159, v75, v159
	v_add_f32_e32 v159, v76, v159
	v_add_f32_e32 v159, v77, v159
	v_add_f32_e32 v159, v78, v159
	v_add_f32_e32 v159, v79, v159
	v_add_f32_e32 v161, v161, v159
	v_cvt_pk_bf16_f32 v64, v64, v65
	v_cvt_pk_bf16_f32 v65, v66, v67
	v_cvt_pk_bf16_f32 v66, v68, v69
	v_cvt_pk_bf16_f32 v67, v70, v71
	v_cvt_pk_bf16_f32 v68, v72, v73
	v_cvt_pk_bf16_f32 v69, v74, v75
	v_cvt_pk_bf16_f32 v70, v76, v77
	v_cvt_pk_bf16_f32 v71, v78, v79
	s_nop 0
	v_permlane32_swap_b32_e32 v64, v66
	v_permlane32_swap_b32_e32 v65, v67
	v_permlane32_swap_b32_e32 v68, v70
	v_permlane32_swap_b32_e32 v69, v71
	s_waitcnt lgkmcnt(0)
	v_add_u32_e32 v72, v158, v152
	v_add_u32_e32 v73, v158, v153
	ds_read_b128 v[198:201], v72
	ds_read_b128 v[202:205], v73
	v_add_u32_e32 v72, v158, v154
	v_add_u32_e32 v73, v158, v155
	ds_read_b128 v[152:155], v72
	ds_read_b128 v[206:209], v73
	v_add_u32_e32 v72, v158, v156
	v_add_u32_e32 v73, v158, v157
	ds_read_b128 v[156:159], v72
	ds_read_b128 v[210:213], v73
	s_setprio 0
	v_mfma_f32_32x32x16_bf16 v[48:63], v[64:67], v[166:169], v[48:63]
	v_mfma_f32_32x32x16_bf16 v[32:47], v[64:67], v[174:177], v[32:47]
	v_mfma_f32_32x32x16_bf16 v[16:31], v[64:67], v[182:185], v[16:31]
	v_mfma_f32_32x32x16_bf16 v[0:15], v[64:67], v[190:193], v[0:15]
	v_mfma_f32_32x32x16_bf16 v[48:63], v[68:71], v[170:173], v[48:63]
	v_mfma_f32_32x32x16_bf16 v[32:47], v[68:71], v[178:181], v[32:47]
	v_mfma_f32_32x32x16_bf16 v[16:31], v[68:71], v[186:189], v[16:31]
	v_mfma_f32_32x32x16_bf16 v[0:15], v[68:71], v[194:197], v[0:15]
	s_waitcnt lgkmcnt(0)
; #define LAS __attribute__((address_space(3)))
; DI void expsum(f32x16& p, float& l_reg, bf16x8& pa0, bf16x8& pa1) {
; #pragma unroll
;     for (int r = 0; r < 16; ++r) p[r] = __builtin_amdgcn_exp2f(p[r]);
;     float ps = 0.f;
; #pragma unroll
;     for (int r = 0; r < 16; ++r) ps += p[r];
;     l_reg += ps; asm volatile("" : "+v"(l_reg));
;     ...
;     ATT_PK4(p, 0, pa0); ATT_PK4(p, 8, pa1);
;     ...
; }
; DI int v_rd_base(int lane) { return ((lane & 3) << 3) | (((lane >> 2) & 3) << 6) | (((lane >> 4) & 1) << 5) | (((lane >> 5) & 1) << 8); }
; template <int OFF> DI s16x4 tr_read(int vb) { s16x4 r; asm volatile("ds_read_b64_tr_b16 %0, %1 offset:%2" : "=&v"(r) : "v"(vb), "i"(OFF) : "memory"); return r; }
; template <int H> DI void v_reads(s16x4* vf, int vb) {
;     vf[0] = tr_read<v_rd_off(0, 2 * H, 0)>(vb); vf[1] = tr_read<v_rd_off(0, 2 * H, 1)>(vb); vf[2] = tr_read<v_rd_off(0, 2 * H + 1, 0)>(vb); vf[3] = tr_read<v_rd_off(0, 2 * H + 1, 1)>(vb);
;     vf[4] = tr_read<v_rd_off(1, 2 * H, 0)>(vb); vf[5] = tr_read<v_rd_off(1, 2 * H, 1)>(vb); vf[6] = tr_read<v_rd_off(1, 2 * H + 1, 0)>(vb); vf[7] = tr_read<v_rd_off(1, 2 * H + 1, 1)>(vb);
;     vf[8] = tr_read<v_rd_off(2, 2 * H, 0)>(vb); vf[9] = tr_read<v_rd_off(2, 2 * H, 1)>(vb); vf[10] = tr_read<v_rd_off(2, 2 * H + 1, 0)>(vb); vf[11] = tr_read<v_rd_off(2, 2 * H + 1, 1)>(vb);
;     vf[12] = tr_read<v_rd_off(3, 2 * H, 0)>(vb); vf[13] = tr_read<v_rd_off(3, 2 * H, 1)>(vb); vf[14] = tr_read<v_rd_off(3, 2 * H + 1, 0)>(vb); vf[15] = tr_read<v_rd_off(3, 2 * H + 1, 1)>(vb);
; }
; DI void pv_mma(f32x16* o, const s16x4* vf, bf16x8 pa0, bf16x8 pa1) {
;     ...
; #pragma unroll
;     for (int d0 = 0; d0 < 4; ++d0) {
;         o[d0] = __builtin_amdgcn_mfma_f32_32x32x16_bf16(pa0, ATT_PK(vf[4 * d0], vf[4 * d0 + 1]), o[d0], 0, 0, 0);
;         o[d0] = __builtin_amdgcn_mfma_f32_32x32x16_bf16(pa1, ATT_PK(vf[4 * d0 + 2], vf[4 * d0 + 3]), o[d0], 0, 0, 0); }
;     ...
; }
; template <int DQK, int D0A, int D0B> DI void k_reads(bf16x8* kf, const LAS unsigned char* Ks, int half, int r32, int hi) {
; #pragma unroll
;     for (int d0 = D0A; d0 < D0B; ++d0) kf[d0 - D0A] = *(const LAS bf16x8*)(Ks + half * (32 * DQK * 2) + kswz<DQK>(r32, (d0 * 16 + hi * 8) * 2));
; }
; template <int D0A, int D0B> DI void qk_mma(f32x16& p, const bf16x8* kf, const bf16x8* qr) {
; #pragma unroll
;     for (int d0 = D0A; d0 < D0B; ++d0) {
	v_mfma_f32_32x32x16_bf16 v[64:79], v[132:135], v[80:83], 0
	v_mfma_f32_32x32x16_bf16 v[64:79], v[136:139], v[84:87], v[64:79]
	v_mfma_f32_32x32x16_bf16 v[64:79], v[140:143], v[88:91], v[64:79]
	v_mfma_f32_32x32x16_bf16 v[64:79], v[162:165], v[92:95], v[64:79]
	v_mfma_f32_32x32x16_bf16 v[64:79], v[144:147], v[96:99], v[64:79]
	v_mfma_f32_32x32x16_bf16 v[64:79], v[148:151], v[100:103], v[64:79]
	s_waitcnt lgkmcnt(0)
	v_mfma_f32_32x32x16_bf16 v[64:79], v[198:201], v[104:107], v[64:79]
	v_mfma_f32_32x32x16_bf16 v[64:79], v[202:205], v[108:111], v[64:79]
	v_mfma_f32_32x32x16_bf16 v[64:79], v[152:155], v[112:115], v[64:79]
	v_mfma_f32_32x32x16_bf16 v[64:79], v[206:209], v[116:119], v[64:79]
	v_mfma_f32_32x32x16_bf16 v[64:79], v[156:159], v[120:123], v[64:79]
	v_mfma_f32_32x32x16_bf16 v[64:79], v[210:213], v[124:127], v[64:79]
	s_setprio 1
	ds_read_b64_tr_b16 v[80:81], v130 offset:0x2000
	ds_read_b64_tr_b16 v[82:83], v130 offset:0x2800
	ds_read_b64_tr_b16 v[84:85], v130 offset:0x3000
	ds_read_b64_tr_b16 v[86:87], v130 offset:0x3800
	ds_read_b64_tr_b16 v[88:89], v130 offset:0x2200
	ds_read_b64_tr_b16 v[90:91], v130 offset:0x2a00
	ds_read_b64_tr_b16 v[92:93], v130 offset:0x3200
	ds_read_b64_tr_b16 v[94:95], v130 offset:0x3a00
	ds_read_b64_tr_b16 v[96:97], v130 offset:0x2400
	ds_read_b64_tr_b16 v[98:99], v130 offset:0x2c00
	ds_read_b64_tr_b16 v[100:101], v130 offset:0x3400
	ds_read_b64_tr_b16 v[102:103], v130 offset:0x3c00
	ds_read_b64_tr_b16 v[104:105], v130 offset:0x2600
	ds_read_b64_tr_b16 v[106:107], v130 offset:0x2e00
	ds_read_b64_tr_b16 v[108:109], v130 offset:0x3600
	ds_read_b64_tr_b16 v[110:111], v130 offset:0x3e00
	s_nop 11
	v_exp_f32_e32 v112, v64
	v_exp_f32_e32 v65, v65
	v_exp_f32_e32 v113, v66
	v_exp_f32_e32 v67, v67
	v_exp_f32_e32 v68, v68
	v_add_f32_e32 v64, 0, v112
	v_exp_f32_e32 v69, v69
	v_add_f32_e32 v64, v65, v64
	v_exp_f32_e32 v70, v70
	v_add_f32_e32 v64, v113, v64
	v_exp_f32_e32 v71, v71
	v_add_f32_e32 v64, v67, v64
	v_exp_f32_e32 v72, v72
	v_add_f32_e32 v64, v68, v64
	v_exp_f32_e32 v73, v73
	v_add_f32_e32 v64, v69, v64
	v_exp_f32_e32 v74, v74
	v_add_f32_e32 v64, v70, v64
	v_exp_f32_e32 v75, v75
	v_add_f32_e32 v64, v71, v64
	v_exp_f32_e32 v76, v76
	v_add_f32_e32 v64, v72, v64
	v_exp_f32_e32 v77, v77
	v_add_f32_e32 v64, v73, v64
	v_exp_f32_e32 v78, v78
	v_add_f32_e32 v64, v74, v64
	v_exp_f32_e32 v79, v79
	v_add_f32_e32 v64, v75, v64
	v_add_f32_e32 v64, v76, v64
	v_add_f32_e32 v64, v77, v64
	v_add_f32_e32 v64, v78, v64
	v_add_f32_e32 v64, v79, v64
	v_add_f32_e32 v64, v161, v64
	v_cvt_pk_bf16_f32 v66, v112, v65
	v_cvt_pk_bf16_f32 v67, v113, v67
	v_cvt_pk_bf16_f32 v68, v68, v69
	v_cvt_pk_bf16_f32 v69, v70, v71
	v_cvt_pk_bf16_f32 v70, v72, v73
	v_cvt_pk_bf16_f32 v71, v74, v75
	v_cvt_pk_bf16_f32 v72, v76, v77
	v_cvt_pk_bf16_f32 v73, v78, v79
	s_nop 0
	v_permlane32_swap_b32_e32 v66, v68
	v_permlane32_swap_b32_e32 v67, v69
	v_permlane32_swap_b32_e32 v70, v72
	v_permlane32_swap_b32_e32 v71, v73
	s_waitcnt lgkmcnt(0)
	s_setprio 0
	v_mfma_f32_32x32x16_bf16 v[48:63], v[66:69], v[80:83], v[48:63]
	v_mfma_f32_32x32x16_bf16 v[32:47], v[66:69], v[88:91], v[32:47]
	v_mfma_f32_32x32x16_bf16 v[16:31], v[66:69], v[96:99], v[16:31]
	v_mfma_f32_32x32x16_bf16 v[0:15], v[66:69], v[104:107], v[0:15]
	v_mfma_f32_32x32x16_bf16 v[48:63], v[70:73], v[84:87], v[48:63]
	v_mfma_f32_32x32x16_bf16 v[32:47], v[70:73], v[92:95], v[32:47]
	v_mfma_f32_32x32x16_bf16 v[16:31], v[70:73], v[100:103], v[16:31]
	v_mfma_f32_32x32x16_bf16 v[0:15], v[70:73], v[108:111], v[0:15]
	s_setprio 0
	v_mbcnt_lo_u32_b32 v66, -1, 0
	v_mbcnt_hi_u32_b32 v66, -1, v66
	v_mov_b32_e32 v67, v64
	v_and_b32_e32 v65, 31, v66
	v_bfe_u32 v66, v66, 5, 1
	v_permlane32_swap_b32_e32 v64, v67
	v_cmp_eq_u32_e32 vcc, 0, v66
	s_and_saveexec_b64 s[2:3], vcc
	s_cbranch_execz .LBB0_1910
	v_lshl_add_u32 v68, v65, 2, s4
	v_add_f32_e32 v64, v64, v67
	ds_write_b32 v68, v64
	s_branch .LBB0_1910
